# combo12 + K-loop A-fragment ds_reads through one per-unit base VGPR with immediate offsets (4 v_add_u32 per iteration removed from the load segments)
# speedup vs baseline: 1.0026x; 1.0026x over previous
; #define PG8_STAGE(bufoff, gbase, voff) do { _Pragma("unroll") for (int _i = 0; _i < 2; ++_i) \
;         __builtin_amdgcn_global_load_lds((const unsigned*)((const char*)(gbase) + (voff)[_i]), (PG8_LAS unsigned*)(lds + (bufoff) + ldsw + _i * 8192), 16, 0, 0); } while (0)
; #define PG8_LDA(dst, b, h) do { _Pragma("unroll") for (int m = 0; m < 4; ++m) _Pragma("unroll") for (int k = 0; k < 2; ++k) dst[m][k] = *(const PG8_LAS bf16x8*)(lds + PG8_SA(b, h) + aoff + m * 2048 + k * 1024); } while (0)
; #define PG8_LDB(dst, b, h) do { _Pragma("unroll") for (int n = 0; n < 2; ++n) _Pragma("unroll") for (int k = 0; k < 2; ++k) dst[n][k] = *(const PG8_LAS bf16x8*)(lds + PG8_SB(b, h) + boff + n * 2048 + k * 1024); } while (0)
; #define PG8_MMA(ai, bj, At, Bt) do { __builtin_amdgcn_s_setprio(1); _Pragma("unroll") for (int m = 0; m < 4; ++m) _Pragma("unroll") for (int n = 0; n < 2; ++n) _Pragma("unroll") for (int k = 0; k < 2; ++k) \
;         acc[ai][bj][m][n] = __builtin_amdgcn_mfma_f32_16x16x32_bf16(Bt[n][k], At[m][k], acc[ai][bj][m][n], 0, 0, 0); __builtin_amdgcn_s_setprio(0); } while (0)
; #define PG8_WAIT_V(n) asm volatile("s_waitcnt vmcnt(" #n ")" ::: "memory")
; #define PG8_WAIT_L(n) asm volatile("s_waitcnt lgkmcnt(" #n ")" ::: "memory")
; #define PG8_BAR __builtin_amdgcn_s_barrier()
; #define PG8_SCHED __builtin_amdgcn_sched_barrier(0)
; template <class Epi, class Sched, bool ALIGN_EPI = false, bool SP2 = false, bool ACHUNK = false>
; __device__ __forceinline__ void gemm_phase(PG8_LAS unsigned char* lds, const Gemm g, const Sched& S, const Epi& E) {
;     ...
;             PG8_LDB(B0, 0, 0); PG8_LDB(B1, 0, 1); PG8_SCHED; PG8_LDA(At, 0, 0); PG8_STAGE(PG8_SA(1, 1), a1 + hstepA, voffA);
;             PG8_WAIT_V(8); PG8_WAIT_L(0); PG8_BAR; PG8_MMA(0, 0, At, B0); PG8_MMA(0, 1, At, B1); PG8_BAR; PG8_SCHED;
;             PG8_LDA(At, 0, 1); PG8_STAGE(PG8_SB(0, 0), b2, voffB); PG8_STAGE(PG8_SB(0, 1), b2 + hstepB, voffB); PG8_STAGE(PG8_SA(0, 0), a2, voffA);
;             PG8_WAIT_V(8); PG8_WAIT_L(0); PG8_BAR; PG8_MMA(1, 0, At, B0); PG8_MMA(1, 1, At, B1); PG8_BAR; PG8_SCHED;
.LBB0_51:
	s_add_u32 s20, s20, 0x80
	s_addc_u32 s21, s21, 0
	s_add_u32 s44, s18, 0x100
	s_addc_u32 s45, s19, 0
	s_mov_b32 s18, 0
	v_add_u32_e32 v192, 0x10000, v147
.LBB0_52:
	s_add_i32 s46, s18, 2
	s_add_u32 s47, s20, 0x80
	s_addc_u32 s19, s21, 0
	s_add_i32 s50, 0, 0x10000
	s_cmp_eq_u32 s30, s18
	s_cselect_b32 s19, s1, s19
	s_cselect_b32 s18, s0, s47
	s_cselect_b32 s49, s17, s45
	s_cselect_b32 s48, s16, s44
	s_cbranch_scc0 .Lnl_dn
	s_cmpk_lg_u32 s87, 0x100
	s_cbranch_scc1 .Lnl_dn
	v_mov_b32_e32 v2, 0
	v_mov_b32_e32 v136, 0
	v_mov_b32_e32 v132, 0
	v_mov_b32_e32 v134, 0
.Lnl_dn:
	s_add_i32 s47, 0, 0x14000
	ds_read_b128 v[142:145], v192
	ds_read_b128 v[152:155], v192 offset:1024
	ds_read_b128 v[156:159], v192 offset:2048
	ds_read_b128 v[160:163], v192 offset:3072
	ds_read_b128 v[164:167], v192 offset:16384
	ds_read_b128 v[168:171], v192 offset:17408
	ds_read_b128 v[172:175], v192 offset:18432
	ds_read_b128 v[176:179], v192 offset:19456
	s_add_i32 m0, s23, 0xc000
	ds_read_b128 v[180:183], v150
	ds_read_b128 v[184:187], v150 offset:1024
	ds_read_b128 v[188:191], v150 offset:2048
	ds_read_b128 v[198:201], v150 offset:3072
	ds_read_b128 v[202:205], v150 offset:4096
	ds_read_b128 v[206:209], v150 offset:5120
	ds_read_b128 v[210:213], v150 offset:6144
	ds_read_b128 v[214:217], v150 offset:7168
	global_load_lds_dwordx4 v138, s[20:21]
	s_add_i32 m0, s23, 0xe000
	s_nop 0
	global_load_lds_dwordx4 v140, s[20:21]
	s_waitcnt vmcnt(8)
	s_waitcnt lgkmcnt(0)
	s_barrier
	s_setprio 1
	v_mfma_f32_16x16x32_bf16 v[120:123], v[142:145], v[180:183], v[120:123]
	v_mfma_f32_16x16x32_bf16 v[128:131], v[156:159], v[180:183], v[128:131]
	v_mfma_f32_16x16x32_bf16 v[104:107], v[142:145], v[188:191], v[104:107]
	v_mfma_f32_16x16x32_bf16 v[112:115], v[156:159], v[188:191], v[112:115]
	v_mfma_f32_16x16x32_bf16 v[88:91], v[142:145], v[202:205], v[88:91]
	v_mfma_f32_16x16x32_bf16 v[96:99], v[156:159], v[202:205], v[96:99]
	v_mfma_f32_16x16x32_bf16 v[72:75], v[142:145], v[210:213], v[72:75]
	v_mfma_f32_16x16x32_bf16 v[80:83], v[156:159], v[210:213], v[80:83]
	v_mfma_f32_16x16x32_bf16 v[120:123], v[152:155], v[184:187], v[120:123]
	v_mfma_f32_16x16x32_bf16 v[128:131], v[160:163], v[184:187], v[128:131]
	v_mfma_f32_16x16x32_bf16 v[104:107], v[152:155], v[198:201], v[104:107]
	v_mfma_f32_16x16x32_bf16 v[112:115], v[160:163], v[198:201], v[112:115]
	v_mfma_f32_16x16x32_bf16 v[88:91], v[152:155], v[206:209], v[88:91]
	v_mfma_f32_16x16x32_bf16 v[96:99], v[160:163], v[206:209], v[96:99]
	v_mfma_f32_16x16x32_bf16 v[72:75], v[152:155], v[214:217], v[72:75]
	v_mfma_f32_16x16x32_bf16 v[80:83], v[160:163], v[214:217], v[80:83]
	s_setprio 0
	s_setprio 1
	v_mfma_f32_16x16x32_bf16 v[116:119], v[164:167], v[180:183], v[116:119]
	v_mfma_f32_16x16x32_bf16 v[124:127], v[172:175], v[180:183], v[124:127]
	v_mfma_f32_16x16x32_bf16 v[100:103], v[164:167], v[188:191], v[100:103]
	v_mfma_f32_16x16x32_bf16 v[108:111], v[172:175], v[188:191], v[108:111]
	v_mfma_f32_16x16x32_bf16 v[84:87], v[164:167], v[202:205], v[84:87]
	v_mfma_f32_16x16x32_bf16 v[92:95], v[172:175], v[202:205], v[92:95]
	v_mfma_f32_16x16x32_bf16 v[68:71], v[164:167], v[210:213], v[68:71]
	v_mfma_f32_16x16x32_bf16 v[76:79], v[172:175], v[210:213], v[76:79]
	v_mfma_f32_16x16x32_bf16 v[116:119], v[168:171], v[184:187], v[116:119]
	v_mfma_f32_16x16x32_bf16 v[124:127], v[176:179], v[184:187], v[124:127]
	v_mfma_f32_16x16x32_bf16 v[100:103], v[168:171], v[198:201], v[100:103]
	v_mfma_f32_16x16x32_bf16 v[108:111], v[176:179], v[198:201], v[108:111]
	v_mfma_f32_16x16x32_bf16 v[84:87], v[168:171], v[206:209], v[84:87]
	v_mfma_f32_16x16x32_bf16 v[92:95], v[176:179], v[206:209], v[92:95]
	v_mfma_f32_16x16x32_bf16 v[68:71], v[168:171], v[214:217], v[68:71]
	v_mfma_f32_16x16x32_bf16 v[76:79], v[176:179], v[214:217], v[76:79]
	s_setprio 0
	s_barrier
	s_add_i32 s50, s50, s22
	s_mov_b32 m0, s50
	ds_read_b128 v[180:183], v150 offset:16384
	ds_read_b128 v[184:187], v150 offset:17408
	ds_read_b128 v[188:191], v150 offset:18432
	ds_read_b128 v[198:201], v150 offset:19456
	ds_read_b128 v[202:205], v150 offset:20480
	ds_read_b128 v[206:209], v150 offset:21504
	ds_read_b128 v[210:213], v150 offset:22528
	ds_read_b128 v[214:217], v150 offset:23552
	global_load_lds_dwordx4 v2, s[48:49]
	s_add_i32 m0, s50, 0x2000
	s_add_i32 s47, s47, s22
	global_load_lds_dwordx4 v136, s[48:49]
	s_add_u32 s48, s48, s2
	s_addc_u32 s49, s49, s3
	s_mov_b64 vcc, s[48:49]
	s_sub_u32 s98, s48, s2
	s_subb_u32 s99, s49, s3
	s_mov_b32 m0, s47
	s_nop 0
	global_load_lds_dwordx4 v2, s[48:49]
	s_add_i32 m0, s47, 0x2000
	s_nop 0
	global_load_lds_dwordx4 v136, s[48:49]
	s_mov_b32 m0, s23
	s_nop 0
	global_load_lds_dwordx4 v132, s[18:19]
	s_mov_b32 m0, s24
	s_nop 0
	global_load_lds_dwordx4 v134, s[18:19]
	s_waitcnt vmcnt(8)
	s_waitcnt lgkmcnt(0)
	s_barrier
; #define PG8_STAGE(bufoff, gbase, voff) do { _Pragma("unroll") for (int _i = 0; _i < 2; ++_i) \
;         __builtin_amdgcn_global_load_lds((const unsigned*)((const char*)(gbase) + (voff)[_i]), (PG8_LAS unsigned*)(lds + (bufoff) + ldsw + _i * 8192), 16, 0, 0); } while (0)
; #define PG8_LDA(dst, b, h) do { _Pragma("unroll") for (int m = 0; m < 4; ++m) _Pragma("unroll") for (int k = 0; k < 2; ++k) dst[m][k] = *(const PG8_LAS bf16x8*)(lds + PG8_SA(b, h) + aoff + m * 2048 + k * 1024); } while (0)
; #define PG8_LDB(dst, b, h) do { _Pragma("unroll") for (int n = 0; n < 2; ++n) _Pragma("unroll") for (int k = 0; k < 2; ++k) dst[n][k] = *(const PG8_LAS bf16x8*)(lds + PG8_SB(b, h) + boff + n * 2048 + k * 1024); } while (0)
; #define PG8_MMA(ai, bj, At, Bt) do { __builtin_amdgcn_s_setprio(1); _Pragma("unroll") for (int m = 0; m < 4; ++m) _Pragma("unroll") for (int n = 0; n < 2; ++n) _Pragma("unroll") for (int k = 0; k < 2; ++k) \
;         acc[ai][bj][m][n] = __builtin_amdgcn_mfma_f32_16x16x32_bf16(Bt[n][k], At[m][k], acc[ai][bj][m][n], 0, 0, 0); __builtin_amdgcn_s_setprio(0); } while (0)
; #define PG8_WAIT_V(n) asm volatile("s_waitcnt vmcnt(" #n ")" ::: "memory")
; #define PG8_WAIT_L(n) asm volatile("s_waitcnt lgkmcnt(" #n ")" ::: "memory")
; #define PG8_BAR __builtin_amdgcn_s_barrier()
; #define PG8_SCHED __builtin_amdgcn_sched_barrier(0)
; template <class Epi, class Sched, bool ALIGN_EPI = false, bool SP2 = false, bool ACHUNK = false>
; __device__ __forceinline__ void gemm_phase(PG8_LAS unsigned char* lds, const Gemm g, const Sched& S, const Epi& E) {
;     ...
;             PG8_WAIT_V(8); PG8_WAIT_L(0); PG8_BAR; PG8_MMA(1, 0, At, B0); PG8_MMA(1, 1, At, B1); PG8_BAR; PG8_SCHED;
;             PG8_LDB(B0, 1, 0); PG8_LDB(B1, 1, 1); PG8_SCHED; PG8_LDA(At, 1, 0); PG8_STAGE(PG8_SA(0, 1), a2 + hstepA, voffA);
;             PG8_WAIT_V(8); PG8_WAIT_L(0); PG8_BAR; PG8_MMA(0, 0, At, B0); PG8_MMA(0, 1, At, B1); PG8_BAR; PG8_SCHED;
	s_setprio 1
	v_mfma_f32_16x16x32_bf16 v[56:59], v[142:145], v[180:183], v[56:59]
	v_mfma_f32_16x16x32_bf16 v[64:67], v[156:159], v[180:183], v[64:67]
	v_mfma_f32_16x16x32_bf16 v[40:43], v[142:145], v[188:191], v[40:43]
	v_mfma_f32_16x16x32_bf16 v[48:51], v[156:159], v[188:191], v[48:51]
	v_mfma_f32_16x16x32_bf16 v[24:27], v[142:145], v[202:205], v[24:27]
	v_mfma_f32_16x16x32_bf16 v[32:35], v[156:159], v[202:205], v[32:35]
	v_mfma_f32_16x16x32_bf16 v[8:11], v[142:145], v[210:213], v[8:11]
	v_mfma_f32_16x16x32_bf16 v[16:19], v[156:159], v[210:213], v[16:19]
	v_mfma_f32_16x16x32_bf16 v[56:59], v[152:155], v[184:187], v[56:59]
	v_mfma_f32_16x16x32_bf16 v[64:67], v[160:163], v[184:187], v[64:67]
	v_mfma_f32_16x16x32_bf16 v[40:43], v[152:155], v[198:201], v[40:43]
	v_mfma_f32_16x16x32_bf16 v[48:51], v[160:163], v[198:201], v[48:51]
	v_mfma_f32_16x16x32_bf16 v[24:27], v[152:155], v[206:209], v[24:27]
	v_mfma_f32_16x16x32_bf16 v[32:35], v[160:163], v[206:209], v[32:35]
	v_mfma_f32_16x16x32_bf16 v[8:11], v[152:155], v[214:217], v[8:11]
	v_mfma_f32_16x16x32_bf16 v[16:19], v[160:163], v[214:217], v[16:19]
	s_setprio 0
	s_setprio 1
	v_mfma_f32_16x16x32_bf16 v[52:55], v[164:167], v[180:183], v[52:55]
	v_mfma_f32_16x16x32_bf16 v[60:63], v[172:175], v[180:183], v[60:63]
	v_mfma_f32_16x16x32_bf16 v[36:39], v[164:167], v[188:191], v[36:39]
	v_mfma_f32_16x16x32_bf16 v[44:47], v[172:175], v[188:191], v[44:47]
	v_mfma_f32_16x16x32_bf16 v[20:23], v[164:167], v[202:205], v[20:23]
	v_mfma_f32_16x16x32_bf16 v[28:31], v[172:175], v[202:205], v[28:31]
	v_mfma_f32_16x16x32_bf16 v[4:7], v[164:167], v[210:213], v[4:7]
	v_mfma_f32_16x16x32_bf16 v[12:15], v[172:175], v[210:213], v[12:15]
	v_mfma_f32_16x16x32_bf16 v[52:55], v[168:171], v[184:187], v[52:55]
	v_mfma_f32_16x16x32_bf16 v[60:63], v[176:179], v[184:187], v[60:63]
	v_mfma_f32_16x16x32_bf16 v[36:39], v[168:171], v[198:201], v[36:39]
	v_mfma_f32_16x16x32_bf16 v[44:47], v[176:179], v[198:201], v[44:47]
	v_mfma_f32_16x16x32_bf16 v[20:23], v[168:171], v[206:209], v[20:23]
	v_mfma_f32_16x16x32_bf16 v[28:31], v[176:179], v[206:209], v[28:31]
	v_mfma_f32_16x16x32_bf16 v[4:7], v[168:171], v[214:217], v[4:7]
	v_mfma_f32_16x16x32_bf16 v[12:15], v[176:179], v[214:217], v[12:15]
	s_setprio 0
	s_barrier
	s_add_i32 s47, 0, 0x18000
	s_add_i32 s48, 0, 0x1c000
	ds_read_b128 v[142:145], v192 offset:32768
	ds_read_b128 v[152:155], v192 offset:33792
	ds_read_b128 v[156:159], v192 offset:34816
	ds_read_b128 v[160:163], v192 offset:35840
	ds_read_b128 v[164:167], v192 offset:49152
	ds_read_b128 v[168:171], v192 offset:50176
	ds_read_b128 v[172:175], v192 offset:51200
	ds_read_b128 v[176:179], v192 offset:52224
	s_add_u32 s18, s18, s2
	s_addc_u32 s19, s19, s3
	s_mov_b32 m0, s25
	ds_read_b128 v[180:183], v150 offset:32768
	ds_read_b128 v[184:187], v150 offset:33792
	ds_read_b128 v[188:191], v150 offset:34816
	ds_read_b128 v[198:201], v150 offset:35840
	ds_read_b128 v[202:205], v150 offset:36864
	ds_read_b128 v[206:209], v150 offset:37888
	ds_read_b128 v[210:213], v150 offset:38912
	ds_read_b128 v[214:217], v150 offset:39936
	global_load_lds_dwordx4 v132, s[18:19]
	s_mov_b32 m0, s26
	s_nop 0
	global_load_lds_dwordx4 v134, s[18:19]
	s_waitcnt vmcnt(8)
	s_waitcnt lgkmcnt(0)
	s_barrier
	s_setprio 1
	v_mfma_f32_16x16x32_bf16 v[120:123], v[142:145], v[180:183], v[120:123]
	v_mfma_f32_16x16x32_bf16 v[128:131], v[156:159], v[180:183], v[128:131]
	v_mfma_f32_16x16x32_bf16 v[104:107], v[142:145], v[188:191], v[104:107]
	v_mfma_f32_16x16x32_bf16 v[112:115], v[156:159], v[188:191], v[112:115]
	v_mfma_f32_16x16x32_bf16 v[88:91], v[142:145], v[202:205], v[88:91]
	v_mfma_f32_16x16x32_bf16 v[96:99], v[156:159], v[202:205], v[96:99]
	v_mfma_f32_16x16x32_bf16 v[72:75], v[142:145], v[210:213], v[72:75]
	v_mfma_f32_16x16x32_bf16 v[80:83], v[156:159], v[210:213], v[80:83]
	v_mfma_f32_16x16x32_bf16 v[120:123], v[152:155], v[184:187], v[120:123]
	v_mfma_f32_16x16x32_bf16 v[128:131], v[160:163], v[184:187], v[128:131]
	v_mfma_f32_16x16x32_bf16 v[104:107], v[152:155], v[198:201], v[104:107]
	v_mfma_f32_16x16x32_bf16 v[112:115], v[160:163], v[198:201], v[112:115]
	v_mfma_f32_16x16x32_bf16 v[88:91], v[152:155], v[206:209], v[88:91]
	v_mfma_f32_16x16x32_bf16 v[96:99], v[160:163], v[206:209], v[96:99]
	v_mfma_f32_16x16x32_bf16 v[72:75], v[152:155], v[214:217], v[72:75]
	v_mfma_f32_16x16x32_bf16 v[80:83], v[160:163], v[214:217], v[80:83]
	s_setprio 0
	s_setprio 1
	v_mfma_f32_16x16x32_bf16 v[116:119], v[164:167], v[180:183], v[116:119]
	v_mfma_f32_16x16x32_bf16 v[124:127], v[172:175], v[180:183], v[124:127]
	v_mfma_f32_16x16x32_bf16 v[100:103], v[164:167], v[188:191], v[100:103]
	v_mfma_f32_16x16x32_bf16 v[108:111], v[172:175], v[188:191], v[108:111]
	v_mfma_f32_16x16x32_bf16 v[84:87], v[164:167], v[202:205], v[84:87]
	v_mfma_f32_16x16x32_bf16 v[92:95], v[172:175], v[202:205], v[92:95]
	v_mfma_f32_16x16x32_bf16 v[68:71], v[164:167], v[210:213], v[68:71]
	v_mfma_f32_16x16x32_bf16 v[76:79], v[172:175], v[210:213], v[76:79]
	v_mfma_f32_16x16x32_bf16 v[116:119], v[168:171], v[184:187], v[116:119]
	v_mfma_f32_16x16x32_bf16 v[124:127], v[176:179], v[184:187], v[124:127]
	v_mfma_f32_16x16x32_bf16 v[100:103], v[168:171], v[198:201], v[100:103]
	v_mfma_f32_16x16x32_bf16 v[108:111], v[176:179], v[198:201], v[108:111]
	v_mfma_f32_16x16x32_bf16 v[84:87], v[168:171], v[206:209], v[84:87]
	v_mfma_f32_16x16x32_bf16 v[92:95], v[176:179], v[206:209], v[92:95]
	v_mfma_f32_16x16x32_bf16 v[68:71], v[168:171], v[214:217], v[68:71]
	v_mfma_f32_16x16x32_bf16 v[76:79], v[176:179], v[214:217], v[76:79]
	s_setprio 0
	s_barrier
; #define PG8_STAGE(bufoff, gbase, voff) do { _Pragma("unroll") for (int _i = 0; _i < 2; ++_i) \
;         __builtin_amdgcn_global_load_lds((const unsigned*)((const char*)(gbase) + (voff)[_i]), (PG8_LAS unsigned*)(lds + (bufoff) + ldsw + _i * 8192), 16, 0, 0); } while (0)
; #define PG8_LDA(dst, b, h) do { _Pragma("unroll") for (int m = 0; m < 4; ++m) _Pragma("unroll") for (int k = 0; k < 2; ++k) dst[m][k] = *(const PG8_LAS bf16x8*)(lds + PG8_SA(b, h) + aoff + m * 2048 + k * 1024); } while (0)
; #define PG8_MMA(ai, bj, At, Bt) do { __builtin_amdgcn_s_setprio(1); _Pragma("unroll") for (int m = 0; m < 4; ++m) _Pragma("unroll") for (int n = 0; n < 2; ++n) _Pragma("unroll") for (int k = 0; k < 2; ++k) \
;         acc[ai][bj][m][n] = __builtin_amdgcn_mfma_f32_16x16x32_bf16(Bt[n][k], At[m][k], acc[ai][bj][m][n], 0, 0, 0); __builtin_amdgcn_s_setprio(0); } while (0)
; #define PG8_WAIT_V(n) asm volatile("s_waitcnt vmcnt(" #n ")" ::: "memory")
; #define PG8_WAIT_L(n) asm volatile("s_waitcnt lgkmcnt(" #n ")" ::: "memory")
; #define PG8_BAR __builtin_amdgcn_s_barrier()
; #define PG8_SCHED __builtin_amdgcn_sched_barrier(0)
; template <class Epi, class Sched, bool ALIGN_EPI = false, bool SP2 = false, bool ACHUNK = false>
; __device__ __forceinline__ void gemm_phase(PG8_LAS unsigned char* lds, const Gemm g, const Sched& S, const Epi& E) {
;     ...
;         for (int t = 0; t < nt; t += 2) {
;             const bool last = (t == nt - 2);
;             if constexpr (Epi::HAS_MID) { if (t == Epi::MID_T) E.mid(acc, cur, wr, wc, fr, fq, ShflDev{}); }
;             const char* a1 = cA + (size_t)(t + 1) * kstep;
;             const char* a2 = last ? nA : cA + (size_t)(t + 2) * kstep; const char* b2 = last ? nB : cB + (size_t)(t + 2) * kstep;
;     ...
;             PG8_LDA(At, 1, 1); PG8_STAGE(PG8_SB(1, 0), b3, voffB); PG8_STAGE(PG8_SB(1, 1), b3 + hstepB, voffB); PG8_STAGE(PG8_SA(1, 0), a3, voffA);
;             PG8_WAIT_V(8); PG8_WAIT_L(0); PG8_BAR; PG8_MMA(1, 0, At, B0); PG8_MMA(1, 1, At, B1); PG8_BAR; PG8_SCHED;
	s_add_u32 vcc_lo, vcc_lo, s10
	s_addc_u32 vcc_hi, vcc_hi, s11
	s_add_u32 s98, s98, s10
	s_addc_u32 s99, s99, s11
	s_sub_u32 s18, s18, s2
	s_subb_u32 s19, s19, s3
	s_add_u32 s18, s18, s10
	s_addc_u32 s19, s19, s11
	s_add_i32 m0, s47, s22
	ds_read_b128 v[180:183], v150 offset:49152
	ds_read_b128 v[184:187], v150 offset:50176
	ds_read_b128 v[188:191], v150 offset:51200
	ds_read_b128 v[198:201], v150 offset:52224
	ds_read_b128 v[202:205], v150 offset:53248
	ds_read_b128 v[206:209], v150 offset:54272
	ds_read_b128 v[210:213], v150 offset:55296
	ds_read_b128 v[214:217], v150 offset:56320
	global_load_lds_dwordx4 v2, s[98:99]
	s_add_i32 m0, m0, 0x2000
	s_nop 0
	global_load_lds_dwordx4 v136, s[98:99]
	s_add_i32 m0, s48, s22
	s_nop 0
	global_load_lds_dwordx4 v2, vcc
	s_add_i32 m0, m0, 0x2000
	s_nop 0
	global_load_lds_dwordx4 v136, vcc
	s_mov_b32 m0, s27
	s_nop 0
	global_load_lds_dwordx4 v132, s[18:19]
	s_mov_b32 m0, s28
	s_nop 0
	global_load_lds_dwordx4 v134, s[18:19]
	s_waitcnt vmcnt(8)
	s_waitcnt lgkmcnt(0)
	s_barrier
	s_setprio 1
	v_mfma_f32_16x16x32_bf16 v[56:59], v[142:145], v[180:183], v[56:59]
	v_mfma_f32_16x16x32_bf16 v[64:67], v[156:159], v[180:183], v[64:67]
	v_mfma_f32_16x16x32_bf16 v[40:43], v[142:145], v[188:191], v[40:43]
	v_mfma_f32_16x16x32_bf16 v[48:51], v[156:159], v[188:191], v[48:51]
	v_mfma_f32_16x16x32_bf16 v[24:27], v[142:145], v[202:205], v[24:27]
	v_mfma_f32_16x16x32_bf16 v[32:35], v[156:159], v[202:205], v[32:35]
	v_mfma_f32_16x16x32_bf16 v[8:11], v[142:145], v[210:213], v[8:11]
	v_mfma_f32_16x16x32_bf16 v[16:19], v[156:159], v[210:213], v[16:19]
	v_mfma_f32_16x16x32_bf16 v[56:59], v[152:155], v[184:187], v[56:59]
	v_mfma_f32_16x16x32_bf16 v[64:67], v[160:163], v[184:187], v[64:67]
	v_mfma_f32_16x16x32_bf16 v[40:43], v[152:155], v[198:201], v[40:43]
	v_mfma_f32_16x16x32_bf16 v[48:51], v[160:163], v[198:201], v[48:51]
	v_mfma_f32_16x16x32_bf16 v[24:27], v[152:155], v[206:209], v[24:27]
	v_mfma_f32_16x16x32_bf16 v[32:35], v[160:163], v[206:209], v[32:35]
	v_mfma_f32_16x16x32_bf16 v[8:11], v[152:155], v[214:217], v[8:11]
	v_mfma_f32_16x16x32_bf16 v[16:19], v[160:163], v[214:217], v[16:19]
	s_setprio 0
	s_setprio 1
	v_mfma_f32_16x16x32_bf16 v[52:55], v[164:167], v[180:183], v[52:55]
	v_mfma_f32_16x16x32_bf16 v[60:63], v[172:175], v[180:183], v[60:63]
	v_mfma_f32_16x16x32_bf16 v[36:39], v[164:167], v[188:191], v[36:39]
	v_mfma_f32_16x16x32_bf16 v[44:47], v[172:175], v[188:191], v[44:47]
	v_mfma_f32_16x16x32_bf16 v[20:23], v[164:167], v[202:205], v[20:23]
	v_mfma_f32_16x16x32_bf16 v[28:31], v[172:175], v[202:205], v[28:31]
	v_mfma_f32_16x16x32_bf16 v[4:7], v[164:167], v[210:213], v[4:7]
	v_mfma_f32_16x16x32_bf16 v[12:15], v[172:175], v[210:213], v[12:15]
	v_mfma_f32_16x16x32_bf16 v[52:55], v[168:171], v[184:187], v[52:55]
	v_mfma_f32_16x16x32_bf16 v[60:63], v[176:179], v[184:187], v[60:63]
	v_mfma_f32_16x16x32_bf16 v[36:39], v[168:171], v[198:201], v[36:39]
	v_mfma_f32_16x16x32_bf16 v[44:47], v[176:179], v[198:201], v[44:47]
	v_mfma_f32_16x16x32_bf16 v[20:23], v[168:171], v[206:209], v[20:23]
	v_mfma_f32_16x16x32_bf16 v[28:31], v[176:179], v[206:209], v[28:31]
	v_mfma_f32_16x16x32_bf16 v[4:7], v[168:171], v[214:217], v[4:7]
	v_mfma_f32_16x16x32_bf16 v[12:15], v[176:179], v[214:217], v[12:15]
	s_setprio 0
	s_barrier
	s_add_u32 s20, s20, 0x100
	s_addc_u32 s21, s21, 0
	s_add_u32 s44, s44, 0x100
	s_addc_u32 s45, s45, 0
	s_cmp_ge_i32 s46, s29
	s_mov_b32 s18, s46
	s_cbranch_scc0 .LBB0_52
	v_readlane_b32 s47, v255, 0
	s_mov_b32 s50, s94
	s_and_b64 vcc, exec, s[12:13]
	s_cbranch_vccnz .LBB0_57
	s_branch .LBB0_58

; #define PG8_STAGE(bufoff, gbase, voff) do { _Pragma("unroll") for (int _i = 0; _i < 2; ++_i) \
;         __builtin_amdgcn_global_load_lds((const unsigned*)((const char*)(gbase) + (voff)[_i]), (PG8_LAS unsigned*)(lds + (bufoff) + ldsw + _i * 8192), 16, 0, 0); } while (0)
; #define PG8_LDA(dst, b, h) do { _Pragma("unroll") for (int m = 0; m < 4; ++m) _Pragma("unroll") for (int k = 0; k < 2; ++k) dst[m][k] = *(const PG8_LAS bf16x8*)(lds + PG8_SA(b, h) + aoff + m * 2048 + k * 1024); } while (0)
; #define PG8_LDB(dst, b, h) do { _Pragma("unroll") for (int n = 0; n < 2; ++n) _Pragma("unroll") for (int k = 0; k < 2; ++k) dst[n][k] = *(const PG8_LAS bf16x8*)(lds + PG8_SB(b, h) + boff + n * 2048 + k * 1024); } while (0)
; #define PG8_MMA(ai, bj, At, Bt) do { __builtin_amdgcn_s_setprio(1); _Pragma("unroll") for (int m = 0; m < 4; ++m) _Pragma("unroll") for (int n = 0; n < 2; ++n) _Pragma("unroll") for (int k = 0; k < 2; ++k) \
;         acc[ai][bj][m][n] = __builtin_amdgcn_mfma_f32_16x16x32_bf16(Bt[n][k], At[m][k], acc[ai][bj][m][n], 0, 0, 0); __builtin_amdgcn_s_setprio(0); } while (0)
; #define PG8_WAIT_V(n) asm volatile("s_waitcnt vmcnt(" #n ")" ::: "memory")
; #define PG8_WAIT_L(n) asm volatile("s_waitcnt lgkmcnt(" #n ")" ::: "memory")
; #define PG8_BAR __builtin_amdgcn_s_barrier()
; template <class Epi, class Sched, bool ALIGN_EPI = false, bool SP2 = false, bool ACHUNK = false>
; __device__ __forceinline__ void gemm_phase(PG8_LAS unsigned char* lds, const Gemm g, const Sched& S, const Epi& E) {
;     ...
;             const char* a1 = cA + (size_t)(t + 1) * kstep;
;             const char* a2 = last ? nA : cA + (size_t)(t + 2) * kstep; const char* b2 = last ? nB : cB + (size_t)(t + 2) * kstep;
;             const char* a3 = a2 + kstep; const char* b3 = b2 + kstep;
;             if (last && has_next) S.a_ready(nxt);
;             if constexpr (SP2) {
;             PG8_LDB(B0, 0, 0); PG8_LDB(B1, 0, 1); PG8_SCHED; PG8_LDA(At, 0, 0); PG8_STAGE(PG8_SA(1, 1), a1 + hstepA, voffA);
;             PG8_WAIT_V(8); PG8_WAIT_L(0); PG8_BAR; PG8_MMA(0, 0, At, B0); PG8_MMA(0, 1, At, B1); PG8_BAR; PG8_SCHED;
;             PG8_LDA(At, 0, 1); PG8_STAGE(PG8_SB(0, 0), b2, voffB); PG8_STAGE(PG8_SB(0, 1), b2 + hstepB, voffB); PG8_STAGE(PG8_SA(0, 0), a2, voffA);
;             PG8_WAIT_V(8); PG8_WAIT_L(0); PG8_BAR; PG8_MMA(1, 0, At, B0); PG8_MMA(1, 1, At, B1); PG8_BAR; PG8_SCHED;
.LBB0_106:
	s_andn2_b64 vcc, exec, s[44:45]
	s_nop 0
	s_cbranch_vccnz .LBB0_110
	s_add_u32 s8, s4, 0x100
	s_addc_u32 s9, s5, 0
	s_add_u32 s0, s6, 0x80
	s_addc_u32 s1, s7, 0
	s_mov_b32 s4, 0
	v_add_u32_e32 v192, 0x10000, v224
	s_add_i32 s6, s4, 2
	s_add_u32 s7, s0, 0x80
	s_addc_u32 s5, s1, 0
	s_add_i32 s77, 0, 0x10000
	s_cmp_eq_u32 s54, s4
	s_cselect_b32 s5, s49, s5
	s_cselect_b32 s4, s48, s7
	s_cselect_b32 s79, s51, s9
	s_cselect_b32 s78, s50, s8
	s_add_i32 s7, 0, 0x14000
	s_waitcnt lgkmcnt(0)
	ds_read_b128 v[36:39], v192
	ds_read_b128 v[40:43], v192 offset:1024
	ds_read_b128 v[44:47], v192 offset:2048
	ds_read_b128 v[48:51], v192 offset:3072
	ds_read_b128 v[52:55], v192 offset:16384
	ds_read_b128 v[56:59], v192 offset:17408
	ds_read_b128 v[60:63], v192 offset:18432
	ds_read_b128 v[64:67], v192 offset:19456
	s_add_u32 s98, s0, s28
	s_addc_u32 s99, s1, s29
	s_add_i32 m0, s25, 0xc000
	ds_read_b128 v[164:167], v238
	ds_read_b128 v[168:171], v238 offset:1024
	ds_read_b128 v[184:187], v238 offset:2048
	ds_read_b128 v[188:191], v238 offset:3072
	ds_read_b128 v[198:201], v238 offset:4096
	ds_read_b128 v[202:205], v238 offset:5120
	ds_read_b128 v[206:209], v238 offset:6144
	ds_read_b128 v[210:213], v238 offset:7168
	global_load_lds_dwordx4 v172, s[98:99]
	s_add_i32 m0, s25, 0xe000
	s_nop 0
	global_load_lds_dwordx4 v176, s[98:99]
	s_waitcnt vmcnt(8)
	s_waitcnt lgkmcnt(0)
	s_barrier
	s_setprio 1
	v_mfma_f32_16x16x32_bf16 v[148:151], v[36:39], v[164:167], 0
	v_mfma_f32_16x16x32_bf16 v[152:155], v[44:47], v[164:167], 0
	v_mfma_f32_16x16x32_bf16 v[132:135], v[36:39], v[184:187], 0
	v_mfma_f32_16x16x32_bf16 v[140:143], v[44:47], v[184:187], 0
	v_mfma_f32_16x16x32_bf16 v[136:139], v[36:39], v[198:201], 0
	v_mfma_f32_16x16x32_bf16 v[144:147], v[44:47], v[198:201], 0
	v_mfma_f32_16x16x32_bf16 v[160:163], v[36:39], v[206:209], 0
	v_mfma_f32_16x16x32_bf16 v[156:159], v[44:47], v[206:209], 0
	v_mfma_f32_16x16x32_bf16 v[148:151], v[40:43], v[168:171], v[148:151]
	v_mfma_f32_16x16x32_bf16 v[152:155], v[48:51], v[168:171], v[152:155]
	v_mfma_f32_16x16x32_bf16 v[132:135], v[40:43], v[188:191], v[132:135]
	v_mfma_f32_16x16x32_bf16 v[140:143], v[48:51], v[188:191], v[140:143]
	v_mfma_f32_16x16x32_bf16 v[136:139], v[40:43], v[202:205], v[136:139]
	v_mfma_f32_16x16x32_bf16 v[144:147], v[48:51], v[202:205], v[144:147]
	v_mfma_f32_16x16x32_bf16 v[160:163], v[40:43], v[210:213], v[160:163]
	v_mfma_f32_16x16x32_bf16 v[156:159], v[48:51], v[210:213], v[156:159]
	s_setprio 0
	s_setprio 1
	v_mfma_f32_16x16x32_bf16 v[124:127], v[52:55], v[164:167], 0
	v_mfma_f32_16x16x32_bf16 v[128:131], v[60:63], v[164:167], 0
	v_mfma_f32_16x16x32_bf16 v[116:119], v[52:55], v[184:187], 0
	v_mfma_f32_16x16x32_bf16 v[120:123], v[60:63], v[184:187], 0
	v_mfma_f32_16x16x32_bf16 v[112:115], v[52:55], v[198:201], 0
	v_mfma_f32_16x16x32_bf16 v[108:111], v[60:63], v[198:201], 0
	v_mfma_f32_16x16x32_bf16 v[104:107], v[52:55], v[206:209], 0
	v_mfma_f32_16x16x32_bf16 v[100:103], v[60:63], v[206:209], 0
	v_mfma_f32_16x16x32_bf16 v[124:127], v[56:59], v[168:171], v[124:127]
	v_mfma_f32_16x16x32_bf16 v[128:131], v[64:67], v[168:171], v[128:131]
	v_mfma_f32_16x16x32_bf16 v[116:119], v[56:59], v[188:191], v[116:119]
	v_mfma_f32_16x16x32_bf16 v[120:123], v[64:67], v[188:191], v[120:123]
	v_mfma_f32_16x16x32_bf16 v[112:115], v[56:59], v[202:205], v[112:115]
	v_mfma_f32_16x16x32_bf16 v[108:111], v[64:67], v[202:205], v[108:111]
	v_mfma_f32_16x16x32_bf16 v[104:107], v[56:59], v[210:213], v[104:107]
	v_mfma_f32_16x16x32_bf16 v[100:103], v[64:67], v[210:213], v[100:103]
	s_setprio 0
	s_barrier
	s_add_i32 s77, s77, s17
	s_add_u32 s98, s78, s18
	s_addc_u32 s99, s79, s19
	s_mov_b32 m0, s77
	ds_read_b128 v[164:167], v238 offset:16384
	ds_read_b128 v[168:171], v238 offset:17408
	ds_read_b128 v[184:187], v238 offset:18432
	ds_read_b128 v[188:191], v238 offset:19456
	ds_read_b128 v[198:201], v238 offset:20480
	ds_read_b128 v[202:205], v238 offset:21504
	ds_read_b128 v[206:209], v238 offset:22528
	ds_read_b128 v[210:213], v238 offset:23552
	global_load_lds_dwordx4 v174, s[78:79]
	s_add_i32 m0, s77, 0x2000
	s_add_i32 s7, s7, s17
	global_load_lds_dwordx4 v178, s[78:79]
	s_mov_b32 m0, s7
	s_nop 0
	global_load_lds_dwordx4 v174, s[98:99]
	s_add_i32 m0, s7, 0x2000
	s_nop 0
	global_load_lds_dwordx4 v178, s[98:99]
	s_mov_b32 m0, s25
	s_nop 0
	global_load_lds_dwordx4 v172, s[4:5]
	s_mov_b32 m0, s26
	s_nop 0
	global_load_lds_dwordx4 v176, s[4:5]
	s_waitcnt vmcnt(8)
	s_waitcnt lgkmcnt(0)
	s_barrier
	s_setprio 1
	v_mfma_f32_16x16x32_bf16 v[96:99], v[36:39], v[164:167], 0
	v_mfma_f32_16x16x32_bf16 v[92:95], v[44:47], v[164:167], 0
	v_mfma_f32_16x16x32_bf16 v[88:91], v[36:39], v[184:187], 0
	v_mfma_f32_16x16x32_bf16 v[84:87], v[44:47], v[184:187], 0
	v_mfma_f32_16x16x32_bf16 v[80:83], v[36:39], v[198:201], 0
	v_mfma_f32_16x16x32_bf16 v[76:79], v[44:47], v[198:201], 0
	v_mfma_f32_16x16x32_bf16 v[36:39], v[36:39], v[206:209], 0
	v_mfma_f32_16x16x32_bf16 v[96:99], v[40:43], v[168:171], v[96:99]
	v_mfma_f32_16x16x32_bf16 v[92:95], v[48:51], v[168:171], v[92:95]
	v_mfma_f32_16x16x32_bf16 v[88:91], v[40:43], v[188:191], v[88:91]
	v_mfma_f32_16x16x32_bf16 v[84:87], v[48:51], v[188:191], v[84:87]
	v_mfma_f32_16x16x32_bf16 v[80:83], v[40:43], v[202:205], v[80:83]
	v_mfma_f32_16x16x32_bf16 v[76:79], v[48:51], v[202:205], v[76:79]
	v_mfma_f32_16x16x32_bf16 v[36:39], v[40:43], v[210:213], v[36:39]
	v_mfma_f32_16x16x32_bf16 v[40:43], v[44:47], v[206:209], 0
	v_mfma_f32_16x16x32_bf16 v[40:43], v[48:51], v[210:213], v[40:43]
	s_setprio 0
	s_setprio 1
	v_mfma_f32_16x16x32_bf16 v[28:31], v[52:55], v[164:167], 0
	v_mfma_f32_16x16x32_bf16 v[32:35], v[60:63], v[164:167], 0
	v_mfma_f32_16x16x32_bf16 v[20:23], v[52:55], v[184:187], 0
	v_mfma_f32_16x16x32_bf16 v[24:27], v[60:63], v[184:187], 0
	v_mfma_f32_16x16x32_bf16 v[16:19], v[52:55], v[198:201], 0
	v_mfma_f32_16x16x32_bf16 v[12:15], v[60:63], v[198:201], 0
	v_mfma_f32_16x16x32_bf16 v[8:11], v[52:55], v[206:209], 0
	v_mfma_f32_16x16x32_bf16 v[4:7], v[60:63], v[206:209], 0
	v_mfma_f32_16x16x32_bf16 v[28:31], v[56:59], v[168:171], v[28:31]
	v_mfma_f32_16x16x32_bf16 v[32:35], v[64:67], v[168:171], v[32:35]
	v_mfma_f32_16x16x32_bf16 v[20:23], v[56:59], v[188:191], v[20:23]
	v_mfma_f32_16x16x32_bf16 v[24:27], v[64:67], v[188:191], v[24:27]
	v_mfma_f32_16x16x32_bf16 v[16:19], v[56:59], v[202:205], v[16:19]
	v_mfma_f32_16x16x32_bf16 v[12:15], v[64:67], v[202:205], v[12:15]
	v_mfma_f32_16x16x32_bf16 v[8:11], v[56:59], v[210:213], v[8:11]
	v_mfma_f32_16x16x32_bf16 v[4:7], v[64:67], v[210:213], v[4:7]
	s_setprio 0
	s_barrier
	s_branch .Lpe_join_108
; #define PG8_STAGE(bufoff, gbase, voff) do { _Pragma("unroll") for (int _i = 0; _i < 2; ++_i) \
;         __builtin_amdgcn_global_load_lds((const unsigned*)((const char*)(gbase) + (voff)[_i]), (PG8_LAS unsigned*)(lds + (bufoff) + ldsw + _i * 8192), 16, 0, 0); } while (0)
; #define PG8_LDA(dst, b, h) do { _Pragma("unroll") for (int m = 0; m < 4; ++m) _Pragma("unroll") for (int k = 0; k < 2; ++k) dst[m][k] = *(const PG8_LAS bf16x8*)(lds + PG8_SA(b, h) + aoff + m * 2048 + k * 1024); } while (0)
; #define PG8_LDB(dst, b, h) do { _Pragma("unroll") for (int n = 0; n < 2; ++n) _Pragma("unroll") for (int k = 0; k < 2; ++k) dst[n][k] = *(const PG8_LAS bf16x8*)(lds + PG8_SB(b, h) + boff + n * 2048 + k * 1024); } while (0)
; #define PG8_MMA(ai, bj, At, Bt) do { __builtin_amdgcn_s_setprio(1); _Pragma("unroll") for (int m = 0; m < 4; ++m) _Pragma("unroll") for (int n = 0; n < 2; ++n) _Pragma("unroll") for (int k = 0; k < 2; ++k) \
;         acc[ai][bj][m][n] = __builtin_amdgcn_mfma_f32_16x16x32_bf16(Bt[n][k], At[m][k], acc[ai][bj][m][n], 0, 0, 0); __builtin_amdgcn_s_setprio(0); } while (0)
; #define PG8_WAIT_V(n) asm volatile("s_waitcnt vmcnt(" #n ")" ::: "memory")
; #define PG8_WAIT_L(n) asm volatile("s_waitcnt lgkmcnt(" #n ")" ::: "memory")
; #define PG8_BAR __builtin_amdgcn_s_barrier()
; #define PG8_SCHED __builtin_amdgcn_sched_barrier(0)
; template <class Epi, class Sched, bool ALIGN_EPI = false, bool SP2 = false, bool ACHUNK = false>
; __device__ __forceinline__ void gemm_phase(PG8_LAS unsigned char* lds, const Gemm g, const Sched& S, const Epi& E) {
;     ...
;             PG8_LDB(B0, 0, 0); PG8_LDB(B1, 0, 1); PG8_SCHED; PG8_LDA(At, 0, 0); PG8_STAGE(PG8_SA(1, 1), a1 + hstepA, voffA);
;             PG8_WAIT_V(8); PG8_WAIT_L(0); PG8_BAR; PG8_MMA(0, 0, At, B0); PG8_MMA(0, 1, At, B1); PG8_BAR; PG8_SCHED;
;             PG8_LDA(At, 0, 1); PG8_STAGE(PG8_SB(0, 0), b2, voffB); PG8_STAGE(PG8_SB(0, 1), b2 + hstepB, voffB); PG8_STAGE(PG8_SA(0, 0), a2, voffA);
;             PG8_WAIT_V(8); PG8_WAIT_L(0); PG8_BAR; PG8_MMA(1, 0, At, B0); PG8_MMA(1, 1, At, B1); PG8_BAR; PG8_SCHED;
.LBB0_108:
	s_add_i32 s6, s4, 2
	s_add_u32 s7, s0, 0x80
	s_addc_u32 s5, s1, 0
	s_add_i32 s77, 0, 0x10000
	s_cmp_eq_u32 s54, s4
	s_cselect_b32 s5, s49, s5
	s_cselect_b32 s4, s48, s7
	s_cselect_b32 s79, s51, s9
	s_cselect_b32 s78, s50, s8
	s_add_i32 s7, 0, 0x14000
	s_waitcnt lgkmcnt(0)
	ds_read_b128 v[36:39], v192
	ds_read_b128 v[40:43], v192 offset:1024
	ds_read_b128 v[44:47], v192 offset:2048
	ds_read_b128 v[48:51], v192 offset:3072
	ds_read_b128 v[52:55], v192 offset:16384
	ds_read_b128 v[56:59], v192 offset:17408
	ds_read_b128 v[60:63], v192 offset:18432
	ds_read_b128 v[64:67], v192 offset:19456
	s_add_u32 s98, s0, s28
	s_addc_u32 s99, s1, s29
	s_add_i32 m0, s25, 0xc000
	ds_read_b128 v[164:167], v238
	ds_read_b128 v[168:171], v238 offset:1024
	ds_read_b128 v[184:187], v238 offset:2048
	ds_read_b128 v[188:191], v238 offset:3072
	ds_read_b128 v[198:201], v238 offset:4096
	ds_read_b128 v[202:205], v238 offset:5120
	ds_read_b128 v[206:209], v238 offset:6144
	ds_read_b128 v[210:213], v238 offset:7168
	global_load_lds_dwordx4 v172, s[98:99]
	s_add_i32 m0, s25, 0xe000
	s_nop 0
	global_load_lds_dwordx4 v176, s[98:99]
	s_waitcnt vmcnt(8)
	s_waitcnt lgkmcnt(0)
	s_barrier
	s_setprio 1
	v_mfma_f32_16x16x32_bf16 v[148:151], v[36:39], v[164:167], v[148:151]
	v_mfma_f32_16x16x32_bf16 v[152:155], v[44:47], v[164:167], v[152:155]
	v_mfma_f32_16x16x32_bf16 v[132:135], v[36:39], v[184:187], v[132:135]
	v_mfma_f32_16x16x32_bf16 v[140:143], v[44:47], v[184:187], v[140:143]
	v_mfma_f32_16x16x32_bf16 v[136:139], v[36:39], v[198:201], v[136:139]
	v_mfma_f32_16x16x32_bf16 v[144:147], v[44:47], v[198:201], v[144:147]
	v_mfma_f32_16x16x32_bf16 v[160:163], v[36:39], v[206:209], v[160:163]
	v_mfma_f32_16x16x32_bf16 v[156:159], v[44:47], v[206:209], v[156:159]
	v_mfma_f32_16x16x32_bf16 v[148:151], v[40:43], v[168:171], v[148:151]
	v_mfma_f32_16x16x32_bf16 v[152:155], v[48:51], v[168:171], v[152:155]
	v_mfma_f32_16x16x32_bf16 v[132:135], v[40:43], v[188:191], v[132:135]
	v_mfma_f32_16x16x32_bf16 v[140:143], v[48:51], v[188:191], v[140:143]
	v_mfma_f32_16x16x32_bf16 v[136:139], v[40:43], v[202:205], v[136:139]
	v_mfma_f32_16x16x32_bf16 v[144:147], v[48:51], v[202:205], v[144:147]
	v_mfma_f32_16x16x32_bf16 v[160:163], v[40:43], v[210:213], v[160:163]
	v_mfma_f32_16x16x32_bf16 v[156:159], v[48:51], v[210:213], v[156:159]
	s_setprio 0
	s_setprio 1
	v_mfma_f32_16x16x32_bf16 v[124:127], v[52:55], v[164:167], v[124:127]
	v_mfma_f32_16x16x32_bf16 v[128:131], v[60:63], v[164:167], v[128:131]
	v_mfma_f32_16x16x32_bf16 v[116:119], v[52:55], v[184:187], v[116:119]
	v_mfma_f32_16x16x32_bf16 v[120:123], v[60:63], v[184:187], v[120:123]
	v_mfma_f32_16x16x32_bf16 v[112:115], v[52:55], v[198:201], v[112:115]
	v_mfma_f32_16x16x32_bf16 v[108:111], v[60:63], v[198:201], v[108:111]
	v_mfma_f32_16x16x32_bf16 v[104:107], v[52:55], v[206:209], v[104:107]
	v_mfma_f32_16x16x32_bf16 v[100:103], v[60:63], v[206:209], v[100:103]
	v_mfma_f32_16x16x32_bf16 v[124:127], v[56:59], v[168:171], v[124:127]
	v_mfma_f32_16x16x32_bf16 v[128:131], v[64:67], v[168:171], v[128:131]
	v_mfma_f32_16x16x32_bf16 v[116:119], v[56:59], v[188:191], v[116:119]
	v_mfma_f32_16x16x32_bf16 v[120:123], v[64:67], v[188:191], v[120:123]
	v_mfma_f32_16x16x32_bf16 v[112:115], v[56:59], v[202:205], v[112:115]
	v_mfma_f32_16x16x32_bf16 v[108:111], v[64:67], v[202:205], v[108:111]
	v_mfma_f32_16x16x32_bf16 v[104:107], v[56:59], v[210:213], v[104:107]
	v_mfma_f32_16x16x32_bf16 v[100:103], v[64:67], v[210:213], v[100:103]
	s_setprio 0
	s_barrier
	s_add_i32 s77, s77, s17
	s_add_u32 s98, s78, s18
	s_addc_u32 s99, s79, s19
	s_mov_b32 m0, s77
	ds_read_b128 v[164:167], v238 offset:16384
	ds_read_b128 v[168:171], v238 offset:17408
	ds_read_b128 v[184:187], v238 offset:18432
	ds_read_b128 v[188:191], v238 offset:19456
	ds_read_b128 v[198:201], v238 offset:20480
	ds_read_b128 v[202:205], v238 offset:21504
	ds_read_b128 v[206:209], v238 offset:22528
	ds_read_b128 v[210:213], v238 offset:23552
	global_load_lds_dwordx4 v174, s[78:79]
	s_add_i32 m0, s77, 0x2000
	s_add_i32 s7, s7, s17
	global_load_lds_dwordx4 v178, s[78:79]
	s_mov_b32 m0, s7
	s_nop 0
	global_load_lds_dwordx4 v174, s[98:99]
	s_add_i32 m0, s7, 0x2000
	s_nop 0
	global_load_lds_dwordx4 v178, s[98:99]
	s_mov_b32 m0, s25
	s_nop 0
	global_load_lds_dwordx4 v172, s[4:5]
	s_mov_b32 m0, s26
	s_nop 0
	global_load_lds_dwordx4 v176, s[4:5]
	s_waitcnt vmcnt(8)
	s_waitcnt lgkmcnt(0)
	s_barrier
	s_setprio 1
	v_mfma_f32_16x16x32_bf16 v[96:99], v[36:39], v[164:167], v[96:99]
	v_mfma_f32_16x16x32_bf16 v[92:95], v[44:47], v[164:167], v[92:95]
	v_mfma_f32_16x16x32_bf16 v[88:91], v[36:39], v[184:187], v[88:91]
	v_mfma_f32_16x16x32_bf16 v[84:87], v[44:47], v[184:187], v[84:87]
	v_mfma_f32_16x16x32_bf16 v[80:83], v[36:39], v[198:201], v[80:83]
	v_mfma_f32_16x16x32_bf16 v[76:79], v[44:47], v[198:201], v[76:79]
	v_mfma_f32_16x16x32_bf16 v[36:39], v[36:39], v[206:209], v[72:75]
	v_mfma_f32_16x16x32_bf16 v[96:99], v[40:43], v[168:171], v[96:99]
	v_mfma_f32_16x16x32_bf16 v[92:95], v[48:51], v[168:171], v[92:95]
	v_mfma_f32_16x16x32_bf16 v[88:91], v[40:43], v[188:191], v[88:91]
	v_mfma_f32_16x16x32_bf16 v[84:87], v[48:51], v[188:191], v[84:87]
	v_mfma_f32_16x16x32_bf16 v[80:83], v[40:43], v[202:205], v[80:83]
	v_mfma_f32_16x16x32_bf16 v[76:79], v[48:51], v[202:205], v[76:79]
	v_mfma_f32_16x16x32_bf16 v[36:39], v[40:43], v[210:213], v[36:39]
	v_mfma_f32_16x16x32_bf16 v[40:43], v[44:47], v[206:209], v[68:71]
	v_mfma_f32_16x16x32_bf16 v[40:43], v[48:51], v[210:213], v[40:43]
	s_setprio 0
	s_setprio 1
	v_mfma_f32_16x16x32_bf16 v[28:31], v[52:55], v[164:167], v[28:31]
	v_mfma_f32_16x16x32_bf16 v[32:35], v[60:63], v[164:167], v[32:35]
	v_mfma_f32_16x16x32_bf16 v[20:23], v[52:55], v[184:187], v[20:23]
	v_mfma_f32_16x16x32_bf16 v[24:27], v[60:63], v[184:187], v[24:27]
	v_mfma_f32_16x16x32_bf16 v[16:19], v[52:55], v[198:201], v[16:19]
	v_mfma_f32_16x16x32_bf16 v[12:15], v[60:63], v[198:201], v[12:15]
	v_mfma_f32_16x16x32_bf16 v[8:11], v[52:55], v[206:209], v[8:11]
	v_mfma_f32_16x16x32_bf16 v[4:7], v[60:63], v[206:209], v[4:7]
	v_mfma_f32_16x16x32_bf16 v[28:31], v[56:59], v[168:171], v[28:31]
	v_mfma_f32_16x16x32_bf16 v[32:35], v[64:67], v[168:171], v[32:35]
	v_mfma_f32_16x16x32_bf16 v[20:23], v[56:59], v[188:191], v[20:23]
	v_mfma_f32_16x16x32_bf16 v[24:27], v[64:67], v[188:191], v[24:27]
	v_mfma_f32_16x16x32_bf16 v[16:19], v[56:59], v[202:205], v[16:19]
	v_mfma_f32_16x16x32_bf16 v[12:15], v[64:67], v[202:205], v[12:15]
	v_mfma_f32_16x16x32_bf16 v[8:11], v[56:59], v[210:213], v[8:11]
	v_mfma_f32_16x16x32_bf16 v[4:7], v[64:67], v[210:213], v[4:7]
	s_setprio 0
	s_barrier
; #define PG8_STAGE(bufoff, gbase, voff) do { _Pragma("unroll") for (int _i = 0; _i < 2; ++_i) \
;         __builtin_amdgcn_global_load_lds((const unsigned*)((const char*)(gbase) + (voff)[_i]), (PG8_LAS unsigned*)(lds + (bufoff) + ldsw + _i * 8192), 16, 0, 0); } while (0)
; #define PG8_LDA(dst, b, h) do { _Pragma("unroll") for (int m = 0; m < 4; ++m) _Pragma("unroll") for (int k = 0; k < 2; ++k) dst[m][k] = *(const PG8_LAS bf16x8*)(lds + PG8_SA(b, h) + aoff + m * 2048 + k * 1024); } while (0)
; #define PG8_LDB(dst, b, h) do { _Pragma("unroll") for (int n = 0; n < 2; ++n) _Pragma("unroll") for (int k = 0; k < 2; ++k) dst[n][k] = *(const PG8_LAS bf16x8*)(lds + PG8_SB(b, h) + boff + n * 2048 + k * 1024); } while (0)
; #define PG8_MMA(ai, bj, At, Bt) do { __builtin_amdgcn_s_setprio(1); _Pragma("unroll") for (int m = 0; m < 4; ++m) _Pragma("unroll") for (int n = 0; n < 2; ++n) _Pragma("unroll") for (int k = 0; k < 2; ++k) \
;         acc[ai][bj][m][n] = __builtin_amdgcn_mfma_f32_16x16x32_bf16(Bt[n][k], At[m][k], acc[ai][bj][m][n], 0, 0, 0); __builtin_amdgcn_s_setprio(0); } while (0)
; #define PG8_WAIT_V(n) asm volatile("s_waitcnt vmcnt(" #n ")" ::: "memory")
; #define PG8_WAIT_L(n) asm volatile("s_waitcnt lgkmcnt(" #n ")" ::: "memory")
; #define PG8_BAR __builtin_amdgcn_s_barrier()
; #define PG8_SCHED __builtin_amdgcn_sched_barrier(0)
; template <class Epi, class Sched, bool ALIGN_EPI = false, bool SP2 = false, bool ACHUNK = false>
; __device__ __forceinline__ void gemm_phase(PG8_LAS unsigned char* lds, const Gemm g, const Sched& S, const Epi& E) {
;     ...
;         for (int t = 0; t < nt; t += 2) {
;     ...
;             PG8_LDB(B0, 1, 0); PG8_LDB(B1, 1, 1); PG8_SCHED; PG8_LDA(At, 1, 0); PG8_STAGE(PG8_SA(0, 1), a2 + hstepA, voffA);
;             PG8_WAIT_V(8); PG8_WAIT_L(0); PG8_BAR; PG8_MMA(0, 0, At, B0); PG8_MMA(0, 1, At, B1); PG8_BAR; PG8_SCHED;
;             PG8_LDA(At, 1, 1); PG8_STAGE(PG8_SB(1, 0), b3, voffB); PG8_STAGE(PG8_SB(1, 1), b3 + hstepB, voffB); PG8_STAGE(PG8_SA(1, 0), a3, voffA);
;             PG8_WAIT_V(8); PG8_WAIT_L(0); PG8_BAR; PG8_MMA(1, 0, At, B0); PG8_MMA(1, 1, At, B1); PG8_BAR; PG8_SCHED;
.Lpe_join_108:
	s_add_i32 s7, 0, 0x18000
	s_add_i32 s77, 0, 0x1c000
	ds_read_b128 v[44:47], v192 offset:32768
	ds_read_b128 v[48:51], v192 offset:33792
	ds_read_b128 v[52:55], v192 offset:34816
	ds_read_b128 v[56:59], v192 offset:35840
	ds_read_b128 v[60:63], v192 offset:49152
	ds_read_b128 v[64:67], v192 offset:50176
	ds_read_b128 v[164:167], v192 offset:51200
	ds_read_b128 v[168:171], v192 offset:52224
	s_add_u32 s4, s4, s28
	s_addc_u32 s5, s5, s29
	s_mov_b32 m0, s27
	ds_read_b128 v[68:71], v238 offset:32768
	ds_read_b128 v[72:75], v238 offset:33792
	ds_read_b128 v[184:187], v238 offset:34816
	ds_read_b128 v[188:191], v238 offset:35840
	ds_read_b128 v[198:201], v238 offset:36864
	ds_read_b128 v[202:205], v238 offset:37888
	ds_read_b128 v[206:209], v238 offset:38912
	ds_read_b128 v[210:213], v238 offset:39936
	global_load_lds_dwordx4 v172, s[4:5]
	s_mov_b32 m0, s36
	s_nop 0
	global_load_lds_dwordx4 v176, s[4:5]
	s_waitcnt vmcnt(8)
	s_waitcnt lgkmcnt(0)
	s_barrier
	s_setprio 1
	v_mfma_f32_16x16x32_bf16 v[148:151], v[44:47], v[68:71], v[148:151]
	v_mfma_f32_16x16x32_bf16 v[152:155], v[52:55], v[68:71], v[152:155]
	v_mfma_f32_16x16x32_bf16 v[132:135], v[44:47], v[184:187], v[132:135]
	v_mfma_f32_16x16x32_bf16 v[140:143], v[52:55], v[184:187], v[140:143]
	v_mfma_f32_16x16x32_bf16 v[136:139], v[44:47], v[198:201], v[136:139]
	v_mfma_f32_16x16x32_bf16 v[144:147], v[52:55], v[198:201], v[144:147]
	v_mfma_f32_16x16x32_bf16 v[160:163], v[44:47], v[206:209], v[160:163]
	v_mfma_f32_16x16x32_bf16 v[156:159], v[52:55], v[206:209], v[156:159]
	v_mfma_f32_16x16x32_bf16 v[148:151], v[48:51], v[72:75], v[148:151]
	v_mfma_f32_16x16x32_bf16 v[152:155], v[56:59], v[72:75], v[152:155]
	v_mfma_f32_16x16x32_bf16 v[132:135], v[48:51], v[188:191], v[132:135]
	v_mfma_f32_16x16x32_bf16 v[140:143], v[56:59], v[188:191], v[140:143]
	v_mfma_f32_16x16x32_bf16 v[136:139], v[48:51], v[202:205], v[136:139]
	v_mfma_f32_16x16x32_bf16 v[144:147], v[56:59], v[202:205], v[144:147]
	v_mfma_f32_16x16x32_bf16 v[160:163], v[48:51], v[210:213], v[160:163]
	v_mfma_f32_16x16x32_bf16 v[156:159], v[56:59], v[210:213], v[156:159]
	s_setprio 0
	s_setprio 1
	v_mfma_f32_16x16x32_bf16 v[124:127], v[60:63], v[68:71], v[124:127]
	v_mfma_f32_16x16x32_bf16 v[68:71], v[164:167], v[68:71], v[128:131]
	v_mfma_f32_16x16x32_bf16 v[128:131], v[168:171], v[72:75], v[68:71]
	v_mfma_f32_16x16x32_bf16 v[68:71], v[60:63], v[184:187], v[116:119]
	v_mfma_f32_16x16x32_bf16 v[116:119], v[64:67], v[188:191], v[68:71]
	v_mfma_f32_16x16x32_bf16 v[68:71], v[164:167], v[184:187], v[120:123]
	v_mfma_f32_16x16x32_bf16 v[120:123], v[168:171], v[188:191], v[68:71]
	v_mfma_f32_16x16x32_bf16 v[68:71], v[60:63], v[198:201], v[112:115]
	v_mfma_f32_16x16x32_bf16 v[112:115], v[64:67], v[202:205], v[68:71]
	v_mfma_f32_16x16x32_bf16 v[68:71], v[164:167], v[198:201], v[108:111]
	v_mfma_f32_16x16x32_bf16 v[108:111], v[168:171], v[202:205], v[68:71]
	v_mfma_f32_16x16x32_bf16 v[68:71], v[60:63], v[206:209], v[104:107]
	v_mfma_f32_16x16x32_bf16 v[104:107], v[64:67], v[210:213], v[68:71]
	v_mfma_f32_16x16x32_bf16 v[68:71], v[164:167], v[206:209], v[100:103]
	v_mfma_f32_16x16x32_bf16 v[124:127], v[64:67], v[72:75], v[124:127]
	v_mfma_f32_16x16x32_bf16 v[100:103], v[168:171], v[210:213], v[68:71]
	s_setprio 0
	s_barrier
	s_sub_u32 s4, s4, s28
	s_subb_u32 s5, s5, s29
	s_add_u32 s4, s4, s10
	s_addc_u32 s5, s5, s11
	s_add_u32 s78, s78, s10
	s_addc_u32 s79, s79, s11
	s_add_u32 s98, s98, s10
	s_addc_u32 s99, s99, s11
	s_add_i32 m0, s7, s17
	ds_read_b128 v[184:187], v238 offset:49152
	ds_read_b128 v[188:191], v238 offset:50176
	ds_read_b128 v[198:201], v238 offset:51200
	ds_read_b128 v[202:205], v238 offset:52224
	ds_read_b128 v[206:209], v238 offset:53248
	ds_read_b128 v[210:213], v238 offset:54272
	ds_read_b128 v[214:217], v238 offset:55296
	ds_read_b128 v[218:221], v238 offset:56320
	global_load_lds_dwordx4 v174, s[78:79]
	s_add_i32 m0, m0, 0x2000
	s_nop 0
	global_load_lds_dwordx4 v178, s[78:79]
	s_add_i32 m0, s77, s17
	s_nop 0
	global_load_lds_dwordx4 v174, s[98:99]
	s_add_i32 m0, m0, 0x2000
	s_nop 0
	global_load_lds_dwordx4 v178, s[98:99]
	s_mov_b32 m0, s52
	s_nop 0
	global_load_lds_dwordx4 v172, s[4:5]
	s_mov_b32 m0, s53
	s_nop 0
	global_load_lds_dwordx4 v176, s[4:5]
	s_waitcnt vmcnt(8)
	s_waitcnt lgkmcnt(0)
	s_barrier
	s_setprio 1
	v_mfma_f32_16x16x32_bf16 v[68:71], v[44:47], v[184:187], v[96:99]
	v_mfma_f32_16x16x32_bf16 v[96:99], v[48:51], v[188:191], v[68:71]
	v_mfma_f32_16x16x32_bf16 v[68:71], v[52:55], v[184:187], v[92:95]
	v_mfma_f32_16x16x32_bf16 v[92:95], v[56:59], v[188:191], v[68:71]
	v_mfma_f32_16x16x32_bf16 v[68:71], v[44:47], v[198:201], v[88:91]
	v_mfma_f32_16x16x32_bf16 v[88:91], v[48:51], v[202:205], v[68:71]
	v_mfma_f32_16x16x32_bf16 v[68:71], v[52:55], v[198:201], v[84:87]
	v_mfma_f32_16x16x32_bf16 v[84:87], v[56:59], v[202:205], v[68:71]
	v_mfma_f32_16x16x32_bf16 v[68:71], v[44:47], v[206:209], v[80:83]
	v_mfma_f32_16x16x32_bf16 v[36:39], v[44:47], v[214:217], v[36:39]
	v_mfma_f32_16x16x32_bf16 v[80:83], v[48:51], v[210:213], v[68:71]
	v_mfma_f32_16x16x32_bf16 v[68:71], v[52:55], v[206:209], v[76:79]
	v_mfma_f32_16x16x32_bf16 v[72:75], v[48:51], v[218:221], v[36:39]
	v_mfma_f32_16x16x32_bf16 v[36:39], v[52:55], v[214:217], v[40:43]
	v_mfma_f32_16x16x32_bf16 v[76:79], v[56:59], v[210:213], v[68:71]
	v_mfma_f32_16x16x32_bf16 v[68:71], v[56:59], v[218:221], v[36:39]
	s_setprio 0
	s_setprio 1
	v_mfma_f32_16x16x32_bf16 v[28:31], v[60:63], v[184:187], v[28:31]
	v_mfma_f32_16x16x32_bf16 v[32:35], v[164:167], v[184:187], v[32:35]
	v_mfma_f32_16x16x32_bf16 v[20:23], v[60:63], v[198:201], v[20:23]
	v_mfma_f32_16x16x32_bf16 v[24:27], v[164:167], v[198:201], v[24:27]
	v_mfma_f32_16x16x32_bf16 v[16:19], v[60:63], v[206:209], v[16:19]
	v_mfma_f32_16x16x32_bf16 v[12:15], v[164:167], v[206:209], v[12:15]
	v_mfma_f32_16x16x32_bf16 v[8:11], v[60:63], v[214:217], v[8:11]
	v_mfma_f32_16x16x32_bf16 v[4:7], v[164:167], v[214:217], v[4:7]
	v_mfma_f32_16x16x32_bf16 v[28:31], v[64:67], v[188:191], v[28:31]
	v_mfma_f32_16x16x32_bf16 v[32:35], v[168:171], v[188:191], v[32:35]
	v_mfma_f32_16x16x32_bf16 v[20:23], v[64:67], v[202:205], v[20:23]
	v_mfma_f32_16x16x32_bf16 v[24:27], v[168:171], v[202:205], v[24:27]
	v_mfma_f32_16x16x32_bf16 v[16:19], v[64:67], v[210:213], v[16:19]
	v_mfma_f32_16x16x32_bf16 v[12:15], v[168:171], v[210:213], v[12:15]
	v_mfma_f32_16x16x32_bf16 v[8:11], v[64:67], v[218:221], v[8:11]
	v_mfma_f32_16x16x32_bf16 v[4:7], v[168:171], v[218:221], v[4:7]
	s_setprio 0
	s_barrier
	s_add_u32 s8, s8, 0x100
	s_addc_u32 s9, s9, 0
	s_add_u32 s0, s0, 0x100
	s_addc_u32 s1, s1, 0
	s_cmp_ge_i32 s6, s37
	s_mov_b32 s4, s6
	s_cbranch_scc0 .LBB0_108
	v_readlane_b32 s78, v254, 23
	v_readlane_b32 s79, v254, 24

; #define PG8_STAGE(bufoff, gbase, voff) do { _Pragma("unroll") for (int _i = 0; _i < 2; ++_i) \
;         __builtin_amdgcn_global_load_lds((const unsigned*)((const char*)(gbase) + (voff)[_i]), (PG8_LAS unsigned*)(lds + (bufoff) + ldsw + _i * 8192), 16, 0, 0); } while (0)
; #define PG8_LDA(dst, b, h) do { _Pragma("unroll") for (int m = 0; m < 4; ++m) _Pragma("unroll") for (int k = 0; k < 2; ++k) dst[m][k] = *(const PG8_LAS bf16x8*)(lds + PG8_SA(b, h) + aoff + m * 2048 + k * 1024); } while (0)
; #define PG8_LDB(dst, b, h) do { _Pragma("unroll") for (int n = 0; n < 2; ++n) _Pragma("unroll") for (int k = 0; k < 2; ++k) dst[n][k] = *(const PG8_LAS bf16x8*)(lds + PG8_SB(b, h) + boff + n * 2048 + k * 1024); } while (0)
; #define PG8_WAIT_V(n) asm volatile("s_waitcnt vmcnt(" #n ")" ::: "memory")
; #define PG8_WAIT_L(n) asm volatile("s_waitcnt lgkmcnt(" #n ")" ::: "memory")
; template <class Epi, class Sched, bool ALIGN_EPI = false, bool SP2 = false, bool ACHUNK = false>
; __device__ __forceinline__ void gemm_phase(PG8_LAS unsigned char* lds, const Gemm g, const Sched& S, const Epi& E) {
;     ...
;         const bool has_next = S.next(ui + 1, nxt);
;         const char* nA = has_next ? (const char*)g.A + (size_t)nxt.pm * tstepA : cA; const char* nB = has_next ? (const char*)g.Bt + (size_t)nxt.pn * tstepB : cB;
;         for (int t = 0; t < nt; t += 2) {
;             const bool last = (t == nt - 2);
;             if constexpr (Epi::HAS_MID) { if (t == Epi::MID_T) E.mid(acc, cur, wr, wc, fr, fq, ShflDev{}); }
;             const char* a1 = cA + (size_t)(t + 1) * kstep;
;             const char* a2 = last ? nA : cA + (size_t)(t + 2) * kstep; const char* b2 = last ? nB : cB + (size_t)(t + 2) * kstep;
;             const char* a3 = a2 + kstep; const char* b3 = b2 + kstep;
;             if (last && has_next) S.a_ready(nxt);
;             if constexpr (SP2) {
;             PG8_LDB(B0, 0, 0); PG8_LDB(B1, 0, 1); PG8_SCHED; PG8_LDA(At, 0, 0); PG8_STAGE(PG8_SA(1, 1), a1 + hstepA, voffA);
;             PG8_WAIT_V(8); PG8_WAIT_L(0); PG8_BAR; PG8_MMA(0, 0, At, B0); PG8_MMA(0, 1, At, B1); PG8_BAR; PG8_SCHED;
;             PG8_LDA(At, 0, 1); PG8_STAGE(PG8_SB(0, 0), b2, voffB); PG8_STAGE(PG8_SB(0, 1), b2 + hstepB, voffB); PG8_STAGE(PG8_SA(0, 0), a2, voffA);
;             PG8_WAIT_V(8); PG8_WAIT_L(0); PG8_BAR; PG8_MMA(1, 0, At, B0); PG8_MMA(1, 1, At, B1); PG8_BAR; PG8_SCHED;
.LBB0_215:
	s_add_u32 s48, s20, 0x100
	s_addc_u32 s49, s21, 0
	s_add_u32 s20, s22, 0x80
	s_addc_u32 s21, s23, 0
	s_mov_b32 s22, 0
	v_add_u32_e32 v192, 0x10000, v147
.LBB0_216:
	s_add_i32 s50, s22, 2
	s_add_u32 s51, s20, 0x80
	s_addc_u32 s23, s21, 0
	s_add_i32 s54, 0, 0x10000
	s_cmp_eq_u32 s35, s22
	s_cselect_b32 s23, s1, s23
	s_cselect_b32 s22, s0, s51
	s_cselect_b32 s53, s19, s49
	s_cselect_b32 s52, s18, s48
	s_cbranch_scc0 .Lnl_wo
	s_cmpk_lg_u32 s87, 0x100
	s_cbranch_scc1 .Lnl_wo
	v_mov_b32_e32 v2, 0
	v_mov_b32_e32 v136, 0
	v_mov_b32_e32 v132, 0
	v_mov_b32_e32 v134, 0
.Lnl_wo:
	s_add_i32 s51, 0, 0x14000
	ds_read_b128 v[142:145], v192
	ds_read_b128 v[152:155], v192 offset:1024
	ds_read_b128 v[156:159], v192 offset:2048
	ds_read_b128 v[160:163], v192 offset:3072
	ds_read_b128 v[164:167], v192 offset:16384
	ds_read_b128 v[168:171], v192 offset:17408
	ds_read_b128 v[172:175], v192 offset:18432
	ds_read_b128 v[176:179], v192 offset:19456
	s_add_i32 m0, s27, 0xc000
	ds_read_b128 v[180:183], v149
	ds_read_b128 v[184:187], v149 offset:1024
	ds_read_b128 v[188:191], v149 offset:2048
	ds_read_b128 v[198:201], v149 offset:3072
	ds_read_b128 v[202:205], v149 offset:4096
	ds_read_b128 v[206:209], v149 offset:5120
	ds_read_b128 v[210:213], v149 offset:6144
	ds_read_b128 v[214:217], v149 offset:7168
	global_load_lds_dwordx4 v138, s[20:21]
	s_add_i32 m0, s27, 0xe000
	s_nop 0
	global_load_lds_dwordx4 v140, s[20:21]
	s_waitcnt vmcnt(8)
	s_waitcnt lgkmcnt(0)
	s_barrier
	s_setprio 1
	v_mfma_f32_16x16x32_bf16 v[120:123], v[142:145], v[180:183], v[120:123]
	v_mfma_f32_16x16x32_bf16 v[128:131], v[156:159], v[180:183], v[128:131]
	v_mfma_f32_16x16x32_bf16 v[104:107], v[142:145], v[188:191], v[104:107]
	v_mfma_f32_16x16x32_bf16 v[112:115], v[156:159], v[188:191], v[112:115]
	v_mfma_f32_16x16x32_bf16 v[88:91], v[142:145], v[202:205], v[88:91]
	v_mfma_f32_16x16x32_bf16 v[96:99], v[156:159], v[202:205], v[96:99]
	v_mfma_f32_16x16x32_bf16 v[72:75], v[142:145], v[210:213], v[72:75]
	v_mfma_f32_16x16x32_bf16 v[80:83], v[156:159], v[210:213], v[80:83]
	v_mfma_f32_16x16x32_bf16 v[120:123], v[152:155], v[184:187], v[120:123]
	v_mfma_f32_16x16x32_bf16 v[128:131], v[160:163], v[184:187], v[128:131]
	v_mfma_f32_16x16x32_bf16 v[104:107], v[152:155], v[198:201], v[104:107]
	v_mfma_f32_16x16x32_bf16 v[112:115], v[160:163], v[198:201], v[112:115]
	v_mfma_f32_16x16x32_bf16 v[88:91], v[152:155], v[206:209], v[88:91]
	v_mfma_f32_16x16x32_bf16 v[96:99], v[160:163], v[206:209], v[96:99]
	v_mfma_f32_16x16x32_bf16 v[72:75], v[152:155], v[214:217], v[72:75]
	v_mfma_f32_16x16x32_bf16 v[80:83], v[160:163], v[214:217], v[80:83]
	s_setprio 0
	s_setprio 1
	v_mfma_f32_16x16x32_bf16 v[116:119], v[164:167], v[180:183], v[116:119]
	v_mfma_f32_16x16x32_bf16 v[124:127], v[172:175], v[180:183], v[124:127]
	v_mfma_f32_16x16x32_bf16 v[100:103], v[164:167], v[188:191], v[100:103]
	v_mfma_f32_16x16x32_bf16 v[108:111], v[172:175], v[188:191], v[108:111]
	v_mfma_f32_16x16x32_bf16 v[84:87], v[164:167], v[202:205], v[84:87]
	v_mfma_f32_16x16x32_bf16 v[92:95], v[172:175], v[202:205], v[92:95]
	v_mfma_f32_16x16x32_bf16 v[68:71], v[164:167], v[210:213], v[68:71]
	v_mfma_f32_16x16x32_bf16 v[76:79], v[172:175], v[210:213], v[76:79]
	v_mfma_f32_16x16x32_bf16 v[116:119], v[168:171], v[184:187], v[116:119]
	v_mfma_f32_16x16x32_bf16 v[124:127], v[176:179], v[184:187], v[124:127]
	v_mfma_f32_16x16x32_bf16 v[100:103], v[168:171], v[198:201], v[100:103]
	v_mfma_f32_16x16x32_bf16 v[108:111], v[176:179], v[198:201], v[108:111]
	v_mfma_f32_16x16x32_bf16 v[84:87], v[168:171], v[206:209], v[84:87]
	v_mfma_f32_16x16x32_bf16 v[92:95], v[176:179], v[206:209], v[92:95]
	v_mfma_f32_16x16x32_bf16 v[68:71], v[168:171], v[214:217], v[68:71]
	v_mfma_f32_16x16x32_bf16 v[76:79], v[176:179], v[214:217], v[76:79]
	s_setprio 0
	s_barrier
	s_add_i32 s54, s54, s26
	s_mov_b32 m0, s54
	ds_read_b128 v[180:183], v149 offset:16384
	ds_read_b128 v[184:187], v149 offset:17408
	ds_read_b128 v[188:191], v149 offset:18432
	ds_read_b128 v[198:201], v149 offset:19456
	ds_read_b128 v[202:205], v149 offset:20480
	ds_read_b128 v[206:209], v149 offset:21504
	ds_read_b128 v[210:213], v149 offset:22528
	ds_read_b128 v[214:217], v149 offset:23552
	global_load_lds_dwordx4 v2, s[52:53]
	s_add_i32 m0, s54, 0x2000
	s_add_i32 s51, s51, s26
	global_load_lds_dwordx4 v136, s[52:53]
	s_add_u32 s52, s52, s4
	s_addc_u32 s53, s53, s5
	s_mov_b64 vcc, s[52:53]
	s_sub_u32 s98, s52, s4
	s_subb_u32 s99, s53, s5
	s_mov_b32 m0, s51
	s_nop 0
	global_load_lds_dwordx4 v2, s[52:53]
	s_add_i32 m0, s51, 0x2000
	s_nop 0
	global_load_lds_dwordx4 v136, s[52:53]
	s_mov_b32 m0, s27
	s_nop 0
	global_load_lds_dwordx4 v132, s[22:23]
	s_mov_b32 m0, s28
	s_nop 0
	global_load_lds_dwordx4 v134, s[22:23]
	s_waitcnt vmcnt(8)
	s_waitcnt lgkmcnt(0)
	s_barrier
; #define PG8_STAGE(bufoff, gbase, voff) do { _Pragma("unroll") for (int _i = 0; _i < 2; ++_i) \
;         __builtin_amdgcn_global_load_lds((const unsigned*)((const char*)(gbase) + (voff)[_i]), (PG8_LAS unsigned*)(lds + (bufoff) + ldsw + _i * 8192), 16, 0, 0); } while (0)
; #define PG8_LDA(dst, b, h) do { _Pragma("unroll") for (int m = 0; m < 4; ++m) _Pragma("unroll") for (int k = 0; k < 2; ++k) dst[m][k] = *(const PG8_LAS bf16x8*)(lds + PG8_SA(b, h) + aoff + m * 2048 + k * 1024); } while (0)
; #define PG8_LDB(dst, b, h) do { _Pragma("unroll") for (int n = 0; n < 2; ++n) _Pragma("unroll") for (int k = 0; k < 2; ++k) dst[n][k] = *(const PG8_LAS bf16x8*)(lds + PG8_SB(b, h) + boff + n * 2048 + k * 1024); } while (0)
; #define PG8_MMA(ai, bj, At, Bt) do { __builtin_amdgcn_s_setprio(1); _Pragma("unroll") for (int m = 0; m < 4; ++m) _Pragma("unroll") for (int n = 0; n < 2; ++n) _Pragma("unroll") for (int k = 0; k < 2; ++k) \
;         acc[ai][bj][m][n] = __builtin_amdgcn_mfma_f32_16x16x32_bf16(Bt[n][k], At[m][k], acc[ai][bj][m][n], 0, 0, 0); __builtin_amdgcn_s_setprio(0); } while (0)
; #define PG8_WAIT_V(n) asm volatile("s_waitcnt vmcnt(" #n ")" ::: "memory")
; #define PG8_WAIT_L(n) asm volatile("s_waitcnt lgkmcnt(" #n ")" ::: "memory")
; #define PG8_BAR __builtin_amdgcn_s_barrier()
; #define PG8_SCHED __builtin_amdgcn_sched_barrier(0)
; template <class Epi, class Sched, bool ALIGN_EPI = false, bool SP2 = false, bool ACHUNK = false>
; __device__ __forceinline__ void gemm_phase(PG8_LAS unsigned char* lds, const Gemm g, const Sched& S, const Epi& E) {
;     ...
;             PG8_WAIT_V(8); PG8_WAIT_L(0); PG8_BAR; PG8_MMA(1, 0, At, B0); PG8_MMA(1, 1, At, B1); PG8_BAR; PG8_SCHED;
;             PG8_LDB(B0, 1, 0); PG8_LDB(B1, 1, 1); PG8_SCHED; PG8_LDA(At, 1, 0); PG8_STAGE(PG8_SA(0, 1), a2 + hstepA, voffA);
;             PG8_WAIT_V(8); PG8_WAIT_L(0); PG8_BAR; PG8_MMA(0, 0, At, B0); PG8_MMA(0, 1, At, B1); PG8_BAR; PG8_SCHED;
;             PG8_LDA(At, 1, 1); PG8_STAGE(PG8_SB(1, 0), b3, voffB); PG8_STAGE(PG8_SB(1, 1), b3 + hstepB, voffB); PG8_STAGE(PG8_SA(1, 0), a3, voffA);
;             PG8_WAIT_V(8); PG8_WAIT_L(0); PG8_BAR; PG8_MMA(1, 0, At, B0); PG8_MMA(1, 1, At, B1); PG8_BAR; PG8_SCHED;
	s_setprio 1
	v_mfma_f32_16x16x32_bf16 v[56:59], v[142:145], v[180:183], v[56:59]
	v_mfma_f32_16x16x32_bf16 v[64:67], v[156:159], v[180:183], v[64:67]
	v_mfma_f32_16x16x32_bf16 v[40:43], v[142:145], v[188:191], v[40:43]
	v_mfma_f32_16x16x32_bf16 v[48:51], v[156:159], v[188:191], v[48:51]
	v_mfma_f32_16x16x32_bf16 v[24:27], v[142:145], v[202:205], v[24:27]
	v_mfma_f32_16x16x32_bf16 v[32:35], v[156:159], v[202:205], v[32:35]
	v_mfma_f32_16x16x32_bf16 v[8:11], v[142:145], v[210:213], v[8:11]
	v_mfma_f32_16x16x32_bf16 v[16:19], v[156:159], v[210:213], v[16:19]
	v_mfma_f32_16x16x32_bf16 v[56:59], v[152:155], v[184:187], v[56:59]
	v_mfma_f32_16x16x32_bf16 v[64:67], v[160:163], v[184:187], v[64:67]
	v_mfma_f32_16x16x32_bf16 v[40:43], v[152:155], v[198:201], v[40:43]
	v_mfma_f32_16x16x32_bf16 v[48:51], v[160:163], v[198:201], v[48:51]
	v_mfma_f32_16x16x32_bf16 v[24:27], v[152:155], v[206:209], v[24:27]
	v_mfma_f32_16x16x32_bf16 v[32:35], v[160:163], v[206:209], v[32:35]
	v_mfma_f32_16x16x32_bf16 v[8:11], v[152:155], v[214:217], v[8:11]
	v_mfma_f32_16x16x32_bf16 v[16:19], v[160:163], v[214:217], v[16:19]
	s_setprio 0
	s_setprio 1
	v_mfma_f32_16x16x32_bf16 v[52:55], v[164:167], v[180:183], v[52:55]
	v_mfma_f32_16x16x32_bf16 v[60:63], v[172:175], v[180:183], v[60:63]
	v_mfma_f32_16x16x32_bf16 v[36:39], v[164:167], v[188:191], v[36:39]
	v_mfma_f32_16x16x32_bf16 v[44:47], v[172:175], v[188:191], v[44:47]
	v_mfma_f32_16x16x32_bf16 v[20:23], v[164:167], v[202:205], v[20:23]
	v_mfma_f32_16x16x32_bf16 v[28:31], v[172:175], v[202:205], v[28:31]
	v_mfma_f32_16x16x32_bf16 v[4:7], v[164:167], v[210:213], v[4:7]
	v_mfma_f32_16x16x32_bf16 v[12:15], v[172:175], v[210:213], v[12:15]
	v_mfma_f32_16x16x32_bf16 v[52:55], v[168:171], v[184:187], v[52:55]
	v_mfma_f32_16x16x32_bf16 v[60:63], v[176:179], v[184:187], v[60:63]
	v_mfma_f32_16x16x32_bf16 v[36:39], v[168:171], v[198:201], v[36:39]
	v_mfma_f32_16x16x32_bf16 v[44:47], v[176:179], v[198:201], v[44:47]
	v_mfma_f32_16x16x32_bf16 v[20:23], v[168:171], v[206:209], v[20:23]
	v_mfma_f32_16x16x32_bf16 v[28:31], v[176:179], v[206:209], v[28:31]
	v_mfma_f32_16x16x32_bf16 v[4:7], v[168:171], v[214:217], v[4:7]
	v_mfma_f32_16x16x32_bf16 v[12:15], v[176:179], v[214:217], v[12:15]
	s_setprio 0
	s_barrier
	s_add_i32 s51, 0, 0x18000
	s_add_i32 s52, 0, 0x1c000
	ds_read_b128 v[142:145], v192 offset:32768
	ds_read_b128 v[152:155], v192 offset:33792
	ds_read_b128 v[156:159], v192 offset:34816
	ds_read_b128 v[160:163], v192 offset:35840
	ds_read_b128 v[164:167], v192 offset:49152
	ds_read_b128 v[168:171], v192 offset:50176
	ds_read_b128 v[172:175], v192 offset:51200
	ds_read_b128 v[176:179], v192 offset:52224
	s_add_u32 s22, s22, s4
	s_addc_u32 s23, s23, s5
	s_mov_b32 m0, s29
	ds_read_b128 v[180:183], v149 offset:32768
	ds_read_b128 v[184:187], v149 offset:33792
	ds_read_b128 v[188:191], v149 offset:34816
	ds_read_b128 v[198:201], v149 offset:35840
	ds_read_b128 v[202:205], v149 offset:36864
	ds_read_b128 v[206:209], v149 offset:37888
	ds_read_b128 v[210:213], v149 offset:38912
	ds_read_b128 v[214:217], v149 offset:39936
	global_load_lds_dwordx4 v132, s[22:23]
	s_mov_b32 m0, s30
	s_nop 0
	global_load_lds_dwordx4 v134, s[22:23]
	s_waitcnt vmcnt(8)
	s_waitcnt lgkmcnt(0)
	s_barrier
	s_setprio 1
	v_mfma_f32_16x16x32_bf16 v[120:123], v[142:145], v[180:183], v[120:123]
	v_mfma_f32_16x16x32_bf16 v[128:131], v[156:159], v[180:183], v[128:131]
	v_mfma_f32_16x16x32_bf16 v[104:107], v[142:145], v[188:191], v[104:107]
	v_mfma_f32_16x16x32_bf16 v[112:115], v[156:159], v[188:191], v[112:115]
	v_mfma_f32_16x16x32_bf16 v[88:91], v[142:145], v[202:205], v[88:91]
	v_mfma_f32_16x16x32_bf16 v[96:99], v[156:159], v[202:205], v[96:99]
	v_mfma_f32_16x16x32_bf16 v[72:75], v[142:145], v[210:213], v[72:75]
	v_mfma_f32_16x16x32_bf16 v[80:83], v[156:159], v[210:213], v[80:83]
	v_mfma_f32_16x16x32_bf16 v[120:123], v[152:155], v[184:187], v[120:123]
	v_mfma_f32_16x16x32_bf16 v[128:131], v[160:163], v[184:187], v[128:131]
	v_mfma_f32_16x16x32_bf16 v[104:107], v[152:155], v[198:201], v[104:107]
	v_mfma_f32_16x16x32_bf16 v[112:115], v[160:163], v[198:201], v[112:115]
	v_mfma_f32_16x16x32_bf16 v[88:91], v[152:155], v[206:209], v[88:91]
	v_mfma_f32_16x16x32_bf16 v[96:99], v[160:163], v[206:209], v[96:99]
	v_mfma_f32_16x16x32_bf16 v[72:75], v[152:155], v[214:217], v[72:75]
	v_mfma_f32_16x16x32_bf16 v[80:83], v[160:163], v[214:217], v[80:83]
	s_setprio 0
	s_setprio 1
	v_mfma_f32_16x16x32_bf16 v[116:119], v[164:167], v[180:183], v[116:119]
	v_mfma_f32_16x16x32_bf16 v[124:127], v[172:175], v[180:183], v[124:127]
	v_mfma_f32_16x16x32_bf16 v[100:103], v[164:167], v[188:191], v[100:103]
	v_mfma_f32_16x16x32_bf16 v[108:111], v[172:175], v[188:191], v[108:111]
	v_mfma_f32_16x16x32_bf16 v[84:87], v[164:167], v[202:205], v[84:87]
	v_mfma_f32_16x16x32_bf16 v[92:95], v[172:175], v[202:205], v[92:95]
	v_mfma_f32_16x16x32_bf16 v[68:71], v[164:167], v[210:213], v[68:71]
	v_mfma_f32_16x16x32_bf16 v[76:79], v[172:175], v[210:213], v[76:79]
	v_mfma_f32_16x16x32_bf16 v[116:119], v[168:171], v[184:187], v[116:119]
	v_mfma_f32_16x16x32_bf16 v[124:127], v[176:179], v[184:187], v[124:127]
	v_mfma_f32_16x16x32_bf16 v[100:103], v[168:171], v[198:201], v[100:103]
	v_mfma_f32_16x16x32_bf16 v[108:111], v[176:179], v[198:201], v[108:111]
	v_mfma_f32_16x16x32_bf16 v[84:87], v[168:171], v[206:209], v[84:87]
	v_mfma_f32_16x16x32_bf16 v[92:95], v[176:179], v[206:209], v[92:95]
	v_mfma_f32_16x16x32_bf16 v[68:71], v[168:171], v[214:217], v[68:71]
	v_mfma_f32_16x16x32_bf16 v[76:79], v[176:179], v[214:217], v[76:79]
	s_setprio 0
	s_barrier
; #define PG8_STAGE(bufoff, gbase, voff) do { _Pragma("unroll") for (int _i = 0; _i < 2; ++_i) \
;         __builtin_amdgcn_global_load_lds((const unsigned*)((const char*)(gbase) + (voff)[_i]), (PG8_LAS unsigned*)(lds + (bufoff) + ldsw + _i * 8192), 16, 0, 0); } while (0)
; #define PG8_LDA(dst, b, h) do { _Pragma("unroll") for (int m = 0; m < 4; ++m) _Pragma("unroll") for (int k = 0; k < 2; ++k) dst[m][k] = *(const PG8_LAS bf16x8*)(lds + PG8_SA(b, h) + aoff + m * 2048 + k * 1024); } while (0)
; #define PG8_MMA(ai, bj, At, Bt) do { __builtin_amdgcn_s_setprio(1); _Pragma("unroll") for (int m = 0; m < 4; ++m) _Pragma("unroll") for (int n = 0; n < 2; ++n) _Pragma("unroll") for (int k = 0; k < 2; ++k) \
;         acc[ai][bj][m][n] = __builtin_amdgcn_mfma_f32_16x16x32_bf16(Bt[n][k], At[m][k], acc[ai][bj][m][n], 0, 0, 0); __builtin_amdgcn_s_setprio(0); } while (0)
; #define PG8_WAIT_V(n) asm volatile("s_waitcnt vmcnt(" #n ")" ::: "memory")
; #define PG8_WAIT_L(n) asm volatile("s_waitcnt lgkmcnt(" #n ")" ::: "memory")
; #define PG8_BAR __builtin_amdgcn_s_barrier()
; #define PG8_SCHED __builtin_amdgcn_sched_barrier(0)
; template <class Epi, class Sched, bool ALIGN_EPI = false, bool SP2 = false, bool ACHUNK = false>
; __device__ __forceinline__ void gemm_phase(PG8_LAS unsigned char* lds, const Gemm g, const Sched& S, const Epi& E) {
;     ...
;         for (int t = 0; t < nt; t += 2) {
;     ...
;             PG8_LDA(At, 1, 1); PG8_STAGE(PG8_SB(1, 0), b3, voffB); PG8_STAGE(PG8_SB(1, 1), b3 + hstepB, voffB); PG8_STAGE(PG8_SA(1, 0), a3, voffA);
;             PG8_WAIT_V(8); PG8_WAIT_L(0); PG8_BAR; PG8_MMA(1, 0, At, B0); PG8_MMA(1, 1, At, B1); PG8_BAR; PG8_SCHED;
	s_add_u32 vcc_lo, vcc_lo, s10
	s_addc_u32 vcc_hi, vcc_hi, s11
	s_add_u32 s98, s98, s10
	s_addc_u32 s99, s99, s11
	s_sub_u32 s22, s22, s4
	s_subb_u32 s23, s23, s5
	s_add_u32 s22, s22, s10
	s_addc_u32 s23, s23, s11
	s_add_i32 m0, s51, s26
	ds_read_b128 v[180:183], v149 offset:49152
	ds_read_b128 v[184:187], v149 offset:50176
	ds_read_b128 v[188:191], v149 offset:51200
	ds_read_b128 v[198:201], v149 offset:52224
	ds_read_b128 v[202:205], v149 offset:53248
	ds_read_b128 v[206:209], v149 offset:54272
	ds_read_b128 v[210:213], v149 offset:55296
	ds_read_b128 v[214:217], v149 offset:56320
	global_load_lds_dwordx4 v2, s[98:99]
	s_add_i32 m0, m0, 0x2000
	s_nop 0
	global_load_lds_dwordx4 v136, s[98:99]
	s_add_i32 m0, s52, s26
	s_nop 0
	global_load_lds_dwordx4 v2, vcc
	s_add_i32 m0, m0, 0x2000
	s_nop 0
	global_load_lds_dwordx4 v136, vcc
	s_mov_b32 m0, s31
	s_nop 0
	global_load_lds_dwordx4 v132, s[22:23]
	s_mov_b32 m0, s33
	s_nop 0
	global_load_lds_dwordx4 v134, s[22:23]
	s_waitcnt vmcnt(8)
	s_waitcnt lgkmcnt(0)
	s_barrier
	s_setprio 1
	v_mfma_f32_16x16x32_bf16 v[56:59], v[142:145], v[180:183], v[56:59]
	v_mfma_f32_16x16x32_bf16 v[64:67], v[156:159], v[180:183], v[64:67]
	v_mfma_f32_16x16x32_bf16 v[40:43], v[142:145], v[188:191], v[40:43]
	v_mfma_f32_16x16x32_bf16 v[48:51], v[156:159], v[188:191], v[48:51]
	v_mfma_f32_16x16x32_bf16 v[24:27], v[142:145], v[202:205], v[24:27]
	v_mfma_f32_16x16x32_bf16 v[32:35], v[156:159], v[202:205], v[32:35]
	v_mfma_f32_16x16x32_bf16 v[8:11], v[142:145], v[210:213], v[8:11]
	v_mfma_f32_16x16x32_bf16 v[16:19], v[156:159], v[210:213], v[16:19]
	v_mfma_f32_16x16x32_bf16 v[56:59], v[152:155], v[184:187], v[56:59]
	v_mfma_f32_16x16x32_bf16 v[64:67], v[160:163], v[184:187], v[64:67]
	v_mfma_f32_16x16x32_bf16 v[40:43], v[152:155], v[198:201], v[40:43]
	v_mfma_f32_16x16x32_bf16 v[48:51], v[160:163], v[198:201], v[48:51]
	v_mfma_f32_16x16x32_bf16 v[24:27], v[152:155], v[206:209], v[24:27]
	v_mfma_f32_16x16x32_bf16 v[32:35], v[160:163], v[206:209], v[32:35]
	v_mfma_f32_16x16x32_bf16 v[8:11], v[152:155], v[214:217], v[8:11]
	v_mfma_f32_16x16x32_bf16 v[16:19], v[160:163], v[214:217], v[16:19]
	s_setprio 0
	s_setprio 1
	v_mfma_f32_16x16x32_bf16 v[52:55], v[164:167], v[180:183], v[52:55]
	v_mfma_f32_16x16x32_bf16 v[60:63], v[172:175], v[180:183], v[60:63]
	v_mfma_f32_16x16x32_bf16 v[36:39], v[164:167], v[188:191], v[36:39]
	v_mfma_f32_16x16x32_bf16 v[44:47], v[172:175], v[188:191], v[44:47]
	v_mfma_f32_16x16x32_bf16 v[20:23], v[164:167], v[202:205], v[20:23]
	v_mfma_f32_16x16x32_bf16 v[28:31], v[172:175], v[202:205], v[28:31]
	v_mfma_f32_16x16x32_bf16 v[4:7], v[164:167], v[210:213], v[4:7]
	v_mfma_f32_16x16x32_bf16 v[12:15], v[172:175], v[210:213], v[12:15]
	v_mfma_f32_16x16x32_bf16 v[52:55], v[168:171], v[184:187], v[52:55]
	v_mfma_f32_16x16x32_bf16 v[60:63], v[176:179], v[184:187], v[60:63]
	v_mfma_f32_16x16x32_bf16 v[36:39], v[168:171], v[198:201], v[36:39]
	v_mfma_f32_16x16x32_bf16 v[44:47], v[176:179], v[198:201], v[44:47]
	v_mfma_f32_16x16x32_bf16 v[20:23], v[168:171], v[206:209], v[20:23]
	v_mfma_f32_16x16x32_bf16 v[28:31], v[176:179], v[206:209], v[28:31]
	v_mfma_f32_16x16x32_bf16 v[4:7], v[168:171], v[214:217], v[4:7]
	v_mfma_f32_16x16x32_bf16 v[12:15], v[176:179], v[214:217], v[12:15]
	s_setprio 0
	s_barrier
	s_add_u32 s48, s48, 0x100
	s_addc_u32 s49, s49, 0
	s_add_u32 s20, s20, 0x100
	s_addc_u32 s21, s21, 0
	s_cmp_ge_i32 s50, s34
	s_mov_b32 s22, s50
	s_cbranch_scc0 .LBB0_216
	v_readlane_b32 s54, v254, 25
	v_readlane_b32 s52, v254, 27
	v_readlane_b32 s55, v254, 26
	v_readlane_b32 s53, v254, 28
	s_mov_b32 s50, s94
	s_and_b64 vcc, exec, s[16:17]
	s_cbranch_vccnz .LBB0_221
	s_branch .LBB0_222

; template <class Epi, class Sched, bool ALIGN_EPI = false, bool SP2 = false, bool ACHUNK = false>
; __device__ __forceinline__ void gemm_phase(PG8_LAS unsigned char* lds, const Gemm g, const Sched& S, const Epi& E) {
;     ...
;     f32x4 acc[2][2][4][2];
;     if constexpr (Epi::HAS_INIT) { static_assert(SP2, "the accumulator-initialising fill below is written for the SP2 schedule"); }
;     else {
; #pragma unroll
;     for (int a = 0; a < 2; ++a)
; #pragma unroll
;         for (int b = 0; b < 2; ++b)
; #pragma unroll
;             for (int m = 0; m < 4; ++m)
; #pragma unroll
;                 for (int n = 0; n < 2; ++n) acc[a][b][m][n] = (f32x4){0.f, 0.f, 0.f, 0.f};
;     ...
;         const bool has_next = S.next(ui + 1, nxt);
;         const char* nA = has_next ? (const char*)g.A + (size_t)nxt.pm * tstepA : cA; const char* nB = has_next ? (const char*)g.Bt + (size_t)nxt.pn * tstepB : cB;
;         for (int t = 0; t < nt; t += 2) {
;             const bool last = (t == nt - 2);
;             if constexpr (Epi::HAS_MID) { if (t == Epi::MID_T) E.mid(acc, cur, wr, wc, fr, fq, ShflDev{}); }
;             const char* a1 = cA + (size_t)(t + 1) * kstep;
;             const char* a2 = last ? nA : cA + (size_t)(t + 2) * kstep; const char* b2 = last ? nB : cB + (size_t)(t + 2) * kstep;
;             const char* a3 = a2 + kstep; const char* b3 = b2 + kstep;
;             if (last && has_next) S.a_ready(nxt);
.LBB0_264:
	s_nop 0
	v_mov_b32_e32 v129, 0
	s_andn2_b64 vcc, exec, s[30:31]
	v_mov_b32_e32 v128, 0
	v_mov_b32_e32 v127, 0
	v_mov_b32_e32 v126, 0
	v_mov_b32_e32 v133, 0
	v_mov_b32_e32 v132, 0
	v_mov_b32_e32 v131, 0
	v_mov_b32_e32 v130, 0
	v_mov_b32_e32 v117, 0
	v_mov_b32_e32 v116, 0
	v_mov_b32_e32 v115, 0
	v_mov_b32_e32 v114, 0
	v_mov_b32_e32 v113, 0
	v_mov_b32_e32 v112, 0
	v_mov_b32_e32 v111, 0
	v_mov_b32_e32 v110, 0
	v_mov_b32_e32 v101, 0
	v_mov_b32_e32 v100, 0
	v_mov_b32_e32 v99, 0
	v_mov_b32_e32 v98, 0
	v_mov_b32_e32 v97, 0
	v_mov_b32_e32 v96, 0
	v_mov_b32_e32 v95, 0
	v_mov_b32_e32 v94, 0
	v_mov_b32_e32 v85, 0
	v_mov_b32_e32 v84, 0
	v_mov_b32_e32 v83, 0
	v_mov_b32_e32 v82, 0
	v_mov_b32_e32 v81, 0
	v_mov_b32_e32 v80, 0
	v_mov_b32_e32 v79, 0
	v_mov_b32_e32 v78, 0
	v_mov_b32_e32 v125, 0
	v_mov_b32_e32 v124, 0
	v_mov_b32_e32 v123, 0
	v_mov_b32_e32 v122, 0
	v_mov_b32_e32 v121, 0
	v_mov_b32_e32 v120, 0
	v_mov_b32_e32 v119, 0
	v_mov_b32_e32 v118, 0
	v_mov_b32_e32 v109, 0
	v_mov_b32_e32 v108, 0
	v_mov_b32_e32 v107, 0
	v_mov_b32_e32 v106, 0
	v_mov_b32_e32 v105, 0
	v_mov_b32_e32 v104, 0
	v_mov_b32_e32 v103, 0
	v_mov_b32_e32 v102, 0
	v_mov_b32_e32 v93, 0
	v_mov_b32_e32 v92, 0
	v_mov_b32_e32 v91, 0
	v_mov_b32_e32 v90, 0
	v_mov_b32_e32 v89, 0
	v_mov_b32_e32 v88, 0
	v_mov_b32_e32 v87, 0
	v_mov_b32_e32 v86, 0
	v_mov_b32_e32 v77, 0
	v_mov_b32_e32 v76, 0
	v_mov_b32_e32 v75, 0
	v_mov_b32_e32 v74, 0
	v_mov_b32_e32 v73, 0
	v_mov_b32_e32 v72, 0
	v_mov_b32_e32 v71, 0
	v_mov_b32_e32 v70, 0
	v_mov_b32_e32 v69, 0
	v_mov_b32_e32 v68, 0
	v_mov_b32_e32 v67, 0
	v_mov_b32_e32 v66, 0
	v_mov_b32_e32 v65, 0
	v_mov_b32_e32 v64, 0
	v_mov_b32_e32 v63, 0
	v_mov_b32_e32 v62, 0
	v_mov_b32_e32 v53, 0
	v_mov_b32_e32 v52, 0
	v_mov_b32_e32 v51, 0
	v_mov_b32_e32 v50, 0
	v_mov_b32_e32 v49, 0
	v_mov_b32_e32 v48, 0
	v_mov_b32_e32 v47, 0
	v_mov_b32_e32 v46, 0
	v_mov_b32_e32 v37, 0
	v_mov_b32_e32 v36, 0
	v_mov_b32_e32 v35, 0
	v_mov_b32_e32 v34, 0
	v_mov_b32_e32 v33, 0
	v_mov_b32_e32 v32, 0
	v_mov_b32_e32 v31, 0
	v_mov_b32_e32 v30, 0
	v_mov_b32_e32 v21, 0
	v_mov_b32_e32 v20, 0
	v_mov_b32_e32 v19, 0
	v_mov_b32_e32 v18, 0
	v_mov_b32_e32 v17, 0
	v_mov_b32_e32 v16, 0
	v_mov_b32_e32 v15, 0
	v_mov_b32_e32 v14, 0
	v_mov_b32_e32 v61, 0
	v_mov_b32_e32 v60, 0
	v_mov_b32_e32 v59, 0
	v_mov_b32_e32 v58, 0
	v_mov_b32_e32 v57, 0
	v_mov_b32_e32 v56, 0
	v_mov_b32_e32 v55, 0
	v_mov_b32_e32 v54, 0
	v_mov_b32_e32 v45, 0
	v_mov_b32_e32 v44, 0
	v_mov_b32_e32 v43, 0
	v_mov_b32_e32 v42, 0
	v_mov_b32_e32 v41, 0
	v_mov_b32_e32 v40, 0
	v_mov_b32_e32 v39, 0
	v_mov_b32_e32 v38, 0
	v_mov_b32_e32 v29, 0
	v_mov_b32_e32 v28, 0
	v_mov_b32_e32 v27, 0
	v_mov_b32_e32 v26, 0
	v_mov_b32_e32 v25, 0
	v_mov_b32_e32 v24, 0
	v_mov_b32_e32 v23, 0
	v_mov_b32_e32 v22, 0
	v_mov_b32_e32 v13, 0
	v_mov_b32_e32 v12, 0
	v_mov_b32_e32 v11, 0
	v_mov_b32_e32 v10, 0
	v_mov_b32_e32 v9, 0
	v_mov_b32_e32 v8, 0
	v_mov_b32_e32 v7, 0
	v_mov_b32_e32 v6, 0
	s_cbranch_vccnz .LBB0_270
	s_lshl_b32 s8, s46, 8
	s_lshl_b32 s48, s45, 8
	s_or_b32 s47, s8, s25
	s_add_i32 s48, s48, s24
	s_add_u32 s49, s6, 0x100
	s_addc_u32 s50, s7, 0
	s_add_u32 s6, s4, 0x80
	v_mov_b32_e32 v4, v3
	v_mov_b32_e32 v5, v3
	s_addc_u32 s7, s5, 0
	v_mov_b32_e32 v2, v3
	v_mov_b64_e32 v[8:9], v[4:5]
	v_mov_b64_e32 v[12:13], v[4:5]
	v_mov_b64_e32 v[24:25], v[4:5]
	v_mov_b64_e32 v[28:29], v[4:5]
	v_mov_b64_e32 v[40:41], v[4:5]
	v_mov_b64_e32 v[44:45], v[4:5]
	v_mov_b64_e32 v[56:57], v[4:5]
	v_mov_b64_e32 v[60:61], v[4:5]
	v_mov_b64_e32 v[16:17], v[4:5]
	v_mov_b64_e32 v[20:21], v[4:5]
	v_mov_b64_e32 v[32:33], v[4:5]
	v_mov_b64_e32 v[36:37], v[4:5]
	v_mov_b64_e32 v[48:49], v[4:5]
	v_mov_b64_e32 v[52:53], v[4:5]
	v_mov_b64_e32 v[64:65], v[4:5]
	v_mov_b64_e32 v[68:69], v[4:5]
	v_mov_b64_e32 v[72:73], v[4:5]
	v_mov_b64_e32 v[76:77], v[4:5]
	v_mov_b64_e32 v[88:89], v[4:5]
	v_mov_b64_e32 v[92:93], v[4:5]
	v_mov_b64_e32 v[104:105], v[4:5]
	v_mov_b64_e32 v[108:109], v[4:5]
	v_mov_b64_e32 v[120:121], v[4:5]
	v_mov_b64_e32 v[124:125], v[4:5]
	v_mov_b64_e32 v[80:81], v[4:5]
	v_mov_b64_e32 v[84:85], v[4:5]
	v_mov_b64_e32 v[96:97], v[4:5]
	v_mov_b64_e32 v[100:101], v[4:5]
	v_mov_b64_e32 v[112:113], v[4:5]
	v_mov_b64_e32 v[116:117], v[4:5]
	v_mov_b64_e32 v[132:133], v[4:5]
	v_mov_b64_e32 v[128:129], v[4:5]
	v_lshl_add_u64 v[210:211], s[6:7], 0, v[206:207]
	v_lshl_add_u64 v[212:213], s[6:7], 0, v[208:209]
	s_mov_b32 s8, 0
	s_mov_b64 s[6:7], 0
	v_mov_b64_e32 v[6:7], v[2:3]
	v_mov_b64_e32 v[10:11], v[2:3]
	v_mov_b64_e32 v[22:23], v[2:3]
	v_mov_b64_e32 v[26:27], v[2:3]
	v_mov_b64_e32 v[38:39], v[2:3]
	v_mov_b64_e32 v[42:43], v[2:3]
	v_mov_b64_e32 v[54:55], v[2:3]
	v_mov_b64_e32 v[58:59], v[2:3]
	v_mov_b64_e32 v[14:15], v[2:3]
	v_mov_b64_e32 v[18:19], v[2:3]
	v_mov_b64_e32 v[30:31], v[2:3]
	v_mov_b64_e32 v[34:35], v[2:3]
	v_mov_b64_e32 v[46:47], v[2:3]
	v_mov_b64_e32 v[50:51], v[2:3]
	v_mov_b64_e32 v[62:63], v[2:3]
	v_mov_b64_e32 v[66:67], v[2:3]
	v_mov_b64_e32 v[70:71], v[2:3]
	v_mov_b64_e32 v[74:75], v[2:3]
	v_mov_b64_e32 v[86:87], v[2:3]
	v_mov_b64_e32 v[90:91], v[2:3]
	v_mov_b64_e32 v[102:103], v[2:3]
	v_mov_b64_e32 v[106:107], v[2:3]
	v_mov_b64_e32 v[118:119], v[2:3]
	v_mov_b64_e32 v[122:123], v[2:3]
	v_mov_b64_e32 v[78:79], v[2:3]
	v_mov_b64_e32 v[82:83], v[2:3]
	v_mov_b64_e32 v[94:95], v[2:3]
	v_mov_b64_e32 v[98:99], v[2:3]
	v_mov_b64_e32 v[110:111], v[2:3]
	v_mov_b64_e32 v[114:115], v[2:3]
	v_mov_b64_e32 v[130:131], v[2:3]
	v_mov_b64_e32 v[126:127], v[2:3]
	v_add_u32_e32 v218, 0x10000, v235
	s_cmp_lg_u32 s8, 8
	s_cbranch_scc1 .LBB0_268
	s_branch .LBB0_267

; #define PG8_STAGE(bufoff, gbase, voff) do { _Pragma("unroll") for (int _i = 0; _i < 2; ++_i) \
;         __builtin_amdgcn_global_load_lds((const unsigned*)((const char*)(gbase) + (voff)[_i]), (PG8_LAS unsigned*)(lds + (bufoff) + ldsw + _i * 8192), 16, 0, 0); } while (0)
; #define PG8_LDA(dst, b, h) do { _Pragma("unroll") for (int m = 0; m < 4; ++m) _Pragma("unroll") for (int k = 0; k < 2; ++k) dst[m][k] = *(const PG8_LAS bf16x8*)(lds + PG8_SA(b, h) + aoff + m * 2048 + k * 1024); } while (0)
; #define PG8_LDB(dst, b, h) do { _Pragma("unroll") for (int n = 0; n < 2; ++n) _Pragma("unroll") for (int k = 0; k < 2; ++k) dst[n][k] = *(const PG8_LAS bf16x8*)(lds + PG8_SB(b, h) + boff + n * 2048 + k * 1024); } while (0)
; #define PG8_MMA(ai, bj, At, Bt) do { __builtin_amdgcn_s_setprio(1); _Pragma("unroll") for (int m = 0; m < 4; ++m) _Pragma("unroll") for (int n = 0; n < 2; ++n) _Pragma("unroll") for (int k = 0; k < 2; ++k) \
;         acc[ai][bj][m][n] = __builtin_amdgcn_mfma_f32_16x16x32_bf16(Bt[n][k], At[m][k], acc[ai][bj][m][n], 0, 0, 0); __builtin_amdgcn_s_setprio(0); } while (0)
; #define PG8_WAIT_V(n) asm volatile("s_waitcnt vmcnt(" #n ")" ::: "memory")
; #define PG8_WAIT_L(n) asm volatile("s_waitcnt lgkmcnt(" #n ")" ::: "memory")
; #define PG8_BAR __builtin_amdgcn_s_barrier()
; #define PG8_SCHED __builtin_amdgcn_sched_barrier(0)
; template <class Epi, class Sched, bool ALIGN_EPI = false, bool SP2 = false, bool ACHUNK = false>
; __device__ __forceinline__ void gemm_phase(PG8_LAS unsigned char* lds, const Gemm g, const Sched& S, const Epi& E) {
;     ...
;             PG8_LDB(B0, 0, 0); PG8_LDB(B1, 0, 1); PG8_SCHED; PG8_LDA(At, 0, 0); PG8_STAGE(PG8_SA(1, 1), a1 + hstepA, voffA);
;             PG8_WAIT_V(8); PG8_WAIT_L(0); PG8_BAR; PG8_MMA(0, 0, At, B0); PG8_MMA(0, 1, At, B1); PG8_BAR; PG8_SCHED;
;             PG8_LDA(At, 0, 1); PG8_STAGE(PG8_SB(0, 0), b2, voffB); PG8_STAGE(PG8_SB(0, 1), b2 + hstepB, voffB); PG8_STAGE(PG8_SA(0, 0), a2, voffA);
;             PG8_WAIT_V(8); PG8_WAIT_L(0); PG8_BAR; PG8_MMA(1, 0, At, B0); PG8_MMA(1, 1, At, B1); PG8_BAR; PG8_SCHED;
.LBB0_268:
	s_add_i32 s51, s8, 2
	s_add_u32 s9, s4, s6
	s_addc_u32 s52, s5, s7
	s_add_u32 s53, s9, 0x100
	s_addc_u32 s9, s52, 0
	s_add_u32 s52, s49, s6
	s_addc_u32 s54, s50, s7
	s_add_i32 s55, 0, 0x10000
	s_cmp_eq_u32 s33, s8
	s_cselect_b32 s9, s1, s9
	s_cselect_b32 s8, s0, s53
	s_cselect_b32 s53, s41, s54
	s_cselect_b32 s52, s40, s52
	s_cbranch_scc0 .Lnl_mg
	s_cmpk_lg_u32 s87, 0x100
	s_cbranch_scc1 .Lnl_mg
	v_mov_b32_e32 v200, 0
	v_mov_b32_e32 v204, 0
	v_mov_b32_e32 v198, 0
	v_mov_b32_e32 v202, 0
.Lnl_mg:
	s_add_i32 s54, 0, 0x14000
	ds_read_b128 v[134:137], v218
	ds_read_b128 v[138:141], v218 offset:1024
	ds_read_b128 v[142:145], v218 offset:2048
	ds_read_b128 v[146:149], v218 offset:3072
	ds_read_b128 v[150:153], v218 offset:16384
	ds_read_b128 v[154:157], v218 offset:17408
	ds_read_b128 v[158:161], v218 offset:18432
	ds_read_b128 v[162:165], v218 offset:19456
	v_lshl_add_u64 v[4:5], v[210:211], 0, s[6:7]
	s_add_i32 m0, s17, 0xc000
	ds_read_b128 v[166:169], v237
	ds_read_b128 v[170:173], v237 offset:1024
	ds_read_b128 v[174:177], v237 offset:2048
	ds_read_b128 v[178:181], v237 offset:3072
	ds_read_b128 v[182:185], v237 offset:4096
	ds_read_b128 v[186:189], v237 offset:5120
	ds_read_b128 v[190:193], v237 offset:6144
	ds_read_b128 v[214:217], v237 offset:7168
	global_load_lds_dwordx4 v[4:5], off
	v_lshl_add_u64 v[4:5], v[212:213], 0, s[6:7]
	s_add_i32 m0, s17, 0xe000
	s_nop 0
	global_load_lds_dwordx4 v[4:5], off
	s_waitcnt vmcnt(8)
	s_waitcnt lgkmcnt(0)
	s_barrier
	s_setprio 1
	v_mfma_f32_16x16x32_bf16 v[126:129], v[134:137], v[166:169], v[126:129]
	v_mfma_f32_16x16x32_bf16 v[130:133], v[142:145], v[166:169], v[130:133]
	v_mfma_f32_16x16x32_bf16 v[114:117], v[134:137], v[174:177], v[114:117]
	v_mfma_f32_16x16x32_bf16 v[110:113], v[142:145], v[174:177], v[110:113]
	v_mfma_f32_16x16x32_bf16 v[98:101], v[134:137], v[182:185], v[98:101]
	v_mfma_f32_16x16x32_bf16 v[94:97], v[142:145], v[182:185], v[94:97]
	v_mfma_f32_16x16x32_bf16 v[82:85], v[134:137], v[190:193], v[82:85]
	v_mfma_f32_16x16x32_bf16 v[78:81], v[142:145], v[190:193], v[78:81]
	v_mfma_f32_16x16x32_bf16 v[126:129], v[138:141], v[170:173], v[126:129]
	v_mfma_f32_16x16x32_bf16 v[130:133], v[146:149], v[170:173], v[130:133]
	v_mfma_f32_16x16x32_bf16 v[114:117], v[138:141], v[178:181], v[114:117]
	v_mfma_f32_16x16x32_bf16 v[110:113], v[146:149], v[178:181], v[110:113]
	v_mfma_f32_16x16x32_bf16 v[98:101], v[138:141], v[186:189], v[98:101]
	v_mfma_f32_16x16x32_bf16 v[94:97], v[146:149], v[186:189], v[94:97]
	v_mfma_f32_16x16x32_bf16 v[82:85], v[138:141], v[214:217], v[82:85]
	v_mfma_f32_16x16x32_bf16 v[78:81], v[146:149], v[214:217], v[78:81]
	s_setprio 0
	s_setprio 1
	v_mfma_f32_16x16x32_bf16 v[122:125], v[150:153], v[166:169], v[122:125]
	v_mfma_f32_16x16x32_bf16 v[118:121], v[158:161], v[166:169], v[118:121]
	v_mfma_f32_16x16x32_bf16 v[106:109], v[150:153], v[174:177], v[106:109]
	v_mfma_f32_16x16x32_bf16 v[102:105], v[158:161], v[174:177], v[102:105]
	v_mfma_f32_16x16x32_bf16 v[90:93], v[150:153], v[182:185], v[90:93]
	v_mfma_f32_16x16x32_bf16 v[86:89], v[158:161], v[182:185], v[86:89]
	v_mfma_f32_16x16x32_bf16 v[74:77], v[150:153], v[190:193], v[74:77]
	v_mfma_f32_16x16x32_bf16 v[70:73], v[158:161], v[190:193], v[70:73]
	v_mfma_f32_16x16x32_bf16 v[122:125], v[154:157], v[170:173], v[122:125]
	v_mfma_f32_16x16x32_bf16 v[118:121], v[162:165], v[170:173], v[118:121]
	v_mfma_f32_16x16x32_bf16 v[106:109], v[154:157], v[178:181], v[106:109]
	v_mfma_f32_16x16x32_bf16 v[102:105], v[162:165], v[178:181], v[102:105]
	v_mfma_f32_16x16x32_bf16 v[90:93], v[154:157], v[186:189], v[90:93]
	v_mfma_f32_16x16x32_bf16 v[86:89], v[162:165], v[186:189], v[86:89]
	v_mfma_f32_16x16x32_bf16 v[74:77], v[154:157], v[214:217], v[74:77]
	v_mfma_f32_16x16x32_bf16 v[70:73], v[162:165], v[214:217], v[70:73]
	s_setprio 0
	s_barrier
	s_add_i32 s55, s55, s16
	s_mov_b32 m0, s55
	ds_read_b128 v[166:169], v237 offset:16384
	ds_read_b128 v[170:173], v237 offset:17408
	ds_read_b128 v[174:177], v237 offset:18432
	ds_read_b128 v[178:181], v237 offset:19456
	ds_read_b128 v[182:185], v237 offset:20480
	ds_read_b128 v[186:189], v237 offset:21504
	ds_read_b128 v[190:193], v237 offset:22528
	ds_read_b128 v[214:217], v237 offset:23552
	global_load_lds_dwordx4 v200, s[52:53]
	s_add_i32 m0, s55, 0x2000
	s_add_i32 s54, s54, s16
	global_load_lds_dwordx4 v204, s[52:53]
	s_add_u32 s52, s52, s2
	s_addc_u32 s53, s53, s3
	s_mov_b64 vcc, s[52:53]
	s_sub_u32 s98, s52, s2
	s_subb_u32 s99, s53, s3
	s_mov_b32 m0, s54
	s_nop 0
	global_load_lds_dwordx4 v200, s[52:53]
	s_add_i32 m0, s54, 0x2000
	s_nop 0
	global_load_lds_dwordx4 v204, s[52:53]
	s_mov_b32 m0, s17
	s_nop 0
	global_load_lds_dwordx4 v198, s[8:9]
	s_mov_b32 m0, s20
	s_nop 0
	global_load_lds_dwordx4 v202, s[8:9]
	s_waitcnt vmcnt(8)
	s_waitcnt lgkmcnt(0)
	s_barrier
; #define PG8_STAGE(bufoff, gbase, voff) do { _Pragma("unroll") for (int _i = 0; _i < 2; ++_i) \
;         __builtin_amdgcn_global_load_lds((const unsigned*)((const char*)(gbase) + (voff)[_i]), (PG8_LAS unsigned*)(lds + (bufoff) + ldsw + _i * 8192), 16, 0, 0); } while (0)
; #define PG8_LDA(dst, b, h) do { _Pragma("unroll") for (int m = 0; m < 4; ++m) _Pragma("unroll") for (int k = 0; k < 2; ++k) dst[m][k] = *(const PG8_LAS bf16x8*)(lds + PG8_SA(b, h) + aoff + m * 2048 + k * 1024); } while (0)
; #define PG8_LDB(dst, b, h) do { _Pragma("unroll") for (int n = 0; n < 2; ++n) _Pragma("unroll") for (int k = 0; k < 2; ++k) dst[n][k] = *(const PG8_LAS bf16x8*)(lds + PG8_SB(b, h) + boff + n * 2048 + k * 1024); } while (0)
; #define PG8_MMA(ai, bj, At, Bt) do { __builtin_amdgcn_s_setprio(1); _Pragma("unroll") for (int m = 0; m < 4; ++m) _Pragma("unroll") for (int n = 0; n < 2; ++n) _Pragma("unroll") for (int k = 0; k < 2; ++k) \
;         acc[ai][bj][m][n] = __builtin_amdgcn_mfma_f32_16x16x32_bf16(Bt[n][k], At[m][k], acc[ai][bj][m][n], 0, 0, 0); __builtin_amdgcn_s_setprio(0); } while (0)
; #define PG8_WAIT_V(n) asm volatile("s_waitcnt vmcnt(" #n ")" ::: "memory")
; #define PG8_WAIT_L(n) asm volatile("s_waitcnt lgkmcnt(" #n ")" ::: "memory")
; #define PG8_BAR __builtin_amdgcn_s_barrier()
; #define PG8_SCHED __builtin_amdgcn_sched_barrier(0)
; template <class Epi, class Sched, bool ALIGN_EPI = false, bool SP2 = false, bool ACHUNK = false>
; __device__ __forceinline__ void gemm_phase(PG8_LAS unsigned char* lds, const Gemm g, const Sched& S, const Epi& E) {
;     ...
;             PG8_WAIT_V(8); PG8_WAIT_L(0); PG8_BAR; PG8_MMA(1, 0, At, B0); PG8_MMA(1, 1, At, B1); PG8_BAR; PG8_SCHED;
;             PG8_LDB(B0, 1, 0); PG8_LDB(B1, 1, 1); PG8_SCHED; PG8_LDA(At, 1, 0); PG8_STAGE(PG8_SA(0, 1), a2 + hstepA, voffA);
;             PG8_WAIT_V(8); PG8_WAIT_L(0); PG8_BAR; PG8_MMA(0, 0, At, B0); PG8_MMA(0, 1, At, B1); PG8_BAR; PG8_SCHED;
;             PG8_LDA(At, 1, 1); PG8_STAGE(PG8_SB(1, 0), b3, voffB); PG8_STAGE(PG8_SB(1, 1), b3 + hstepB, voffB); PG8_STAGE(PG8_SA(1, 0), a3, voffA);
;             PG8_WAIT_V(8); PG8_WAIT_L(0); PG8_BAR; PG8_MMA(1, 0, At, B0); PG8_MMA(1, 1, At, B1); PG8_BAR; PG8_SCHED;
	s_setprio 1
	v_mfma_f32_16x16x32_bf16 v[66:69], v[134:137], v[166:169], v[66:69]
	v_mfma_f32_16x16x32_bf16 v[62:65], v[142:145], v[166:169], v[62:65]
	v_mfma_f32_16x16x32_bf16 v[50:53], v[134:137], v[174:177], v[50:53]
	v_mfma_f32_16x16x32_bf16 v[46:49], v[142:145], v[174:177], v[46:49]
	v_mfma_f32_16x16x32_bf16 v[34:37], v[134:137], v[182:185], v[34:37]
	v_mfma_f32_16x16x32_bf16 v[30:33], v[142:145], v[182:185], v[30:33]
	v_mfma_f32_16x16x32_bf16 v[18:21], v[134:137], v[190:193], v[18:21]
	v_mfma_f32_16x16x32_bf16 v[14:17], v[142:145], v[190:193], v[14:17]
	v_mfma_f32_16x16x32_bf16 v[66:69], v[138:141], v[170:173], v[66:69]
	v_mfma_f32_16x16x32_bf16 v[62:65], v[146:149], v[170:173], v[62:65]
	v_mfma_f32_16x16x32_bf16 v[50:53], v[138:141], v[178:181], v[50:53]
	v_mfma_f32_16x16x32_bf16 v[46:49], v[146:149], v[178:181], v[46:49]
	v_mfma_f32_16x16x32_bf16 v[34:37], v[138:141], v[186:189], v[34:37]
	v_mfma_f32_16x16x32_bf16 v[30:33], v[146:149], v[186:189], v[30:33]
	v_mfma_f32_16x16x32_bf16 v[18:21], v[138:141], v[214:217], v[18:21]
	v_mfma_f32_16x16x32_bf16 v[14:17], v[146:149], v[214:217], v[14:17]
	s_setprio 0
	s_setprio 1
	v_mfma_f32_16x16x32_bf16 v[58:61], v[150:153], v[166:169], v[58:61]
	v_mfma_f32_16x16x32_bf16 v[54:57], v[158:161], v[166:169], v[54:57]
	v_mfma_f32_16x16x32_bf16 v[42:45], v[150:153], v[174:177], v[42:45]
	v_mfma_f32_16x16x32_bf16 v[38:41], v[158:161], v[174:177], v[38:41]
	v_mfma_f32_16x16x32_bf16 v[26:29], v[150:153], v[182:185], v[26:29]
	v_mfma_f32_16x16x32_bf16 v[22:25], v[158:161], v[182:185], v[22:25]
	v_mfma_f32_16x16x32_bf16 v[10:13], v[150:153], v[190:193], v[10:13]
	v_mfma_f32_16x16x32_bf16 v[4:7], v[158:161], v[190:193], v[6:9]
	v_mfma_f32_16x16x32_bf16 v[58:61], v[154:157], v[170:173], v[58:61]
	v_mfma_f32_16x16x32_bf16 v[54:57], v[162:165], v[170:173], v[54:57]
	v_mfma_f32_16x16x32_bf16 v[42:45], v[154:157], v[178:181], v[42:45]
	v_mfma_f32_16x16x32_bf16 v[38:41], v[162:165], v[178:181], v[38:41]
	v_mfma_f32_16x16x32_bf16 v[26:29], v[154:157], v[186:189], v[26:29]
	v_mfma_f32_16x16x32_bf16 v[22:25], v[162:165], v[186:189], v[22:25]
	v_mfma_f32_16x16x32_bf16 v[10:13], v[154:157], v[214:217], v[10:13]
	v_mfma_f32_16x16x32_bf16 v[4:7], v[162:165], v[214:217], v[4:7]
	s_setprio 0
	s_barrier
	s_add_i32 s52, 0, 0x18000
	s_add_i32 s53, 0, 0x1c000
	ds_read_b128 v[134:137], v218 offset:32768
	ds_read_b128 v[138:141], v218 offset:33792
	ds_read_b128 v[142:145], v218 offset:34816
	ds_read_b128 v[146:149], v218 offset:35840
	ds_read_b128 v[150:153], v218 offset:49152
	ds_read_b128 v[154:157], v218 offset:50176
	ds_read_b128 v[158:161], v218 offset:51200
	ds_read_b128 v[162:165], v218 offset:52224
	s_add_u32 s8, s8, s2
	s_addc_u32 s9, s9, s3
	s_mov_b32 m0, s21
	ds_read_b128 v[166:169], v237 offset:32768
	ds_read_b128 v[170:173], v237 offset:33792
	ds_read_b128 v[174:177], v237 offset:34816
	ds_read_b128 v[178:181], v237 offset:35840
	ds_read_b128 v[182:185], v237 offset:36864
	ds_read_b128 v[186:189], v237 offset:37888
	ds_read_b128 v[190:193], v237 offset:38912
	ds_read_b128 v[214:217], v237 offset:39936
	global_load_lds_dwordx4 v198, s[8:9]
	s_mov_b32 m0, s22
	s_nop 0
	global_load_lds_dwordx4 v202, s[8:9]
	s_waitcnt vmcnt(8)
	s_waitcnt lgkmcnt(0)
	s_barrier
	s_setprio 1
	v_mfma_f32_16x16x32_bf16 v[126:129], v[134:137], v[166:169], v[126:129]
	v_mfma_f32_16x16x32_bf16 v[130:133], v[142:145], v[166:169], v[130:133]
	v_mfma_f32_16x16x32_bf16 v[114:117], v[134:137], v[174:177], v[114:117]
	v_mfma_f32_16x16x32_bf16 v[110:113], v[142:145], v[174:177], v[110:113]
	v_mfma_f32_16x16x32_bf16 v[98:101], v[134:137], v[182:185], v[98:101]
	v_mfma_f32_16x16x32_bf16 v[94:97], v[142:145], v[182:185], v[94:97]
	v_mfma_f32_16x16x32_bf16 v[82:85], v[134:137], v[190:193], v[82:85]
	v_mfma_f32_16x16x32_bf16 v[78:81], v[142:145], v[190:193], v[78:81]
	v_mfma_f32_16x16x32_bf16 v[126:129], v[138:141], v[170:173], v[126:129]
	v_mfma_f32_16x16x32_bf16 v[130:133], v[146:149], v[170:173], v[130:133]
	v_mfma_f32_16x16x32_bf16 v[114:117], v[138:141], v[178:181], v[114:117]
	v_mfma_f32_16x16x32_bf16 v[110:113], v[146:149], v[178:181], v[110:113]
	v_mfma_f32_16x16x32_bf16 v[98:101], v[138:141], v[186:189], v[98:101]
	v_mfma_f32_16x16x32_bf16 v[94:97], v[146:149], v[186:189], v[94:97]
	v_mfma_f32_16x16x32_bf16 v[82:85], v[138:141], v[214:217], v[82:85]
	v_mfma_f32_16x16x32_bf16 v[78:81], v[146:149], v[214:217], v[78:81]
	s_setprio 0
	s_setprio 1
	v_mfma_f32_16x16x32_bf16 v[122:125], v[150:153], v[166:169], v[122:125]
	v_mfma_f32_16x16x32_bf16 v[118:121], v[158:161], v[166:169], v[118:121]
	v_mfma_f32_16x16x32_bf16 v[106:109], v[150:153], v[174:177], v[106:109]
	v_mfma_f32_16x16x32_bf16 v[102:105], v[158:161], v[174:177], v[102:105]
	v_mfma_f32_16x16x32_bf16 v[90:93], v[150:153], v[182:185], v[90:93]
	v_mfma_f32_16x16x32_bf16 v[86:89], v[158:161], v[182:185], v[86:89]
	v_mfma_f32_16x16x32_bf16 v[74:77], v[150:153], v[190:193], v[74:77]
	v_mfma_f32_16x16x32_bf16 v[70:73], v[158:161], v[190:193], v[70:73]
	v_mfma_f32_16x16x32_bf16 v[122:125], v[154:157], v[170:173], v[122:125]
	v_mfma_f32_16x16x32_bf16 v[118:121], v[162:165], v[170:173], v[118:121]
	v_mfma_f32_16x16x32_bf16 v[106:109], v[154:157], v[178:181], v[106:109]
	v_mfma_f32_16x16x32_bf16 v[102:105], v[162:165], v[178:181], v[102:105]
	v_mfma_f32_16x16x32_bf16 v[90:93], v[154:157], v[186:189], v[90:93]
	v_mfma_f32_16x16x32_bf16 v[86:89], v[162:165], v[186:189], v[86:89]
	v_mfma_f32_16x16x32_bf16 v[74:77], v[154:157], v[214:217], v[74:77]
	v_mfma_f32_16x16x32_bf16 v[70:73], v[162:165], v[214:217], v[70:73]
	s_setprio 0
	s_barrier
; #define PG8_STAGE(bufoff, gbase, voff) do { _Pragma("unroll") for (int _i = 0; _i < 2; ++_i) \
;         __builtin_amdgcn_global_load_lds((const unsigned*)((const char*)(gbase) + (voff)[_i]), (PG8_LAS unsigned*)(lds + (bufoff) + ldsw + _i * 8192), 16, 0, 0); } while (0)
; #define PG8_LDA(dst, b, h) do { _Pragma("unroll") for (int m = 0; m < 4; ++m) _Pragma("unroll") for (int k = 0; k < 2; ++k) dst[m][k] = *(const PG8_LAS bf16x8*)(lds + PG8_SA(b, h) + aoff + m * 2048 + k * 1024); } while (0)
; #define PG8_MMA(ai, bj, At, Bt) do { __builtin_amdgcn_s_setprio(1); _Pragma("unroll") for (int m = 0; m < 4; ++m) _Pragma("unroll") for (int n = 0; n < 2; ++n) _Pragma("unroll") for (int k = 0; k < 2; ++k) \
;         acc[ai][bj][m][n] = __builtin_amdgcn_mfma_f32_16x16x32_bf16(Bt[n][k], At[m][k], acc[ai][bj][m][n], 0, 0, 0); __builtin_amdgcn_s_setprio(0); } while (0)
; #define PG8_WAIT_V(n) asm volatile("s_waitcnt vmcnt(" #n ")" ::: "memory")
; #define PG8_WAIT_L(n) asm volatile("s_waitcnt lgkmcnt(" #n ")" ::: "memory")
; #define PG8_BAR __builtin_amdgcn_s_barrier()
; #define PG8_SCHED __builtin_amdgcn_sched_barrier(0)
; template <class Epi, class Sched, bool ALIGN_EPI = false, bool SP2 = false, bool ACHUNK = false>
; __device__ __forceinline__ void gemm_phase(PG8_LAS unsigned char* lds, const Gemm g, const Sched& S, const Epi& E) {
;     ...
;         for (int t = 0; t < nt; t += 2) {
;     ...
;             PG8_LDA(At, 1, 1); PG8_STAGE(PG8_SB(1, 0), b3, voffB); PG8_STAGE(PG8_SB(1, 1), b3 + hstepB, voffB); PG8_STAGE(PG8_SA(1, 0), a3, voffA);
;             PG8_WAIT_V(8); PG8_WAIT_L(0); PG8_BAR; PG8_MMA(1, 0, At, B0); PG8_MMA(1, 1, At, B1); PG8_BAR; PG8_SCHED;
	s_add_u32 vcc_lo, vcc_lo, s10
	s_addc_u32 vcc_hi, vcc_hi, s11
	s_add_u32 s98, s98, s10
	s_addc_u32 s99, s99, s11
	s_sub_u32 s8, s8, s2
	s_subb_u32 s9, s9, s3
	s_add_u32 s8, s8, s10
	s_addc_u32 s9, s9, s11
	s_add_i32 m0, s52, s16
	ds_read_b128 v[166:169], v237 offset:49152
	ds_read_b128 v[170:173], v237 offset:50176
	ds_read_b128 v[174:177], v237 offset:51200
	ds_read_b128 v[178:181], v237 offset:52224
	ds_read_b128 v[182:185], v237 offset:53248
	ds_read_b128 v[186:189], v237 offset:54272
	ds_read_b128 v[190:193], v237 offset:55296
	ds_read_b128 v[214:217], v237 offset:56320
	global_load_lds_dwordx4 v200, s[98:99]
	s_add_i32 m0, m0, 0x2000
	s_nop 0
	global_load_lds_dwordx4 v204, s[98:99]
	s_add_i32 m0, s53, s16
	s_nop 0
	global_load_lds_dwordx4 v200, vcc
	s_add_i32 m0, m0, 0x2000
	s_nop 0
	global_load_lds_dwordx4 v204, vcc
	s_mov_b32 m0, s26
	s_nop 0
	global_load_lds_dwordx4 v198, s[8:9]
	s_mov_b32 m0, s27
	s_nop 0
	global_load_lds_dwordx4 v202, s[8:9]
	s_waitcnt vmcnt(8)
	s_waitcnt lgkmcnt(0)
	s_barrier
	s_setprio 1
	v_mfma_f32_16x16x32_bf16 v[66:69], v[134:137], v[166:169], v[66:69]
	v_mfma_f32_16x16x32_bf16 v[62:65], v[142:145], v[166:169], v[62:65]
	v_mfma_f32_16x16x32_bf16 v[50:53], v[134:137], v[174:177], v[50:53]
	v_mfma_f32_16x16x32_bf16 v[46:49], v[142:145], v[174:177], v[46:49]
	v_mfma_f32_16x16x32_bf16 v[34:37], v[134:137], v[182:185], v[34:37]
	v_mfma_f32_16x16x32_bf16 v[30:33], v[142:145], v[182:185], v[30:33]
	v_mfma_f32_16x16x32_bf16 v[18:21], v[134:137], v[190:193], v[18:21]
	v_mfma_f32_16x16x32_bf16 v[14:17], v[142:145], v[190:193], v[14:17]
	v_mfma_f32_16x16x32_bf16 v[66:69], v[138:141], v[170:173], v[66:69]
	v_mfma_f32_16x16x32_bf16 v[62:65], v[146:149], v[170:173], v[62:65]
	v_mfma_f32_16x16x32_bf16 v[50:53], v[138:141], v[178:181], v[50:53]
	v_mfma_f32_16x16x32_bf16 v[46:49], v[146:149], v[178:181], v[46:49]
	v_mfma_f32_16x16x32_bf16 v[34:37], v[138:141], v[186:189], v[34:37]
	v_mfma_f32_16x16x32_bf16 v[30:33], v[146:149], v[186:189], v[30:33]
	v_mfma_f32_16x16x32_bf16 v[18:21], v[138:141], v[214:217], v[18:21]
	v_mfma_f32_16x16x32_bf16 v[14:17], v[146:149], v[214:217], v[14:17]
	s_setprio 0
	s_setprio 1
	v_mfma_f32_16x16x32_bf16 v[58:61], v[150:153], v[166:169], v[58:61]
	v_mfma_f32_16x16x32_bf16 v[54:57], v[158:161], v[166:169], v[54:57]
	v_mfma_f32_16x16x32_bf16 v[42:45], v[150:153], v[174:177], v[42:45]
	v_mfma_f32_16x16x32_bf16 v[38:41], v[158:161], v[174:177], v[38:41]
	v_mfma_f32_16x16x32_bf16 v[26:29], v[150:153], v[182:185], v[26:29]
	v_mfma_f32_16x16x32_bf16 v[22:25], v[158:161], v[182:185], v[22:25]
	v_mfma_f32_16x16x32_bf16 v[8:11], v[150:153], v[190:193], v[10:13]
	v_mfma_f32_16x16x32_bf16 v[4:7], v[158:161], v[190:193], v[4:7]
	v_mfma_f32_16x16x32_bf16 v[58:61], v[154:157], v[170:173], v[58:61]
	v_mfma_f32_16x16x32_bf16 v[54:57], v[162:165], v[170:173], v[54:57]
	v_mfma_f32_16x16x32_bf16 v[42:45], v[154:157], v[178:181], v[42:45]
	v_mfma_f32_16x16x32_bf16 v[38:41], v[162:165], v[178:181], v[38:41]
	v_mfma_f32_16x16x32_bf16 v[26:29], v[154:157], v[186:189], v[26:29]
	v_mfma_f32_16x16x32_bf16 v[22:25], v[162:165], v[186:189], v[22:25]
	v_mfma_f32_16x16x32_bf16 v[10:13], v[154:157], v[214:217], v[8:11]
	v_mfma_f32_16x16x32_bf16 v[6:9], v[162:165], v[214:217], v[4:7]
	s_setprio 0
	s_barrier
	s_add_u32 s6, s6, 0x100
	s_addc_u32 s7, s7, 0
	s_cmp_ge_i32 s51, s23
	s_cbranch_scc0 .LBB0_266
	v_readlane_b32 s54, v254, 25
	v_readlane_b32 s52, v254, 27
	v_readlane_b32 s55, v254, 26
	v_readlane_b32 s53, v254, 28
	v_readlane_b32 s47, v255, 0
	s_mov_b32 s50, s94

; #define PG8_STAGE(bufoff, gbase, voff) do { _Pragma("unroll") for (int _i = 0; _i < 2; ++_i) \
;         __builtin_amdgcn_global_load_lds((const unsigned*)((const char*)(gbase) + (voff)[_i]), (PG8_LAS unsigned*)(lds + (bufoff) + ldsw + _i * 8192), 16, 0, 0); } while (0)
; #define PG8_LDA(dst, b, h) do { _Pragma("unroll") for (int m = 0; m < 4; ++m) _Pragma("unroll") for (int k = 0; k < 2; ++k) dst[m][k] = *(const PG8_LAS bf16x8*)(lds + PG8_SA(b, h) + aoff + m * 2048 + k * 1024); } while (0)
; #define PG8_LDB(dst, b, h) do { _Pragma("unroll") for (int n = 0; n < 2; ++n) _Pragma("unroll") for (int k = 0; k < 2; ++k) dst[n][k] = *(const PG8_LAS bf16x8*)(lds + PG8_SB(b, h) + boff + n * 2048 + k * 1024); } while (0)
; #define PG8_WAIT_V(n) asm volatile("s_waitcnt vmcnt(" #n ")" ::: "memory")
; #define PG8_WAIT_L(n) asm volatile("s_waitcnt lgkmcnt(" #n ")" ::: "memory")
; template <class Epi, class Sched, bool ALIGN_EPI = false, bool SP2 = false, bool ACHUNK = false>
; __device__ __forceinline__ void gemm_phase(PG8_LAS unsigned char* lds, const Gemm g, const Sched& S, const Epi& E) {
;     ...
;         const bool has_next = S.next(ui + 1, nxt);
;         const char* nA = has_next ? (const char*)g.A + (size_t)nxt.pm * tstepA : cA; const char* nB = has_next ? (const char*)g.Bt + (size_t)nxt.pn * tstepB : cB;
;         for (int t = 0; t < nt; t += 2) {
;             const bool last = (t == nt - 2);
;             if constexpr (Epi::HAS_MID) { if (t == Epi::MID_T) E.mid(acc, cur, wr, wc, fr, fq, ShflDev{}); }
;             const char* a1 = cA + (size_t)(t + 1) * kstep;
;             const char* a2 = last ? nA : cA + (size_t)(t + 2) * kstep; const char* b2 = last ? nB : cB + (size_t)(t + 2) * kstep;
;             const char* a3 = a2 + kstep; const char* b3 = b2 + kstep;
;             if (last && has_next) S.a_ready(nxt);
;             if constexpr (SP2) {
;             PG8_LDB(B0, 0, 0); PG8_LDB(B1, 0, 1); PG8_SCHED; PG8_LDA(At, 0, 0); PG8_STAGE(PG8_SA(1, 1), a1 + hstepA, voffA);
;             PG8_WAIT_V(8); PG8_WAIT_L(0); PG8_BAR; PG8_MMA(0, 0, At, B0); PG8_MMA(0, 1, At, B1); PG8_BAR; PG8_SCHED;
;             PG8_LDA(At, 0, 1); PG8_STAGE(PG8_SB(0, 0), b2, voffB); PG8_STAGE(PG8_SB(0, 1), b2 + hstepB, voffB); PG8_STAGE(PG8_SA(0, 0), a2, voffA);
;             PG8_WAIT_V(8); PG8_WAIT_L(0); PG8_BAR; PG8_MMA(1, 0, At, B0); PG8_MMA(1, 1, At, B1); PG8_BAR; PG8_SCHED;
.LBB0_351:
	s_andn2_b64 vcc, exec, s[4:5]
	s_cbranch_vccnz .LBB0_342
	s_add_u32 s40, s18, 0x100
	s_addc_u32 s41, s19, 0
	s_add_u32 s18, s20, 0x80
	s_addc_u32 s19, s21, 0
	s_mov_b32 s20, 0
	v_add_u32_e32 v222, 0x10000, v143
	s_add_i32 s42, s20, 2
	s_add_u32 s43, s18, 0x80
	s_addc_u32 s21, s19, 0
	s_add_i32 s46, 0, 0x10000
	s_cmp_eq_u32 s33, s20
	s_cselect_b32 s21, s13, s21
	s_cselect_b32 s20, s12, s43
	s_cselect_b32 s45, s17, s41
	s_cselect_b32 s44, s16, s40
	s_add_i32 s43, 0, 0x14000
	ds_read_b128 v[154:157], v222
	ds_read_b128 v[158:161], v222 offset:1024
	ds_read_b128 v[162:165], v222 offset:2048
	ds_read_b128 v[166:169], v222 offset:3072
	ds_read_b128 v[170:173], v222 offset:16384
	ds_read_b128 v[174:177], v222 offset:17408
	ds_read_b128 v[178:181], v222 offset:18432
	ds_read_b128 v[182:185], v222 offset:19456
	s_add_i32 m0, s25, 0xc000
	ds_read_b128 v[186:189], v152
	ds_read_b128 v[190:193], v152 offset:1024
	ds_read_b128 v[198:201], v152 offset:2048
	ds_read_b128 v[202:205], v152 offset:3072
	ds_read_b128 v[206:209], v152 offset:4096
	ds_read_b128 v[210:213], v152 offset:5120
	ds_read_b128 v[214:217], v152 offset:6144
	ds_read_b128 v[218:221], v152 offset:7168
	global_load_lds_dwordx4 v138, s[18:19]
	s_add_i32 m0, s25, 0xe000
	s_nop 0
	global_load_lds_dwordx4 v140, s[18:19]
	s_waitcnt vmcnt(8)
	s_waitcnt lgkmcnt(0)
	s_barrier
	s_setprio 1
	v_mfma_f32_16x16x32_bf16 v[124:127], v[154:157], v[186:189], 0
	v_mfma_f32_16x16x32_bf16 v[128:131], v[162:165], v[186:189], 0
	v_mfma_f32_16x16x32_bf16 v[112:115], v[154:157], v[198:201], 0
	v_mfma_f32_16x16x32_bf16 v[108:111], v[162:165], v[198:201], 0
	v_mfma_f32_16x16x32_bf16 v[96:99], v[154:157], v[206:209], 0
	v_mfma_f32_16x16x32_bf16 v[92:95], v[162:165], v[206:209], 0
	v_mfma_f32_16x16x32_bf16 v[80:83], v[154:157], v[214:217], 0
	v_mfma_f32_16x16x32_bf16 v[76:79], v[162:165], v[214:217], 0
	v_mfma_f32_16x16x32_bf16 v[124:127], v[158:161], v[190:193], v[124:127]
	v_mfma_f32_16x16x32_bf16 v[128:131], v[166:169], v[190:193], v[128:131]
	v_mfma_f32_16x16x32_bf16 v[112:115], v[158:161], v[202:205], v[112:115]
	v_mfma_f32_16x16x32_bf16 v[108:111], v[166:169], v[202:205], v[108:111]
	v_mfma_f32_16x16x32_bf16 v[96:99], v[158:161], v[210:213], v[96:99]
	v_mfma_f32_16x16x32_bf16 v[92:95], v[166:169], v[210:213], v[92:95]
	v_mfma_f32_16x16x32_bf16 v[80:83], v[158:161], v[218:221], v[80:83]
	v_mfma_f32_16x16x32_bf16 v[76:79], v[166:169], v[218:221], v[76:79]
	s_setprio 0
	s_setprio 1
	v_mfma_f32_16x16x32_bf16 v[120:123], v[170:173], v[186:189], 0
	v_mfma_f32_16x16x32_bf16 v[116:119], v[178:181], v[186:189], 0
	v_mfma_f32_16x16x32_bf16 v[104:107], v[170:173], v[198:201], 0
	v_mfma_f32_16x16x32_bf16 v[100:103], v[178:181], v[198:201], 0
	v_mfma_f32_16x16x32_bf16 v[88:91], v[170:173], v[206:209], 0
	v_mfma_f32_16x16x32_bf16 v[84:87], v[178:181], v[206:209], 0
	v_mfma_f32_16x16x32_bf16 v[72:75], v[170:173], v[214:217], 0
	v_mfma_f32_16x16x32_bf16 v[68:71], v[178:181], v[214:217], 0
	v_mfma_f32_16x16x32_bf16 v[120:123], v[174:177], v[190:193], v[120:123]
	v_mfma_f32_16x16x32_bf16 v[116:119], v[182:185], v[190:193], v[116:119]
	v_mfma_f32_16x16x32_bf16 v[104:107], v[174:177], v[202:205], v[104:107]
	v_mfma_f32_16x16x32_bf16 v[100:103], v[182:185], v[202:205], v[100:103]
	v_mfma_f32_16x16x32_bf16 v[88:91], v[174:177], v[210:213], v[88:91]
	v_mfma_f32_16x16x32_bf16 v[84:87], v[182:185], v[210:213], v[84:87]
	v_mfma_f32_16x16x32_bf16 v[72:75], v[174:177], v[218:221], v[72:75]
	v_mfma_f32_16x16x32_bf16 v[68:71], v[182:185], v[218:221], v[68:71]
	s_setprio 0
	s_barrier
	s_add_i32 s46, s46, s24
	s_mov_b32 m0, s46
	ds_read_b128 v[186:189], v152 offset:16384
	ds_read_b128 v[190:193], v152 offset:17408
	ds_read_b128 v[198:201], v152 offset:18432
	ds_read_b128 v[202:205], v152 offset:19456
	ds_read_b128 v[206:209], v152 offset:20480
	ds_read_b128 v[210:213], v152 offset:21504
	ds_read_b128 v[214:217], v152 offset:22528
	ds_read_b128 v[218:221], v152 offset:23552
	global_load_lds_dwordx4 v2, s[44:45]
	s_add_i32 m0, s46, 0x2000
	s_add_i32 s43, s43, s24
	global_load_lds_dwordx4 v136, s[44:45]
	s_add_u32 s44, s44, s0
	s_addc_u32 s45, s45, s1
	s_mov_b64 vcc, s[44:45]
	s_sub_u32 s98, s44, s0
	s_subb_u32 s99, s45, s1
	s_mov_b32 m0, s43
	s_nop 0
	global_load_lds_dwordx4 v2, s[44:45]
	s_add_i32 m0, s43, 0x2000
	s_nop 0
	global_load_lds_dwordx4 v136, s[44:45]
	s_mov_b32 m0, s25
	s_nop 0
	global_load_lds_dwordx4 v132, s[20:21]
	s_mov_b32 m0, s26
	s_nop 0
	global_load_lds_dwordx4 v134, s[20:21]
	s_waitcnt vmcnt(8)
	s_waitcnt lgkmcnt(0)
	s_barrier
	s_setprio 1
	v_mfma_f32_16x16x32_bf16 v[64:67], v[154:157], v[186:189], 0
	v_mfma_f32_16x16x32_bf16 v[60:63], v[162:165], v[186:189], 0
	v_mfma_f32_16x16x32_bf16 v[48:51], v[154:157], v[198:201], 0
	v_mfma_f32_16x16x32_bf16 v[44:47], v[162:165], v[198:201], 0
	v_mfma_f32_16x16x32_bf16 v[32:35], v[154:157], v[206:209], 0
	v_mfma_f32_16x16x32_bf16 v[28:31], v[162:165], v[206:209], 0
	v_mfma_f32_16x16x32_bf16 v[16:19], v[154:157], v[214:217], 0
	v_mfma_f32_16x16x32_bf16 v[12:15], v[162:165], v[214:217], 0
	v_mfma_f32_16x16x32_bf16 v[64:67], v[158:161], v[190:193], v[64:67]
	v_mfma_f32_16x16x32_bf16 v[60:63], v[166:169], v[190:193], v[60:63]
	v_mfma_f32_16x16x32_bf16 v[48:51], v[158:161], v[202:205], v[48:51]
	v_mfma_f32_16x16x32_bf16 v[44:47], v[166:169], v[202:205], v[44:47]
	v_mfma_f32_16x16x32_bf16 v[32:35], v[158:161], v[210:213], v[32:35]
	v_mfma_f32_16x16x32_bf16 v[28:31], v[166:169], v[210:213], v[28:31]
	v_mfma_f32_16x16x32_bf16 v[16:19], v[158:161], v[218:221], v[16:19]
	v_mfma_f32_16x16x32_bf16 v[12:15], v[166:169], v[218:221], v[12:15]
	s_setprio 0
	s_setprio 1
	v_mfma_f32_16x16x32_bf16 v[56:59], v[170:173], v[186:189], 0
	v_mfma_f32_16x16x32_bf16 v[52:55], v[178:181], v[186:189], 0
	v_mfma_f32_16x16x32_bf16 v[40:43], v[170:173], v[198:201], 0
	v_mfma_f32_16x16x32_bf16 v[36:39], v[178:181], v[198:201], 0
	v_mfma_f32_16x16x32_bf16 v[24:27], v[170:173], v[206:209], 0
	v_mfma_f32_16x16x32_bf16 v[20:23], v[178:181], v[206:209], 0
	v_mfma_f32_16x16x32_bf16 v[8:11], v[170:173], v[214:217], 0
	v_mfma_f32_16x16x32_bf16 v[4:7], v[178:181], v[214:217], 0
	v_mfma_f32_16x16x32_bf16 v[56:59], v[174:177], v[190:193], v[56:59]
	v_mfma_f32_16x16x32_bf16 v[52:55], v[182:185], v[190:193], v[52:55]
	v_mfma_f32_16x16x32_bf16 v[40:43], v[174:177], v[202:205], v[40:43]
	v_mfma_f32_16x16x32_bf16 v[36:39], v[182:185], v[202:205], v[36:39]
	v_mfma_f32_16x16x32_bf16 v[24:27], v[174:177], v[210:213], v[24:27]
	v_mfma_f32_16x16x32_bf16 v[20:23], v[182:185], v[210:213], v[20:23]
	v_mfma_f32_16x16x32_bf16 v[8:11], v[174:177], v[218:221], v[8:11]
	v_mfma_f32_16x16x32_bf16 v[4:7], v[182:185], v[218:221], v[4:7]
	s_setprio 0
	s_barrier
	s_branch .Lpe_join_353
; #define PG8_STAGE(bufoff, gbase, voff) do { _Pragma("unroll") for (int _i = 0; _i < 2; ++_i) \
;         __builtin_amdgcn_global_load_lds((const unsigned*)((const char*)(gbase) + (voff)[_i]), (PG8_LAS unsigned*)(lds + (bufoff) + ldsw + _i * 8192), 16, 0, 0); } while (0)
; #define PG8_LDA(dst, b, h) do { _Pragma("unroll") for (int m = 0; m < 4; ++m) _Pragma("unroll") for (int k = 0; k < 2; ++k) dst[m][k] = *(const PG8_LAS bf16x8*)(lds + PG8_SA(b, h) + aoff + m * 2048 + k * 1024); } while (0)
; #define PG8_LDB(dst, b, h) do { _Pragma("unroll") for (int n = 0; n < 2; ++n) _Pragma("unroll") for (int k = 0; k < 2; ++k) dst[n][k] = *(const PG8_LAS bf16x8*)(lds + PG8_SB(b, h) + boff + n * 2048 + k * 1024); } while (0)
; #define PG8_MMA(ai, bj, At, Bt) do { __builtin_amdgcn_s_setprio(1); _Pragma("unroll") for (int m = 0; m < 4; ++m) _Pragma("unroll") for (int n = 0; n < 2; ++n) _Pragma("unroll") for (int k = 0; k < 2; ++k) \
;         acc[ai][bj][m][n] = __builtin_amdgcn_mfma_f32_16x16x32_bf16(Bt[n][k], At[m][k], acc[ai][bj][m][n], 0, 0, 0); __builtin_amdgcn_s_setprio(0); } while (0)
; #define PG8_WAIT_V(n) asm volatile("s_waitcnt vmcnt(" #n ")" ::: "memory")
; #define PG8_WAIT_L(n) asm volatile("s_waitcnt lgkmcnt(" #n ")" ::: "memory")
; #define PG8_BAR __builtin_amdgcn_s_barrier()
; #define PG8_SCHED __builtin_amdgcn_sched_barrier(0)
; template <class Epi, class Sched, bool ALIGN_EPI = false, bool SP2 = false, bool ACHUNK = false>
; __device__ __forceinline__ void gemm_phase(PG8_LAS unsigned char* lds, const Gemm g, const Sched& S, const Epi& E) {
;     ...
;             PG8_LDB(B0, 0, 0); PG8_LDB(B1, 0, 1); PG8_SCHED; PG8_LDA(At, 0, 0); PG8_STAGE(PG8_SA(1, 1), a1 + hstepA, voffA);
;             PG8_WAIT_V(8); PG8_WAIT_L(0); PG8_BAR; PG8_MMA(0, 0, At, B0); PG8_MMA(0, 1, At, B1); PG8_BAR; PG8_SCHED;
;             PG8_LDA(At, 0, 1); PG8_STAGE(PG8_SB(0, 0), b2, voffB); PG8_STAGE(PG8_SB(0, 1), b2 + hstepB, voffB); PG8_STAGE(PG8_SA(0, 0), a2, voffA);
;             PG8_WAIT_V(8); PG8_WAIT_L(0); PG8_BAR; PG8_MMA(1, 0, At, B0); PG8_MMA(1, 1, At, B1); PG8_BAR; PG8_SCHED;
.LBB0_353:
	s_add_i32 s42, s20, 2
	s_add_u32 s43, s18, 0x80
	s_addc_u32 s21, s19, 0
	s_add_i32 s46, 0, 0x10000
	s_cmp_eq_u32 s33, s20
	s_cselect_b32 s21, s13, s21
	s_cselect_b32 s20, s12, s43
	s_cselect_b32 s45, s17, s41
	s_cselect_b32 s44, s16, s40
	s_add_i32 s43, 0, 0x14000
	ds_read_b128 v[154:157], v222
	ds_read_b128 v[158:161], v222 offset:1024
	ds_read_b128 v[162:165], v222 offset:2048
	ds_read_b128 v[166:169], v222 offset:3072
	ds_read_b128 v[170:173], v222 offset:16384
	ds_read_b128 v[174:177], v222 offset:17408
	ds_read_b128 v[178:181], v222 offset:18432
	ds_read_b128 v[182:185], v222 offset:19456
	s_add_i32 m0, s25, 0xc000
	ds_read_b128 v[186:189], v152
	ds_read_b128 v[190:193], v152 offset:1024
	ds_read_b128 v[198:201], v152 offset:2048
	ds_read_b128 v[202:205], v152 offset:3072
	ds_read_b128 v[206:209], v152 offset:4096
	ds_read_b128 v[210:213], v152 offset:5120
	ds_read_b128 v[214:217], v152 offset:6144
	ds_read_b128 v[218:221], v152 offset:7168
	global_load_lds_dwordx4 v138, s[18:19]
	s_add_i32 m0, s25, 0xe000
	s_nop 0
	global_load_lds_dwordx4 v140, s[18:19]
	s_waitcnt vmcnt(8)
	s_waitcnt lgkmcnt(0)
	s_barrier
	s_setprio 1
	v_mfma_f32_16x16x32_bf16 v[124:127], v[154:157], v[186:189], v[124:127]
	v_mfma_f32_16x16x32_bf16 v[128:131], v[162:165], v[186:189], v[128:131]
	v_mfma_f32_16x16x32_bf16 v[112:115], v[154:157], v[198:201], v[112:115]
	v_mfma_f32_16x16x32_bf16 v[108:111], v[162:165], v[198:201], v[108:111]
	v_mfma_f32_16x16x32_bf16 v[96:99], v[154:157], v[206:209], v[96:99]
	v_mfma_f32_16x16x32_bf16 v[92:95], v[162:165], v[206:209], v[92:95]
	v_mfma_f32_16x16x32_bf16 v[80:83], v[154:157], v[214:217], v[80:83]
	v_mfma_f32_16x16x32_bf16 v[76:79], v[162:165], v[214:217], v[76:79]
	v_mfma_f32_16x16x32_bf16 v[124:127], v[158:161], v[190:193], v[124:127]
	v_mfma_f32_16x16x32_bf16 v[128:131], v[166:169], v[190:193], v[128:131]
	v_mfma_f32_16x16x32_bf16 v[112:115], v[158:161], v[202:205], v[112:115]
	v_mfma_f32_16x16x32_bf16 v[108:111], v[166:169], v[202:205], v[108:111]
	v_mfma_f32_16x16x32_bf16 v[96:99], v[158:161], v[210:213], v[96:99]
	v_mfma_f32_16x16x32_bf16 v[92:95], v[166:169], v[210:213], v[92:95]
	v_mfma_f32_16x16x32_bf16 v[80:83], v[158:161], v[218:221], v[80:83]
	v_mfma_f32_16x16x32_bf16 v[76:79], v[166:169], v[218:221], v[76:79]
	s_setprio 0
	s_setprio 1
	v_mfma_f32_16x16x32_bf16 v[120:123], v[170:173], v[186:189], v[120:123]
	v_mfma_f32_16x16x32_bf16 v[116:119], v[178:181], v[186:189], v[116:119]
	v_mfma_f32_16x16x32_bf16 v[104:107], v[170:173], v[198:201], v[104:107]
	v_mfma_f32_16x16x32_bf16 v[100:103], v[178:181], v[198:201], v[100:103]
	v_mfma_f32_16x16x32_bf16 v[88:91], v[170:173], v[206:209], v[88:91]
	v_mfma_f32_16x16x32_bf16 v[84:87], v[178:181], v[206:209], v[84:87]
	v_mfma_f32_16x16x32_bf16 v[72:75], v[170:173], v[214:217], v[72:75]
	v_mfma_f32_16x16x32_bf16 v[68:71], v[178:181], v[214:217], v[68:71]
	v_mfma_f32_16x16x32_bf16 v[120:123], v[174:177], v[190:193], v[120:123]
	v_mfma_f32_16x16x32_bf16 v[116:119], v[182:185], v[190:193], v[116:119]
	v_mfma_f32_16x16x32_bf16 v[104:107], v[174:177], v[202:205], v[104:107]
	v_mfma_f32_16x16x32_bf16 v[100:103], v[182:185], v[202:205], v[100:103]
	v_mfma_f32_16x16x32_bf16 v[88:91], v[174:177], v[210:213], v[88:91]
	v_mfma_f32_16x16x32_bf16 v[84:87], v[182:185], v[210:213], v[84:87]
	v_mfma_f32_16x16x32_bf16 v[72:75], v[174:177], v[218:221], v[72:75]
	v_mfma_f32_16x16x32_bf16 v[68:71], v[182:185], v[218:221], v[68:71]
	s_setprio 0
	s_barrier
	s_add_i32 s46, s46, s24
	s_mov_b32 m0, s46
	ds_read_b128 v[186:189], v152 offset:16384
	ds_read_b128 v[190:193], v152 offset:17408
	ds_read_b128 v[198:201], v152 offset:18432
	ds_read_b128 v[202:205], v152 offset:19456
	ds_read_b128 v[206:209], v152 offset:20480
	ds_read_b128 v[210:213], v152 offset:21504
	ds_read_b128 v[214:217], v152 offset:22528
	ds_read_b128 v[218:221], v152 offset:23552
	global_load_lds_dwordx4 v2, s[44:45]
	s_add_i32 m0, s46, 0x2000
	s_add_i32 s43, s43, s24
	global_load_lds_dwordx4 v136, s[44:45]
	s_add_u32 s44, s44, s0
	s_addc_u32 s45, s45, s1
	s_mov_b64 vcc, s[44:45]
	s_sub_u32 s98, s44, s0
	s_subb_u32 s99, s45, s1
	s_mov_b32 m0, s43
	s_nop 0
	global_load_lds_dwordx4 v2, s[44:45]
	s_add_i32 m0, s43, 0x2000
	s_nop 0
	global_load_lds_dwordx4 v136, s[44:45]
	s_mov_b32 m0, s25
	s_nop 0
	global_load_lds_dwordx4 v132, s[20:21]
	s_mov_b32 m0, s26
	s_nop 0
	global_load_lds_dwordx4 v134, s[20:21]
	s_waitcnt vmcnt(8)
	s_waitcnt lgkmcnt(0)
	s_barrier
	s_setprio 1
	v_mfma_f32_16x16x32_bf16 v[64:67], v[154:157], v[186:189], v[64:67]
	v_mfma_f32_16x16x32_bf16 v[60:63], v[162:165], v[186:189], v[60:63]
	v_mfma_f32_16x16x32_bf16 v[48:51], v[154:157], v[198:201], v[48:51]
	v_mfma_f32_16x16x32_bf16 v[44:47], v[162:165], v[198:201], v[44:47]
	v_mfma_f32_16x16x32_bf16 v[32:35], v[154:157], v[206:209], v[32:35]
	v_mfma_f32_16x16x32_bf16 v[28:31], v[162:165], v[206:209], v[28:31]
	v_mfma_f32_16x16x32_bf16 v[16:19], v[154:157], v[214:217], v[16:19]
	v_mfma_f32_16x16x32_bf16 v[12:15], v[162:165], v[214:217], v[12:15]
	v_mfma_f32_16x16x32_bf16 v[64:67], v[158:161], v[190:193], v[64:67]
	v_mfma_f32_16x16x32_bf16 v[60:63], v[166:169], v[190:193], v[60:63]
	v_mfma_f32_16x16x32_bf16 v[48:51], v[158:161], v[202:205], v[48:51]
	v_mfma_f32_16x16x32_bf16 v[44:47], v[166:169], v[202:205], v[44:47]
	v_mfma_f32_16x16x32_bf16 v[32:35], v[158:161], v[210:213], v[32:35]
	v_mfma_f32_16x16x32_bf16 v[28:31], v[166:169], v[210:213], v[28:31]
	v_mfma_f32_16x16x32_bf16 v[16:19], v[158:161], v[218:221], v[16:19]
	v_mfma_f32_16x16x32_bf16 v[12:15], v[166:169], v[218:221], v[12:15]
	s_setprio 0
	s_setprio 1
	v_mfma_f32_16x16x32_bf16 v[56:59], v[170:173], v[186:189], v[56:59]
	v_mfma_f32_16x16x32_bf16 v[52:55], v[178:181], v[186:189], v[52:55]
	v_mfma_f32_16x16x32_bf16 v[40:43], v[170:173], v[198:201], v[40:43]
	v_mfma_f32_16x16x32_bf16 v[36:39], v[178:181], v[198:201], v[36:39]
	v_mfma_f32_16x16x32_bf16 v[24:27], v[170:173], v[206:209], v[24:27]
	v_mfma_f32_16x16x32_bf16 v[20:23], v[178:181], v[206:209], v[20:23]
	v_mfma_f32_16x16x32_bf16 v[8:11], v[170:173], v[214:217], v[8:11]
	v_mfma_f32_16x16x32_bf16 v[4:7], v[178:181], v[214:217], v[4:7]
	v_mfma_f32_16x16x32_bf16 v[56:59], v[174:177], v[190:193], v[56:59]
	v_mfma_f32_16x16x32_bf16 v[52:55], v[182:185], v[190:193], v[52:55]
	v_mfma_f32_16x16x32_bf16 v[40:43], v[174:177], v[202:205], v[40:43]
	v_mfma_f32_16x16x32_bf16 v[36:39], v[182:185], v[202:205], v[36:39]
	v_mfma_f32_16x16x32_bf16 v[24:27], v[174:177], v[210:213], v[24:27]
	v_mfma_f32_16x16x32_bf16 v[20:23], v[182:185], v[210:213], v[20:23]
	v_mfma_f32_16x16x32_bf16 v[8:11], v[174:177], v[218:221], v[8:11]
	v_mfma_f32_16x16x32_bf16 v[4:7], v[182:185], v[218:221], v[4:7]
	s_setprio 0
	s_barrier
; #define PG8_STAGE(bufoff, gbase, voff) do { _Pragma("unroll") for (int _i = 0; _i < 2; ++_i) \
;         __builtin_amdgcn_global_load_lds((const unsigned*)((const char*)(gbase) + (voff)[_i]), (PG8_LAS unsigned*)(lds + (bufoff) + ldsw + _i * 8192), 16, 0, 0); } while (0)
; #define PG8_LDA(dst, b, h) do { _Pragma("unroll") for (int m = 0; m < 4; ++m) _Pragma("unroll") for (int k = 0; k < 2; ++k) dst[m][k] = *(const PG8_LAS bf16x8*)(lds + PG8_SA(b, h) + aoff + m * 2048 + k * 1024); } while (0)
; #define PG8_LDB(dst, b, h) do { _Pragma("unroll") for (int n = 0; n < 2; ++n) _Pragma("unroll") for (int k = 0; k < 2; ++k) dst[n][k] = *(const PG8_LAS bf16x8*)(lds + PG8_SB(b, h) + boff + n * 2048 + k * 1024); } while (0)
; #define PG8_MMA(ai, bj, At, Bt) do { __builtin_amdgcn_s_setprio(1); _Pragma("unroll") for (int m = 0; m < 4; ++m) _Pragma("unroll") for (int n = 0; n < 2; ++n) _Pragma("unroll") for (int k = 0; k < 2; ++k) \
;         acc[ai][bj][m][n] = __builtin_amdgcn_mfma_f32_16x16x32_bf16(Bt[n][k], At[m][k], acc[ai][bj][m][n], 0, 0, 0); __builtin_amdgcn_s_setprio(0); } while (0)
; #define PG8_WAIT_V(n) asm volatile("s_waitcnt vmcnt(" #n ")" ::: "memory")
; #define PG8_WAIT_L(n) asm volatile("s_waitcnt lgkmcnt(" #n ")" ::: "memory")
; #define PG8_BAR __builtin_amdgcn_s_barrier()
; #define PG8_SCHED __builtin_amdgcn_sched_barrier(0)
; template <class Epi, class Sched, bool ALIGN_EPI = false, bool SP2 = false, bool ACHUNK = false>
; __device__ __forceinline__ void gemm_phase(PG8_LAS unsigned char* lds, const Gemm g, const Sched& S, const Epi& E) {
;     ...
;         for (int t = 0; t < nt; t += 2) {
;     ...
;             PG8_LDB(B0, 1, 0); PG8_LDB(B1, 1, 1); PG8_SCHED; PG8_LDA(At, 1, 0); PG8_STAGE(PG8_SA(0, 1), a2 + hstepA, voffA);
;             PG8_WAIT_V(8); PG8_WAIT_L(0); PG8_BAR; PG8_MMA(0, 0, At, B0); PG8_MMA(0, 1, At, B1); PG8_BAR; PG8_SCHED;
;             PG8_LDA(At, 1, 1); PG8_STAGE(PG8_SB(1, 0), b3, voffB); PG8_STAGE(PG8_SB(1, 1), b3 + hstepB, voffB); PG8_STAGE(PG8_SA(1, 0), a3, voffA);
;             PG8_WAIT_V(8); PG8_WAIT_L(0); PG8_BAR; PG8_MMA(1, 0, At, B0); PG8_MMA(1, 1, At, B1); PG8_BAR; PG8_SCHED;
.Lpe_join_353:
	s_add_i32 s43, 0, 0x18000
	s_add_i32 s44, 0, 0x1c000
	ds_read_b128 v[154:157], v222 offset:32768
	ds_read_b128 v[158:161], v222 offset:33792
	ds_read_b128 v[162:165], v222 offset:34816
	ds_read_b128 v[166:169], v222 offset:35840
	ds_read_b128 v[170:173], v222 offset:49152
	ds_read_b128 v[174:177], v222 offset:50176
	ds_read_b128 v[178:181], v222 offset:51200
	ds_read_b128 v[182:185], v222 offset:52224
	s_add_u32 s20, s20, s0
	s_addc_u32 s21, s21, s1
	s_mov_b32 m0, s27
	ds_read_b128 v[186:189], v152 offset:32768
	ds_read_b128 v[190:193], v152 offset:33792
	ds_read_b128 v[198:201], v152 offset:34816
	ds_read_b128 v[202:205], v152 offset:35840
	ds_read_b128 v[206:209], v152 offset:36864
	ds_read_b128 v[210:213], v152 offset:37888
	ds_read_b128 v[214:217], v152 offset:38912
	ds_read_b128 v[218:221], v152 offset:39936
	global_load_lds_dwordx4 v132, s[20:21]
	s_mov_b32 m0, s28
	s_nop 0
	global_load_lds_dwordx4 v134, s[20:21]
	s_waitcnt vmcnt(8)
	s_waitcnt lgkmcnt(0)
	s_barrier
	s_setprio 1
	v_mfma_f32_16x16x32_bf16 v[124:127], v[154:157], v[186:189], v[124:127]
	v_mfma_f32_16x16x32_bf16 v[128:131], v[162:165], v[186:189], v[128:131]
	v_mfma_f32_16x16x32_bf16 v[112:115], v[154:157], v[198:201], v[112:115]
	v_mfma_f32_16x16x32_bf16 v[108:111], v[162:165], v[198:201], v[108:111]
	v_mfma_f32_16x16x32_bf16 v[96:99], v[154:157], v[206:209], v[96:99]
	v_mfma_f32_16x16x32_bf16 v[92:95], v[162:165], v[206:209], v[92:95]
	v_mfma_f32_16x16x32_bf16 v[80:83], v[154:157], v[214:217], v[80:83]
	v_mfma_f32_16x16x32_bf16 v[76:79], v[162:165], v[214:217], v[76:79]
	v_mfma_f32_16x16x32_bf16 v[124:127], v[158:161], v[190:193], v[124:127]
	v_mfma_f32_16x16x32_bf16 v[128:131], v[166:169], v[190:193], v[128:131]
	v_mfma_f32_16x16x32_bf16 v[112:115], v[158:161], v[202:205], v[112:115]
	v_mfma_f32_16x16x32_bf16 v[108:111], v[166:169], v[202:205], v[108:111]
	v_mfma_f32_16x16x32_bf16 v[96:99], v[158:161], v[210:213], v[96:99]
	v_mfma_f32_16x16x32_bf16 v[92:95], v[166:169], v[210:213], v[92:95]
	v_mfma_f32_16x16x32_bf16 v[80:83], v[158:161], v[218:221], v[80:83]
	v_mfma_f32_16x16x32_bf16 v[76:79], v[166:169], v[218:221], v[76:79]
	s_setprio 0
	s_setprio 1
	v_mfma_f32_16x16x32_bf16 v[120:123], v[170:173], v[186:189], v[120:123]
	v_mfma_f32_16x16x32_bf16 v[116:119], v[178:181], v[186:189], v[116:119]
	v_mfma_f32_16x16x32_bf16 v[104:107], v[170:173], v[198:201], v[104:107]
	v_mfma_f32_16x16x32_bf16 v[100:103], v[178:181], v[198:201], v[100:103]
	v_mfma_f32_16x16x32_bf16 v[88:91], v[170:173], v[206:209], v[88:91]
	v_mfma_f32_16x16x32_bf16 v[84:87], v[178:181], v[206:209], v[84:87]
	v_mfma_f32_16x16x32_bf16 v[72:75], v[170:173], v[214:217], v[72:75]
	v_mfma_f32_16x16x32_bf16 v[68:71], v[178:181], v[214:217], v[68:71]
	v_mfma_f32_16x16x32_bf16 v[120:123], v[174:177], v[190:193], v[120:123]
	v_mfma_f32_16x16x32_bf16 v[116:119], v[182:185], v[190:193], v[116:119]
	v_mfma_f32_16x16x32_bf16 v[104:107], v[174:177], v[202:205], v[104:107]
	v_mfma_f32_16x16x32_bf16 v[100:103], v[182:185], v[202:205], v[100:103]
	v_mfma_f32_16x16x32_bf16 v[88:91], v[174:177], v[210:213], v[88:91]
	v_mfma_f32_16x16x32_bf16 v[84:87], v[182:185], v[210:213], v[84:87]
	v_mfma_f32_16x16x32_bf16 v[72:75], v[174:177], v[218:221], v[72:75]
	v_mfma_f32_16x16x32_bf16 v[68:71], v[182:185], v[218:221], v[68:71]
	s_setprio 0
	s_barrier
	s_add_u32 vcc_lo, vcc_lo, s10
	s_addc_u32 vcc_hi, vcc_hi, s11
	s_add_u32 s98, s98, s10
	s_addc_u32 s99, s99, s11
	s_sub_u32 s20, s20, s0
	s_subb_u32 s21, s21, s1
	s_add_u32 s20, s20, s10
	s_addc_u32 s21, s21, s11
	s_add_i32 m0, s43, s24
	ds_read_b128 v[186:189], v152 offset:49152
	ds_read_b128 v[190:193], v152 offset:50176
	ds_read_b128 v[198:201], v152 offset:51200
	ds_read_b128 v[202:205], v152 offset:52224
	ds_read_b128 v[206:209], v152 offset:53248
	ds_read_b128 v[210:213], v152 offset:54272
	ds_read_b128 v[214:217], v152 offset:55296
	ds_read_b128 v[218:221], v152 offset:56320
	global_load_lds_dwordx4 v2, s[98:99]
	s_add_i32 m0, m0, 0x2000
	s_nop 0
	global_load_lds_dwordx4 v136, s[98:99]
	s_add_i32 m0, s44, s24
	s_nop 0
	global_load_lds_dwordx4 v2, vcc
	s_add_i32 m0, m0, 0x2000
	s_nop 0
	global_load_lds_dwordx4 v136, vcc
	s_mov_b32 m0, s29
	s_nop 0
	global_load_lds_dwordx4 v132, s[20:21]
	s_mov_b32 m0, s30
	s_nop 0
	global_load_lds_dwordx4 v134, s[20:21]
	s_waitcnt vmcnt(8)
	s_waitcnt lgkmcnt(0)
	s_barrier
	s_setprio 1
	v_mfma_f32_16x16x32_bf16 v[64:67], v[154:157], v[186:189], v[64:67]
	v_mfma_f32_16x16x32_bf16 v[60:63], v[162:165], v[186:189], v[60:63]
	v_mfma_f32_16x16x32_bf16 v[48:51], v[154:157], v[198:201], v[48:51]
	v_mfma_f32_16x16x32_bf16 v[44:47], v[162:165], v[198:201], v[44:47]
	v_mfma_f32_16x16x32_bf16 v[32:35], v[154:157], v[206:209], v[32:35]
	v_mfma_f32_16x16x32_bf16 v[28:31], v[162:165], v[206:209], v[28:31]
	v_mfma_f32_16x16x32_bf16 v[16:19], v[154:157], v[214:217], v[16:19]
	v_mfma_f32_16x16x32_bf16 v[12:15], v[162:165], v[214:217], v[12:15]
	v_mfma_f32_16x16x32_bf16 v[64:67], v[158:161], v[190:193], v[64:67]
	v_mfma_f32_16x16x32_bf16 v[60:63], v[166:169], v[190:193], v[60:63]
	v_mfma_f32_16x16x32_bf16 v[48:51], v[158:161], v[202:205], v[48:51]
	v_mfma_f32_16x16x32_bf16 v[44:47], v[166:169], v[202:205], v[44:47]
	v_mfma_f32_16x16x32_bf16 v[32:35], v[158:161], v[210:213], v[32:35]
	v_mfma_f32_16x16x32_bf16 v[28:31], v[166:169], v[210:213], v[28:31]
	v_mfma_f32_16x16x32_bf16 v[16:19], v[158:161], v[218:221], v[16:19]
	v_mfma_f32_16x16x32_bf16 v[12:15], v[166:169], v[218:221], v[12:15]
	s_setprio 0
	s_setprio 1
	v_mfma_f32_16x16x32_bf16 v[56:59], v[170:173], v[186:189], v[56:59]
	v_mfma_f32_16x16x32_bf16 v[52:55], v[178:181], v[186:189], v[52:55]
	v_mfma_f32_16x16x32_bf16 v[40:43], v[170:173], v[198:201], v[40:43]
	v_mfma_f32_16x16x32_bf16 v[36:39], v[178:181], v[198:201], v[36:39]
	v_mfma_f32_16x16x32_bf16 v[24:27], v[170:173], v[206:209], v[24:27]
	v_mfma_f32_16x16x32_bf16 v[20:23], v[178:181], v[206:209], v[20:23]
	v_mfma_f32_16x16x32_bf16 v[8:11], v[170:173], v[214:217], v[8:11]
	v_mfma_f32_16x16x32_bf16 v[4:7], v[178:181], v[214:217], v[4:7]
	v_mfma_f32_16x16x32_bf16 v[56:59], v[174:177], v[190:193], v[56:59]
	v_mfma_f32_16x16x32_bf16 v[52:55], v[182:185], v[190:193], v[52:55]
	v_mfma_f32_16x16x32_bf16 v[40:43], v[174:177], v[202:205], v[40:43]
	v_mfma_f32_16x16x32_bf16 v[36:39], v[182:185], v[202:205], v[36:39]
	v_mfma_f32_16x16x32_bf16 v[24:27], v[174:177], v[210:213], v[24:27]
	v_mfma_f32_16x16x32_bf16 v[20:23], v[182:185], v[210:213], v[20:23]
	v_mfma_f32_16x16x32_bf16 v[8:11], v[174:177], v[218:221], v[8:11]
	v_mfma_f32_16x16x32_bf16 v[4:7], v[182:185], v[218:221], v[4:7]
	s_setprio 0
	s_barrier
	s_add_u32 s40, s40, 0x100
	s_addc_u32 s41, s41, 0
	s_add_u32 s18, s18, 0x100
	s_addc_u32 s19, s19, 0
	s_cmp_ge_i32 s42, s31
	s_mov_b32 s20, s42
	s_cbranch_scc0 .LBB0_353
	s_branch .LBB0_342

; #define PG8_STAGE(bufoff, gbase, voff) do { _Pragma("unroll") for (int _i = 0; _i < 2; ++_i) \
;         __builtin_amdgcn_global_load_lds((const unsigned*)((const char*)(gbase) + (voff)[_i]), (PG8_LAS unsigned*)(lds + (bufoff) + ldsw + _i * 8192), 16, 0, 0); } while (0)
; #define PG8_LDA(dst, b, h) do { _Pragma("unroll") for (int m = 0; m < 4; ++m) _Pragma("unroll") for (int k = 0; k < 2; ++k) dst[m][k] = *(const PG8_LAS bf16x8*)(lds + PG8_SA(b, h) + aoff + m * 2048 + k * 1024); } while (0)
; #define PG8_LDB(dst, b, h) do { _Pragma("unroll") for (int n = 0; n < 2; ++n) _Pragma("unroll") for (int k = 0; k < 2; ++k) dst[n][k] = *(const PG8_LAS bf16x8*)(lds + PG8_SB(b, h) + boff + n * 2048 + k * 1024); } while (0)
; #define PG8_WAIT_V(n) asm volatile("s_waitcnt vmcnt(" #n ")" ::: "memory")
; #define PG8_WAIT_L(n) asm volatile("s_waitcnt lgkmcnt(" #n ")" ::: "memory")
; template <class Epi, class Sched, bool ALIGN_EPI = false, bool SP2 = false, bool ACHUNK = false>
; __device__ __forceinline__ void gemm_phase(PG8_LAS unsigned char* lds, const Gemm g, const Sched& S, const Epi& E) {
;     ...
;         const bool has_next = S.next(ui + 1, nxt);
;         const char* nA = has_next ? (const char*)g.A + (size_t)nxt.pm * tstepA : cA; const char* nB = has_next ? (const char*)g.Bt + (size_t)nxt.pn * tstepB : cB;
;         for (int t = 0; t < nt; t += 2) {
;             const bool last = (t == nt - 2);
;             if constexpr (Epi::HAS_MID) { if (t == Epi::MID_T) E.mid(acc, cur, wr, wc, fr, fq, ShflDev{}); }
;             const char* a1 = cA + (size_t)(t + 1) * kstep;
;             const char* a2 = last ? nA : cA + (size_t)(t + 2) * kstep; const char* b2 = last ? nB : cB + (size_t)(t + 2) * kstep;
;             const char* a3 = a2 + kstep; const char* b3 = b2 + kstep;
;             if (last && has_next) S.a_ready(nxt);
;             if constexpr (SP2) {
;             PG8_LDB(B0, 0, 0); PG8_LDB(B1, 0, 1); PG8_SCHED; PG8_LDA(At, 0, 0); PG8_STAGE(PG8_SA(1, 1), a1 + hstepA, voffA);
;             PG8_WAIT_V(8); PG8_WAIT_L(0); PG8_BAR; PG8_MMA(0, 0, At, B0); PG8_MMA(0, 1, At, B1); PG8_BAR; PG8_SCHED;
;             PG8_LDA(At, 0, 1); PG8_STAGE(PG8_SB(0, 0), b2, voffB); PG8_STAGE(PG8_SB(0, 1), b2 + hstepB, voffB); PG8_STAGE(PG8_SA(0, 0), a2, voffA);
;             PG8_WAIT_V(8); PG8_WAIT_L(0); PG8_BAR; PG8_MMA(1, 0, At, B0); PG8_MMA(1, 1, At, B1); PG8_BAR; PG8_SCHED;
.LBB0_375:
	s_andn2_b64 vcc, exec, s[34:35]
	s_cbranch_vccnz .LBB0_379
	s_add_u32 s4, s4, 0x80
	s_addc_u32 s5, s5, 0
	s_add_u32 s8, s6, 0x100
	s_addc_u32 s9, s7, 0
	s_mov_b32 s6, 0
	v_add_u32_e32 v192, 0x10000, v175
	s_add_i32 s48, s6, 2
	s_add_u32 s49, s4, 0x80
	s_addc_u32 s7, s5, 0
	s_add_i32 s52, 0, 0x10000
	s_cmp_eq_u32 s27, s6
	s_cselect_b32 s7, s1, s7
	s_cselect_b32 s6, s0, s49
	s_cselect_b32 s51, s43, s9
	s_cselect_b32 s50, s42, s8
	s_add_i32 s49, 0, 0x14000
	s_waitcnt lgkmcnt(0)
	ds_read_b128 v[146:149], v192
	ds_read_b128 v[150:153], v192 offset:1024
	ds_read_b128 v[154:157], v192 offset:2048
	ds_read_b128 v[158:161], v192 offset:3072
	ds_read_b128 v[162:165], v192 offset:16384
	ds_read_b128 v[166:169], v192 offset:17408
	ds_read_b128 v[170:173], v192 offset:18432
	ds_read_b128 v[180:183], v192 offset:19456
	s_add_i32 m0, s20, 0xc000
	ds_read_b128 v[184:187], v179
	ds_read_b128 v[188:191], v179 offset:1024
	ds_read_b128 v[198:201], v179 offset:2048
	ds_read_b128 v[202:205], v179 offset:3072
	ds_read_b128 v[206:209], v179 offset:4096
	ds_read_b128 v[210:213], v179 offset:5120
	ds_read_b128 v[214:217], v179 offset:6144
	ds_read_b128 v[218:221], v179 offset:7168
	global_load_lds_dwordx4 v142, s[4:5]
	s_add_i32 m0, s20, 0xe000
	s_nop 0
	global_load_lds_dwordx4 v144, s[4:5]
	s_waitcnt vmcnt(8)
	s_waitcnt lgkmcnt(0)
	s_barrier
	s_setprio 1
	v_mfma_f32_16x16x32_bf16 v[124:127], v[146:149], v[184:187], 0
	v_mfma_f32_16x16x32_bf16 v[116:119], v[154:157], v[184:187], 0
	v_mfma_f32_16x16x32_bf16 v[108:111], v[146:149], v[198:201], 0
	v_mfma_f32_16x16x32_bf16 v[100:103], v[154:157], v[198:201], 0
	v_mfma_f32_16x16x32_bf16 v[92:95], v[146:149], v[206:209], 0
	v_mfma_f32_16x16x32_bf16 v[84:87], v[154:157], v[206:209], 0
	v_mfma_f32_16x16x32_bf16 v[76:79], v[146:149], v[214:217], 0
	v_mfma_f32_16x16x32_bf16 v[68:71], v[154:157], v[214:217], 0
	v_mfma_f32_16x16x32_bf16 v[124:127], v[150:153], v[188:191], v[124:127]
	v_mfma_f32_16x16x32_bf16 v[116:119], v[158:161], v[188:191], v[116:119]
	v_mfma_f32_16x16x32_bf16 v[108:111], v[150:153], v[202:205], v[108:111]
	v_mfma_f32_16x16x32_bf16 v[100:103], v[158:161], v[202:205], v[100:103]
	v_mfma_f32_16x16x32_bf16 v[92:95], v[150:153], v[210:213], v[92:95]
	v_mfma_f32_16x16x32_bf16 v[84:87], v[158:161], v[210:213], v[84:87]
	v_mfma_f32_16x16x32_bf16 v[76:79], v[150:153], v[218:221], v[76:79]
	v_mfma_f32_16x16x32_bf16 v[68:71], v[158:161], v[218:221], v[68:71]
	s_setprio 0
	s_setprio 1
	v_mfma_f32_16x16x32_bf16 v[128:131], v[162:165], v[184:187], 0
	v_mfma_f32_16x16x32_bf16 v[120:123], v[170:173], v[184:187], 0
	v_mfma_f32_16x16x32_bf16 v[112:115], v[162:165], v[198:201], 0
	v_mfma_f32_16x16x32_bf16 v[104:107], v[170:173], v[198:201], 0
	v_mfma_f32_16x16x32_bf16 v[96:99], v[162:165], v[206:209], 0
	v_mfma_f32_16x16x32_bf16 v[88:91], v[170:173], v[206:209], 0
	v_mfma_f32_16x16x32_bf16 v[80:83], v[162:165], v[214:217], 0
	v_mfma_f32_16x16x32_bf16 v[72:75], v[170:173], v[214:217], 0
	v_mfma_f32_16x16x32_bf16 v[128:131], v[166:169], v[188:191], v[128:131]
	v_mfma_f32_16x16x32_bf16 v[120:123], v[180:183], v[188:191], v[120:123]
	v_mfma_f32_16x16x32_bf16 v[112:115], v[166:169], v[202:205], v[112:115]
	v_mfma_f32_16x16x32_bf16 v[104:107], v[180:183], v[202:205], v[104:107]
	v_mfma_f32_16x16x32_bf16 v[96:99], v[166:169], v[210:213], v[96:99]
	v_mfma_f32_16x16x32_bf16 v[88:91], v[180:183], v[210:213], v[88:91]
	v_mfma_f32_16x16x32_bf16 v[80:83], v[166:169], v[218:221], v[80:83]
	v_mfma_f32_16x16x32_bf16 v[72:75], v[180:183], v[218:221], v[72:75]
	s_setprio 0
	s_barrier
	s_add_i32 s52, s52, s13
	s_mov_b32 m0, s52
	ds_read_b128 v[184:187], v179 offset:16384
	ds_read_b128 v[188:191], v179 offset:17408
	ds_read_b128 v[198:201], v179 offset:18432
	ds_read_b128 v[202:205], v179 offset:19456
	ds_read_b128 v[206:209], v179 offset:20480
	ds_read_b128 v[210:213], v179 offset:21504
	ds_read_b128 v[214:217], v179 offset:22528
	ds_read_b128 v[218:221], v179 offset:23552
	global_load_lds_dwordx4 v134, s[50:51]
	s_add_i32 m0, s52, 0x2000
	s_add_i32 s49, s49, s13
	global_load_lds_dwordx4 v138, s[50:51]
	s_add_u32 s50, s50, s18
	s_addc_u32 s51, s51, s19
	s_mov_b64 vcc, s[50:51]
	s_sub_u32 s98, s50, s18
	s_subb_u32 s99, s51, s19
	s_mov_b32 m0, s49
	s_nop 0
	global_load_lds_dwordx4 v134, s[50:51]
	s_add_i32 m0, s49, 0x2000
	s_nop 0
	global_load_lds_dwordx4 v138, s[50:51]
	s_mov_b32 m0, s20
	s_nop 0
	global_load_lds_dwordx4 v132, s[6:7]
	s_mov_b32 m0, s21
	s_nop 0
	global_load_lds_dwordx4 v136, s[6:7]
	s_waitcnt vmcnt(8)
	s_waitcnt lgkmcnt(0)
	s_barrier
	s_setprio 1
	v_mfma_f32_16x16x32_bf16 v[60:63], v[146:149], v[184:187], 0
	v_mfma_f32_16x16x32_bf16 v[52:55], v[154:157], v[184:187], 0
	v_mfma_f32_16x16x32_bf16 v[44:47], v[146:149], v[198:201], 0
	v_mfma_f32_16x16x32_bf16 v[36:39], v[154:157], v[198:201], 0
	v_mfma_f32_16x16x32_bf16 v[28:31], v[146:149], v[206:209], 0
	v_mfma_f32_16x16x32_bf16 v[20:23], v[154:157], v[206:209], 0
	v_mfma_f32_16x16x32_bf16 v[12:15], v[146:149], v[214:217], 0
	v_mfma_f32_16x16x32_bf16 v[4:7], v[154:157], v[214:217], 0
	v_mfma_f32_16x16x32_bf16 v[60:63], v[150:153], v[188:191], v[60:63]
	v_mfma_f32_16x16x32_bf16 v[52:55], v[158:161], v[188:191], v[52:55]
	v_mfma_f32_16x16x32_bf16 v[44:47], v[150:153], v[202:205], v[44:47]
	v_mfma_f32_16x16x32_bf16 v[36:39], v[158:161], v[202:205], v[36:39]
	v_mfma_f32_16x16x32_bf16 v[28:31], v[150:153], v[210:213], v[28:31]
	v_mfma_f32_16x16x32_bf16 v[20:23], v[158:161], v[210:213], v[20:23]
	v_mfma_f32_16x16x32_bf16 v[12:15], v[150:153], v[218:221], v[12:15]
	v_mfma_f32_16x16x32_bf16 v[4:7], v[158:161], v[218:221], v[4:7]
	s_setprio 0
	s_setprio 1
	v_mfma_f32_16x16x32_bf16 v[64:67], v[162:165], v[184:187], 0
	v_mfma_f32_16x16x32_bf16 v[56:59], v[170:173], v[184:187], 0
	v_mfma_f32_16x16x32_bf16 v[48:51], v[162:165], v[198:201], 0
	v_mfma_f32_16x16x32_bf16 v[40:43], v[170:173], v[198:201], 0
	v_mfma_f32_16x16x32_bf16 v[32:35], v[162:165], v[206:209], 0
	v_mfma_f32_16x16x32_bf16 v[24:27], v[170:173], v[206:209], 0
	v_mfma_f32_16x16x32_bf16 v[16:19], v[162:165], v[214:217], 0
	v_mfma_f32_16x16x32_bf16 v[8:11], v[170:173], v[214:217], 0
	v_mfma_f32_16x16x32_bf16 v[64:67], v[166:169], v[188:191], v[64:67]
	v_mfma_f32_16x16x32_bf16 v[56:59], v[180:183], v[188:191], v[56:59]
	v_mfma_f32_16x16x32_bf16 v[48:51], v[166:169], v[202:205], v[48:51]
	v_mfma_f32_16x16x32_bf16 v[40:43], v[180:183], v[202:205], v[40:43]
	v_mfma_f32_16x16x32_bf16 v[32:35], v[166:169], v[210:213], v[32:35]
	v_mfma_f32_16x16x32_bf16 v[24:27], v[180:183], v[210:213], v[24:27]
	v_mfma_f32_16x16x32_bf16 v[16:19], v[166:169], v[218:221], v[16:19]
	v_mfma_f32_16x16x32_bf16 v[8:11], v[180:183], v[218:221], v[8:11]
	s_setprio 0
	s_barrier
	s_branch .Lpe_join_377
; #define PG8_STAGE(bufoff, gbase, voff) do { _Pragma("unroll") for (int _i = 0; _i < 2; ++_i) \
;         __builtin_amdgcn_global_load_lds((const unsigned*)((const char*)(gbase) + (voff)[_i]), (PG8_LAS unsigned*)(lds + (bufoff) + ldsw + _i * 8192), 16, 0, 0); } while (0)
; #define PG8_LDA(dst, b, h) do { _Pragma("unroll") for (int m = 0; m < 4; ++m) _Pragma("unroll") for (int k = 0; k < 2; ++k) dst[m][k] = *(const PG8_LAS bf16x8*)(lds + PG8_SA(b, h) + aoff + m * 2048 + k * 1024); } while (0)
; #define PG8_LDB(dst, b, h) do { _Pragma("unroll") for (int n = 0; n < 2; ++n) _Pragma("unroll") for (int k = 0; k < 2; ++k) dst[n][k] = *(const PG8_LAS bf16x8*)(lds + PG8_SB(b, h) + boff + n * 2048 + k * 1024); } while (0)
; #define PG8_MMA(ai, bj, At, Bt) do { __builtin_amdgcn_s_setprio(1); _Pragma("unroll") for (int m = 0; m < 4; ++m) _Pragma("unroll") for (int n = 0; n < 2; ++n) _Pragma("unroll") for (int k = 0; k < 2; ++k) \
;         acc[ai][bj][m][n] = __builtin_amdgcn_mfma_f32_16x16x32_bf16(Bt[n][k], At[m][k], acc[ai][bj][m][n], 0, 0, 0); __builtin_amdgcn_s_setprio(0); } while (0)
; #define PG8_WAIT_V(n) asm volatile("s_waitcnt vmcnt(" #n ")" ::: "memory")
; #define PG8_WAIT_L(n) asm volatile("s_waitcnt lgkmcnt(" #n ")" ::: "memory")
; #define PG8_BAR __builtin_amdgcn_s_barrier()
; #define PG8_SCHED __builtin_amdgcn_sched_barrier(0)
; template <class Epi, class Sched, bool ALIGN_EPI = false, bool SP2 = false, bool ACHUNK = false>
; __device__ __forceinline__ void gemm_phase(PG8_LAS unsigned char* lds, const Gemm g, const Sched& S, const Epi& E) {
;     ...
;             PG8_LDB(B0, 0, 0); PG8_LDB(B1, 0, 1); PG8_SCHED; PG8_LDA(At, 0, 0); PG8_STAGE(PG8_SA(1, 1), a1 + hstepA, voffA);
;             PG8_WAIT_V(8); PG8_WAIT_L(0); PG8_BAR; PG8_MMA(0, 0, At, B0); PG8_MMA(0, 1, At, B1); PG8_BAR; PG8_SCHED;
;             PG8_LDA(At, 0, 1); PG8_STAGE(PG8_SB(0, 0), b2, voffB); PG8_STAGE(PG8_SB(0, 1), b2 + hstepB, voffB); PG8_STAGE(PG8_SA(0, 0), a2, voffA);
;             PG8_WAIT_V(8); PG8_WAIT_L(0); PG8_BAR; PG8_MMA(1, 0, At, B0); PG8_MMA(1, 1, At, B1); PG8_BAR; PG8_SCHED;
.LBB0_377:
	s_add_i32 s48, s6, 2
	s_add_u32 s49, s4, 0x80
	s_addc_u32 s7, s5, 0
	s_add_i32 s52, 0, 0x10000
	s_cmp_eq_u32 s27, s6
	s_cselect_b32 s7, s1, s7
	s_cselect_b32 s6, s0, s49
	s_cselect_b32 s51, s43, s9
	s_cselect_b32 s50, s42, s8
	s_add_i32 s49, 0, 0x14000
	s_waitcnt lgkmcnt(0)
	ds_read_b128 v[146:149], v192
	ds_read_b128 v[150:153], v192 offset:1024
	ds_read_b128 v[154:157], v192 offset:2048
	ds_read_b128 v[158:161], v192 offset:3072
	ds_read_b128 v[162:165], v192 offset:16384
	ds_read_b128 v[166:169], v192 offset:17408
	ds_read_b128 v[170:173], v192 offset:18432
	ds_read_b128 v[180:183], v192 offset:19456
	s_add_i32 m0, s20, 0xc000
	ds_read_b128 v[184:187], v179
	ds_read_b128 v[188:191], v179 offset:1024
	ds_read_b128 v[198:201], v179 offset:2048
	ds_read_b128 v[202:205], v179 offset:3072
	ds_read_b128 v[206:209], v179 offset:4096
	ds_read_b128 v[210:213], v179 offset:5120
	ds_read_b128 v[214:217], v179 offset:6144
	ds_read_b128 v[218:221], v179 offset:7168
	global_load_lds_dwordx4 v142, s[4:5]
	s_add_i32 m0, s20, 0xe000
	s_nop 0
	global_load_lds_dwordx4 v144, s[4:5]
	s_waitcnt vmcnt(8)
	s_waitcnt lgkmcnt(0)
	s_barrier
	s_setprio 1
	v_mfma_f32_16x16x32_bf16 v[124:127], v[146:149], v[184:187], v[124:127]
	v_mfma_f32_16x16x32_bf16 v[116:119], v[154:157], v[184:187], v[116:119]
	v_mfma_f32_16x16x32_bf16 v[108:111], v[146:149], v[198:201], v[108:111]
	v_mfma_f32_16x16x32_bf16 v[100:103], v[154:157], v[198:201], v[100:103]
	v_mfma_f32_16x16x32_bf16 v[92:95], v[146:149], v[206:209], v[92:95]
	v_mfma_f32_16x16x32_bf16 v[84:87], v[154:157], v[206:209], v[84:87]
	v_mfma_f32_16x16x32_bf16 v[76:79], v[146:149], v[214:217], v[76:79]
	v_mfma_f32_16x16x32_bf16 v[68:71], v[154:157], v[214:217], v[68:71]
	v_mfma_f32_16x16x32_bf16 v[124:127], v[150:153], v[188:191], v[124:127]
	v_mfma_f32_16x16x32_bf16 v[116:119], v[158:161], v[188:191], v[116:119]
	v_mfma_f32_16x16x32_bf16 v[108:111], v[150:153], v[202:205], v[108:111]
	v_mfma_f32_16x16x32_bf16 v[100:103], v[158:161], v[202:205], v[100:103]
	v_mfma_f32_16x16x32_bf16 v[92:95], v[150:153], v[210:213], v[92:95]
	v_mfma_f32_16x16x32_bf16 v[84:87], v[158:161], v[210:213], v[84:87]
	v_mfma_f32_16x16x32_bf16 v[76:79], v[150:153], v[218:221], v[76:79]
	v_mfma_f32_16x16x32_bf16 v[68:71], v[158:161], v[218:221], v[68:71]
	s_setprio 0
	s_setprio 1
	v_mfma_f32_16x16x32_bf16 v[128:131], v[162:165], v[184:187], v[128:131]
	v_mfma_f32_16x16x32_bf16 v[120:123], v[170:173], v[184:187], v[120:123]
	v_mfma_f32_16x16x32_bf16 v[112:115], v[162:165], v[198:201], v[112:115]
	v_mfma_f32_16x16x32_bf16 v[104:107], v[170:173], v[198:201], v[104:107]
	v_mfma_f32_16x16x32_bf16 v[96:99], v[162:165], v[206:209], v[96:99]
	v_mfma_f32_16x16x32_bf16 v[88:91], v[170:173], v[206:209], v[88:91]
	v_mfma_f32_16x16x32_bf16 v[80:83], v[162:165], v[214:217], v[80:83]
	v_mfma_f32_16x16x32_bf16 v[72:75], v[170:173], v[214:217], v[72:75]
	v_mfma_f32_16x16x32_bf16 v[128:131], v[166:169], v[188:191], v[128:131]
	v_mfma_f32_16x16x32_bf16 v[120:123], v[180:183], v[188:191], v[120:123]
	v_mfma_f32_16x16x32_bf16 v[112:115], v[166:169], v[202:205], v[112:115]
	v_mfma_f32_16x16x32_bf16 v[104:107], v[180:183], v[202:205], v[104:107]
	v_mfma_f32_16x16x32_bf16 v[96:99], v[166:169], v[210:213], v[96:99]
	v_mfma_f32_16x16x32_bf16 v[88:91], v[180:183], v[210:213], v[88:91]
	v_mfma_f32_16x16x32_bf16 v[80:83], v[166:169], v[218:221], v[80:83]
	v_mfma_f32_16x16x32_bf16 v[72:75], v[180:183], v[218:221], v[72:75]
	s_setprio 0
	s_barrier
	s_add_i32 s52, s52, s13
	s_mov_b32 m0, s52
	ds_read_b128 v[184:187], v179 offset:16384
	ds_read_b128 v[188:191], v179 offset:17408
	ds_read_b128 v[198:201], v179 offset:18432
	ds_read_b128 v[202:205], v179 offset:19456
	ds_read_b128 v[206:209], v179 offset:20480
	ds_read_b128 v[210:213], v179 offset:21504
	ds_read_b128 v[214:217], v179 offset:22528
	ds_read_b128 v[218:221], v179 offset:23552
	global_load_lds_dwordx4 v134, s[50:51]
	s_add_i32 m0, s52, 0x2000
	s_add_i32 s49, s49, s13
	global_load_lds_dwordx4 v138, s[50:51]
	s_add_u32 s50, s50, s18
	s_addc_u32 s51, s51, s19
	s_mov_b64 vcc, s[50:51]
	s_sub_u32 s98, s50, s18
	s_subb_u32 s99, s51, s19
	s_mov_b32 m0, s49
	s_nop 0
	global_load_lds_dwordx4 v134, s[50:51]
	s_add_i32 m0, s49, 0x2000
	s_nop 0
	global_load_lds_dwordx4 v138, s[50:51]
	s_mov_b32 m0, s20
	s_nop 0
	global_load_lds_dwordx4 v132, s[6:7]
	s_mov_b32 m0, s21
	s_nop 0
	global_load_lds_dwordx4 v136, s[6:7]
	s_waitcnt vmcnt(8)
	s_waitcnt lgkmcnt(0)
	s_barrier
	s_setprio 1
	v_mfma_f32_16x16x32_bf16 v[60:63], v[146:149], v[184:187], v[60:63]
	v_mfma_f32_16x16x32_bf16 v[52:55], v[154:157], v[184:187], v[52:55]
	v_mfma_f32_16x16x32_bf16 v[44:47], v[146:149], v[198:201], v[44:47]
	v_mfma_f32_16x16x32_bf16 v[36:39], v[154:157], v[198:201], v[36:39]
	v_mfma_f32_16x16x32_bf16 v[28:31], v[146:149], v[206:209], v[28:31]
	v_mfma_f32_16x16x32_bf16 v[20:23], v[154:157], v[206:209], v[20:23]
	v_mfma_f32_16x16x32_bf16 v[12:15], v[146:149], v[214:217], v[12:15]
	v_mfma_f32_16x16x32_bf16 v[4:7], v[154:157], v[214:217], v[4:7]
	v_mfma_f32_16x16x32_bf16 v[60:63], v[150:153], v[188:191], v[60:63]
	v_mfma_f32_16x16x32_bf16 v[52:55], v[158:161], v[188:191], v[52:55]
	v_mfma_f32_16x16x32_bf16 v[44:47], v[150:153], v[202:205], v[44:47]
	v_mfma_f32_16x16x32_bf16 v[36:39], v[158:161], v[202:205], v[36:39]
	v_mfma_f32_16x16x32_bf16 v[28:31], v[150:153], v[210:213], v[28:31]
	v_mfma_f32_16x16x32_bf16 v[20:23], v[158:161], v[210:213], v[20:23]
	v_mfma_f32_16x16x32_bf16 v[12:15], v[150:153], v[218:221], v[12:15]
	v_mfma_f32_16x16x32_bf16 v[4:7], v[158:161], v[218:221], v[4:7]
	s_setprio 0
	s_setprio 1
	v_mfma_f32_16x16x32_bf16 v[64:67], v[162:165], v[184:187], v[64:67]
	v_mfma_f32_16x16x32_bf16 v[56:59], v[170:173], v[184:187], v[56:59]
	v_mfma_f32_16x16x32_bf16 v[48:51], v[162:165], v[198:201], v[48:51]
	v_mfma_f32_16x16x32_bf16 v[40:43], v[170:173], v[198:201], v[40:43]
	v_mfma_f32_16x16x32_bf16 v[32:35], v[162:165], v[206:209], v[32:35]
	v_mfma_f32_16x16x32_bf16 v[24:27], v[170:173], v[206:209], v[24:27]
	v_mfma_f32_16x16x32_bf16 v[16:19], v[162:165], v[214:217], v[16:19]
	v_mfma_f32_16x16x32_bf16 v[8:11], v[170:173], v[214:217], v[8:11]
	v_mfma_f32_16x16x32_bf16 v[64:67], v[166:169], v[188:191], v[64:67]
	v_mfma_f32_16x16x32_bf16 v[56:59], v[180:183], v[188:191], v[56:59]
	v_mfma_f32_16x16x32_bf16 v[48:51], v[166:169], v[202:205], v[48:51]
	v_mfma_f32_16x16x32_bf16 v[40:43], v[180:183], v[202:205], v[40:43]
	v_mfma_f32_16x16x32_bf16 v[32:35], v[166:169], v[210:213], v[32:35]
	v_mfma_f32_16x16x32_bf16 v[24:27], v[180:183], v[210:213], v[24:27]
	v_mfma_f32_16x16x32_bf16 v[16:19], v[166:169], v[218:221], v[16:19]
	v_mfma_f32_16x16x32_bf16 v[8:11], v[180:183], v[218:221], v[8:11]
	s_setprio 0
	s_barrier
; #define PG8_STAGE(bufoff, gbase, voff) do { _Pragma("unroll") for (int _i = 0; _i < 2; ++_i) \
;         __builtin_amdgcn_global_load_lds((const unsigned*)((const char*)(gbase) + (voff)[_i]), (PG8_LAS unsigned*)(lds + (bufoff) + ldsw + _i * 8192), 16, 0, 0); } while (0)
; #define PG8_LDA(dst, b, h) do { _Pragma("unroll") for (int m = 0; m < 4; ++m) _Pragma("unroll") for (int k = 0; k < 2; ++k) dst[m][k] = *(const PG8_LAS bf16x8*)(lds + PG8_SA(b, h) + aoff + m * 2048 + k * 1024); } while (0)
; #define PG8_LDB(dst, b, h) do { _Pragma("unroll") for (int n = 0; n < 2; ++n) _Pragma("unroll") for (int k = 0; k < 2; ++k) dst[n][k] = *(const PG8_LAS bf16x8*)(lds + PG8_SB(b, h) + boff + n * 2048 + k * 1024); } while (0)
; #define PG8_MMA(ai, bj, At, Bt) do { __builtin_amdgcn_s_setprio(1); _Pragma("unroll") for (int m = 0; m < 4; ++m) _Pragma("unroll") for (int n = 0; n < 2; ++n) _Pragma("unroll") for (int k = 0; k < 2; ++k) \
;         acc[ai][bj][m][n] = __builtin_amdgcn_mfma_f32_16x16x32_bf16(Bt[n][k], At[m][k], acc[ai][bj][m][n], 0, 0, 0); __builtin_amdgcn_s_setprio(0); } while (0)
; #define PG8_WAIT_V(n) asm volatile("s_waitcnt vmcnt(" #n ")" ::: "memory")
; #define PG8_WAIT_L(n) asm volatile("s_waitcnt lgkmcnt(" #n ")" ::: "memory")
; #define PG8_BAR __builtin_amdgcn_s_barrier()
; #define PG8_SCHED __builtin_amdgcn_sched_barrier(0)
; template <class Epi, class Sched, bool ALIGN_EPI = false, bool SP2 = false, bool ACHUNK = false>
; __device__ __forceinline__ void gemm_phase(PG8_LAS unsigned char* lds, const Gemm g, const Sched& S, const Epi& E) {
;     ...
;         for (int t = 0; t < nt; t += 2) {
;     ...
;             PG8_LDB(B0, 1, 0); PG8_LDB(B1, 1, 1); PG8_SCHED; PG8_LDA(At, 1, 0); PG8_STAGE(PG8_SA(0, 1), a2 + hstepA, voffA);
;             PG8_WAIT_V(8); PG8_WAIT_L(0); PG8_BAR; PG8_MMA(0, 0, At, B0); PG8_MMA(0, 1, At, B1); PG8_BAR; PG8_SCHED;
;             PG8_LDA(At, 1, 1); PG8_STAGE(PG8_SB(1, 0), b3, voffB); PG8_STAGE(PG8_SB(1, 1), b3 + hstepB, voffB); PG8_STAGE(PG8_SA(1, 0), a3, voffA);
;             PG8_WAIT_V(8); PG8_WAIT_L(0); PG8_BAR; PG8_MMA(1, 0, At, B0); PG8_MMA(1, 1, At, B1); PG8_BAR; PG8_SCHED;
.Lpe_join_377:
	s_add_i32 s49, 0, 0x18000
	s_add_i32 s50, 0, 0x1c000
	ds_read_b128 v[146:149], v192 offset:32768
	ds_read_b128 v[150:153], v192 offset:33792
	ds_read_b128 v[154:157], v192 offset:34816
	ds_read_b128 v[158:161], v192 offset:35840
	ds_read_b128 v[162:165], v192 offset:49152
	ds_read_b128 v[166:169], v192 offset:50176
	ds_read_b128 v[170:173], v192 offset:51200
	ds_read_b128 v[180:183], v192 offset:52224
	s_add_u32 s6, s6, s18
	s_addc_u32 s7, s7, s19
	s_mov_b32 m0, s22
	ds_read_b128 v[184:187], v179 offset:32768
	ds_read_b128 v[188:191], v179 offset:33792
	ds_read_b128 v[198:201], v179 offset:34816
	ds_read_b128 v[202:205], v179 offset:35840
	ds_read_b128 v[206:209], v179 offset:36864
	ds_read_b128 v[210:213], v179 offset:37888
	ds_read_b128 v[214:217], v179 offset:38912
	ds_read_b128 v[218:221], v179 offset:39936
	global_load_lds_dwordx4 v132, s[6:7]
	s_mov_b32 m0, s23
	s_nop 0
	global_load_lds_dwordx4 v136, s[6:7]
	s_waitcnt vmcnt(8)
	s_waitcnt lgkmcnt(0)
	s_barrier
	s_setprio 1
	v_mfma_f32_16x16x32_bf16 v[124:127], v[146:149], v[184:187], v[124:127]
	v_mfma_f32_16x16x32_bf16 v[116:119], v[154:157], v[184:187], v[116:119]
	v_mfma_f32_16x16x32_bf16 v[108:111], v[146:149], v[198:201], v[108:111]
	v_mfma_f32_16x16x32_bf16 v[100:103], v[154:157], v[198:201], v[100:103]
	v_mfma_f32_16x16x32_bf16 v[92:95], v[146:149], v[206:209], v[92:95]
	v_mfma_f32_16x16x32_bf16 v[84:87], v[154:157], v[206:209], v[84:87]
	v_mfma_f32_16x16x32_bf16 v[76:79], v[146:149], v[214:217], v[76:79]
	v_mfma_f32_16x16x32_bf16 v[68:71], v[154:157], v[214:217], v[68:71]
	v_mfma_f32_16x16x32_bf16 v[124:127], v[150:153], v[188:191], v[124:127]
	v_mfma_f32_16x16x32_bf16 v[116:119], v[158:161], v[188:191], v[116:119]
	v_mfma_f32_16x16x32_bf16 v[108:111], v[150:153], v[202:205], v[108:111]
	v_mfma_f32_16x16x32_bf16 v[100:103], v[158:161], v[202:205], v[100:103]
	v_mfma_f32_16x16x32_bf16 v[92:95], v[150:153], v[210:213], v[92:95]
	v_mfma_f32_16x16x32_bf16 v[84:87], v[158:161], v[210:213], v[84:87]
	v_mfma_f32_16x16x32_bf16 v[76:79], v[150:153], v[218:221], v[76:79]
	v_mfma_f32_16x16x32_bf16 v[68:71], v[158:161], v[218:221], v[68:71]
	s_setprio 0
	s_setprio 1
	v_mfma_f32_16x16x32_bf16 v[128:131], v[162:165], v[184:187], v[128:131]
	v_mfma_f32_16x16x32_bf16 v[120:123], v[170:173], v[184:187], v[120:123]
	v_mfma_f32_16x16x32_bf16 v[112:115], v[162:165], v[198:201], v[112:115]
	v_mfma_f32_16x16x32_bf16 v[104:107], v[170:173], v[198:201], v[104:107]
	v_mfma_f32_16x16x32_bf16 v[96:99], v[162:165], v[206:209], v[96:99]
	v_mfma_f32_16x16x32_bf16 v[88:91], v[170:173], v[206:209], v[88:91]
	v_mfma_f32_16x16x32_bf16 v[80:83], v[162:165], v[214:217], v[80:83]
	v_mfma_f32_16x16x32_bf16 v[72:75], v[170:173], v[214:217], v[72:75]
	v_mfma_f32_16x16x32_bf16 v[128:131], v[166:169], v[188:191], v[128:131]
	v_mfma_f32_16x16x32_bf16 v[120:123], v[180:183], v[188:191], v[120:123]
	v_mfma_f32_16x16x32_bf16 v[112:115], v[166:169], v[202:205], v[112:115]
	v_mfma_f32_16x16x32_bf16 v[104:107], v[180:183], v[202:205], v[104:107]
	v_mfma_f32_16x16x32_bf16 v[96:99], v[166:169], v[210:213], v[96:99]
	v_mfma_f32_16x16x32_bf16 v[88:91], v[180:183], v[210:213], v[88:91]
	v_mfma_f32_16x16x32_bf16 v[80:83], v[166:169], v[218:221], v[80:83]
	v_mfma_f32_16x16x32_bf16 v[72:75], v[180:183], v[218:221], v[72:75]
	s_setprio 0
	s_barrier
	s_add_u32 vcc_lo, vcc_lo, s10
	s_addc_u32 vcc_hi, vcc_hi, s11
	s_add_u32 s98, s98, s10
	s_addc_u32 s99, s99, s11
	s_sub_u32 s6, s6, s18
	s_subb_u32 s7, s7, s19
	s_add_u32 s6, s6, s10
	s_addc_u32 s7, s7, s11
	s_add_i32 m0, s49, s13
	ds_read_b128 v[184:187], v179 offset:49152
	ds_read_b128 v[188:191], v179 offset:50176
	ds_read_b128 v[198:201], v179 offset:51200
	ds_read_b128 v[202:205], v179 offset:52224
	ds_read_b128 v[206:209], v179 offset:53248
	ds_read_b128 v[210:213], v179 offset:54272
	ds_read_b128 v[214:217], v179 offset:55296
	ds_read_b128 v[218:221], v179 offset:56320
	global_load_lds_dwordx4 v134, s[98:99]
	s_add_i32 m0, m0, 0x2000
	s_nop 0
	global_load_lds_dwordx4 v138, s[98:99]
	s_add_i32 m0, s50, s13
	s_nop 0
	global_load_lds_dwordx4 v134, vcc
	s_add_i32 m0, m0, 0x2000
	s_nop 0
	global_load_lds_dwordx4 v138, vcc
	s_mov_b32 m0, s25
	s_nop 0
	global_load_lds_dwordx4 v132, s[6:7]
	s_mov_b32 m0, s26
	s_nop 0
	global_load_lds_dwordx4 v136, s[6:7]
	s_waitcnt vmcnt(8)
	s_waitcnt lgkmcnt(0)
	s_barrier
	s_setprio 1
	v_mfma_f32_16x16x32_bf16 v[60:63], v[146:149], v[184:187], v[60:63]
	v_mfma_f32_16x16x32_bf16 v[52:55], v[154:157], v[184:187], v[52:55]
	v_mfma_f32_16x16x32_bf16 v[44:47], v[146:149], v[198:201], v[44:47]
	v_mfma_f32_16x16x32_bf16 v[36:39], v[154:157], v[198:201], v[36:39]
	v_mfma_f32_16x16x32_bf16 v[28:31], v[146:149], v[206:209], v[28:31]
	v_mfma_f32_16x16x32_bf16 v[20:23], v[154:157], v[206:209], v[20:23]
	v_mfma_f32_16x16x32_bf16 v[12:15], v[146:149], v[214:217], v[12:15]
	v_mfma_f32_16x16x32_bf16 v[4:7], v[154:157], v[214:217], v[4:7]
	v_mfma_f32_16x16x32_bf16 v[60:63], v[150:153], v[188:191], v[60:63]
	v_mfma_f32_16x16x32_bf16 v[52:55], v[158:161], v[188:191], v[52:55]
	v_mfma_f32_16x16x32_bf16 v[44:47], v[150:153], v[202:205], v[44:47]
	v_mfma_f32_16x16x32_bf16 v[36:39], v[158:161], v[202:205], v[36:39]
	v_mfma_f32_16x16x32_bf16 v[28:31], v[150:153], v[210:213], v[28:31]
	v_mfma_f32_16x16x32_bf16 v[20:23], v[158:161], v[210:213], v[20:23]
	v_mfma_f32_16x16x32_bf16 v[12:15], v[150:153], v[218:221], v[12:15]
	v_mfma_f32_16x16x32_bf16 v[4:7], v[158:161], v[218:221], v[4:7]
	s_setprio 0
	s_setprio 1
	v_mfma_f32_16x16x32_bf16 v[64:67], v[162:165], v[184:187], v[64:67]
	v_mfma_f32_16x16x32_bf16 v[56:59], v[170:173], v[184:187], v[56:59]
	v_mfma_f32_16x16x32_bf16 v[48:51], v[162:165], v[198:201], v[48:51]
	v_mfma_f32_16x16x32_bf16 v[40:43], v[170:173], v[198:201], v[40:43]
	v_mfma_f32_16x16x32_bf16 v[32:35], v[162:165], v[206:209], v[32:35]
	v_mfma_f32_16x16x32_bf16 v[24:27], v[170:173], v[206:209], v[24:27]
	v_mfma_f32_16x16x32_bf16 v[16:19], v[162:165], v[214:217], v[16:19]
	v_mfma_f32_16x16x32_bf16 v[8:11], v[170:173], v[214:217], v[8:11]
	v_mfma_f32_16x16x32_bf16 v[64:67], v[166:169], v[188:191], v[64:67]
	v_mfma_f32_16x16x32_bf16 v[56:59], v[180:183], v[188:191], v[56:59]
	v_mfma_f32_16x16x32_bf16 v[48:51], v[166:169], v[202:205], v[48:51]
	v_mfma_f32_16x16x32_bf16 v[40:43], v[180:183], v[202:205], v[40:43]
	v_mfma_f32_16x16x32_bf16 v[32:35], v[166:169], v[210:213], v[32:35]
	v_mfma_f32_16x16x32_bf16 v[24:27], v[180:183], v[210:213], v[24:27]
	v_mfma_f32_16x16x32_bf16 v[16:19], v[166:169], v[218:221], v[16:19]
	v_mfma_f32_16x16x32_bf16 v[8:11], v[180:183], v[218:221], v[8:11]
	s_setprio 0
	s_barrier
	s_add_u32 s4, s4, 0x100
	s_addc_u32 s5, s5, 0
	s_add_u32 s8, s8, 0x100
	s_addc_u32 s9, s9, 0
	s_cmp_ge_i32 s48, s24
	s_mov_b32 s6, s48
	s_cbranch_scc0 .LBB0_377
	v_readlane_b32 s52, v254, 27
	v_readlane_b32 s53, v254, 28
	s_mov_b32 s50, s94

; #define PG8_STAGE(bufoff, gbase, voff) do { _Pragma("unroll") for (int _i = 0; _i < 2; ++_i) \
;         __builtin_amdgcn_global_load_lds((const unsigned*)((const char*)(gbase) + (voff)[_i]), (PG8_LAS unsigned*)(lds + (bufoff) + ldsw + _i * 8192), 16, 0, 0); } while (0)
; #define PG8_LDA(dst, b, h) do { _Pragma("unroll") for (int m = 0; m < 4; ++m) _Pragma("unroll") for (int k = 0; k < 2; ++k) dst[m][k] = *(const PG8_LAS bf16x8*)(lds + PG8_SA(b, h) + aoff + m * 2048 + k * 1024); } while (0)
; #define PG8_LDB(dst, b, h) do { _Pragma("unroll") for (int n = 0; n < 2; ++n) _Pragma("unroll") for (int k = 0; k < 2; ++k) dst[n][k] = *(const PG8_LAS bf16x8*)(lds + PG8_SB(b, h) + boff + n * 2048 + k * 1024); } while (0)
; #define PG8_WAIT_V(n) asm volatile("s_waitcnt vmcnt(" #n ")" ::: "memory")
; #define PG8_WAIT_L(n) asm volatile("s_waitcnt lgkmcnt(" #n ")" ::: "memory")
; template <class Epi, class Sched, bool ALIGN_EPI = false, bool SP2 = false, bool ACHUNK = false>
; __device__ __forceinline__ void gemm_phase(PG8_LAS unsigned char* lds, const Gemm g, const Sched& S, const Epi& E) {
;     ...
;         const bool has_next = S.next(ui + 1, nxt);
;         const char* nA = has_next ? (const char*)g.A + (size_t)nxt.pm * tstepA : cA; const char* nB = has_next ? (const char*)g.Bt + (size_t)nxt.pn * tstepB : cB;
;         for (int t = 0; t < nt; t += 2) {
;             const bool last = (t == nt - 2);
;             if constexpr (Epi::HAS_MID) { if (t == Epi::MID_T) E.mid(acc, cur, wr, wc, fr, fq, ShflDev{}); }
;             const char* a1 = cA + (size_t)(t + 1) * kstep;
;             const char* a2 = last ? nA : cA + (size_t)(t + 2) * kstep; const char* b2 = last ? nB : cB + (size_t)(t + 2) * kstep;
;             const char* a3 = a2 + kstep; const char* b3 = b2 + kstep;
;             if (last && has_next) S.a_ready(nxt);
;             if constexpr (SP2) {
;             PG8_LDB(B0, 0, 0); PG8_LDB(B1, 0, 1); PG8_SCHED; PG8_LDA(At, 0, 0); PG8_STAGE(PG8_SA(1, 1), a1 + hstepA, voffA);
;             PG8_WAIT_V(8); PG8_WAIT_L(0); PG8_BAR; PG8_MMA(0, 0, At, B0); PG8_MMA(0, 1, At, B1); PG8_BAR; PG8_SCHED;
;             PG8_LDA(At, 0, 1); PG8_STAGE(PG8_SB(0, 0), b2, voffB); PG8_STAGE(PG8_SB(0, 1), b2 + hstepB, voffB); PG8_STAGE(PG8_SA(0, 0), a2, voffA);
;             PG8_WAIT_V(8); PG8_WAIT_L(0); PG8_BAR; PG8_MMA(1, 0, At, B0); PG8_MMA(1, 1, At, B1); PG8_BAR; PG8_SCHED;
.LBB0_429:
	s_andn2_b64 vcc, exec, s[54:55]
	s_nop 0
	s_cbranch_vccnz .LBB0_432
	s_add_u32 s0, s6, 0x80
	s_addc_u32 s1, s7, 0
	s_add_u32 s6, s4, 0x100
	s_addc_u32 s7, s5, 0
	s_mov_b32 s4, 0
	v_add_u32_e32 v214, 0x10000, v221
	s_add_i32 s8, s4, 2
	s_add_u32 s9, s0, 0x80
	s_addc_u32 s5, s1, 0
	s_add_i32 s15, 0, 0x10000
	s_cmp_eq_u32 s81, s4
	s_cselect_b32 s5, s31, s5
	s_cselect_b32 s4, s30, s9
	s_cselect_b32 s17, s93, s7
	s_cselect_b32 s16, s92, s6
	s_cbranch_scc0 .Lnl_pl_pe
	s_cmpk_lg_u32 s87, 0x100
	s_cbranch_scc1 .Lnl_pl_pe
	v_mov_b32_e32 v2, 0
	v_mov_b32_e32 v168, 0
	v_mov_b32_e32 v164, 0
	v_mov_b32_e32 v166, 0
.Lnl_pl_pe:
	s_add_i32 s9, 0, 0x14000
	ds_read_b128 v[132:135], v214
	ds_read_b128 v[136:139], v214 offset:1024
	ds_read_b128 v[140:143], v214 offset:2048
	ds_read_b128 v[144:147], v214 offset:3072
	ds_read_b128 v[148:151], v214 offset:16384
	ds_read_b128 v[152:155], v214 offset:17408
	ds_read_b128 v[156:159], v214 offset:18432
	ds_read_b128 v[160:163], v214 offset:19456
	s_add_i32 m0, s27, 0xc000
	ds_read_b128 v[178:181], v223
	ds_read_b128 v[182:185], v223 offset:1024
	ds_read_b128 v[186:189], v223 offset:2048
	ds_read_b128 v[190:193], v223 offset:3072
	ds_read_b128 v[198:201], v223 offset:4096
	ds_read_b128 v[202:205], v223 offset:5120
	ds_read_b128 v[206:209], v223 offset:6144
	ds_read_b128 v[210:213], v223 offset:7168
	global_load_lds_dwordx4 v174, s[0:1]
	s_add_i32 m0, s27, 0xe000
	s_nop 0
	global_load_lds_dwordx4 v176, s[0:1]
	s_waitcnt vmcnt(8)
	s_waitcnt lgkmcnt(0)
	s_barrier
	s_setprio 1
	v_mfma_f32_16x16x32_bf16 v[128:131], v[132:135], v[178:181], 0
	v_mfma_f32_16x16x32_bf16 v[124:127], v[140:143], v[178:181], 0
	v_mfma_f32_16x16x32_bf16 v[112:115], v[132:135], v[186:189], 0
	v_mfma_f32_16x16x32_bf16 v[108:111], v[140:143], v[186:189], 0
	v_mfma_f32_16x16x32_bf16 v[96:99], v[132:135], v[198:201], 0
	v_mfma_f32_16x16x32_bf16 v[92:95], v[140:143], v[198:201], 0
	v_mfma_f32_16x16x32_bf16 v[80:83], v[132:135], v[206:209], 0
	v_mfma_f32_16x16x32_bf16 v[76:79], v[140:143], v[206:209], 0
	v_mfma_f32_16x16x32_bf16 v[128:131], v[136:139], v[182:185], v[128:131]
	v_mfma_f32_16x16x32_bf16 v[124:127], v[144:147], v[182:185], v[124:127]
	v_mfma_f32_16x16x32_bf16 v[112:115], v[136:139], v[190:193], v[112:115]
	v_mfma_f32_16x16x32_bf16 v[108:111], v[144:147], v[190:193], v[108:111]
	v_mfma_f32_16x16x32_bf16 v[96:99], v[136:139], v[202:205], v[96:99]
	v_mfma_f32_16x16x32_bf16 v[92:95], v[144:147], v[202:205], v[92:95]
	v_mfma_f32_16x16x32_bf16 v[80:83], v[136:139], v[210:213], v[80:83]
	v_mfma_f32_16x16x32_bf16 v[76:79], v[144:147], v[210:213], v[76:79]
	s_setprio 0
	s_setprio 1
	v_mfma_f32_16x16x32_bf16 v[120:123], v[148:151], v[178:181], 0
	v_mfma_f32_16x16x32_bf16 v[116:119], v[156:159], v[178:181], 0
	v_mfma_f32_16x16x32_bf16 v[104:107], v[148:151], v[186:189], 0
	v_mfma_f32_16x16x32_bf16 v[100:103], v[156:159], v[186:189], 0
	v_mfma_f32_16x16x32_bf16 v[88:91], v[148:151], v[198:201], 0
	v_mfma_f32_16x16x32_bf16 v[84:87], v[156:159], v[198:201], 0
	v_mfma_f32_16x16x32_bf16 v[72:75], v[148:151], v[206:209], 0
	v_mfma_f32_16x16x32_bf16 v[68:71], v[156:159], v[206:209], 0
	v_mfma_f32_16x16x32_bf16 v[120:123], v[152:155], v[182:185], v[120:123]
	v_mfma_f32_16x16x32_bf16 v[116:119], v[160:163], v[182:185], v[116:119]
	v_mfma_f32_16x16x32_bf16 v[104:107], v[152:155], v[190:193], v[104:107]
	v_mfma_f32_16x16x32_bf16 v[100:103], v[160:163], v[190:193], v[100:103]
	v_mfma_f32_16x16x32_bf16 v[88:91], v[152:155], v[202:205], v[88:91]
	v_mfma_f32_16x16x32_bf16 v[84:87], v[160:163], v[202:205], v[84:87]
	v_mfma_f32_16x16x32_bf16 v[72:75], v[152:155], v[210:213], v[72:75]
	v_mfma_f32_16x16x32_bf16 v[68:71], v[160:163], v[210:213], v[68:71]
	s_setprio 0
	s_barrier
	s_add_i32 s15, s15, s26
	s_mov_b32 m0, s15
	ds_read_b128 v[178:181], v223 offset:16384
	ds_read_b128 v[182:185], v223 offset:17408
	ds_read_b128 v[186:189], v223 offset:18432
	ds_read_b128 v[190:193], v223 offset:19456
	ds_read_b128 v[198:201], v223 offset:20480
	ds_read_b128 v[202:205], v223 offset:21504
	ds_read_b128 v[206:209], v223 offset:22528
	ds_read_b128 v[210:213], v223 offset:23552
	global_load_lds_dwordx4 v2, s[16:17]
	s_add_i32 m0, s15, 0x2000
	s_add_i32 s9, s9, s26
	global_load_lds_dwordx4 v168, s[16:17]
	s_add_u32 s16, s16, s18
	s_addc_u32 s17, s17, s19
	s_mov_b64 vcc, s[16:17]
	s_sub_u32 s98, s16, s18
	s_subb_u32 s99, s17, s19
	s_mov_b32 m0, s9
	s_nop 0
	global_load_lds_dwordx4 v2, s[16:17]
	s_add_i32 m0, s9, 0x2000
	s_nop 0
	global_load_lds_dwordx4 v168, s[16:17]
	s_mov_b32 m0, s27
	s_nop 0
	global_load_lds_dwordx4 v164, s[4:5]
	s_mov_b32 m0, s36
	s_nop 0
	global_load_lds_dwordx4 v166, s[4:5]
	s_waitcnt vmcnt(8)
	s_waitcnt lgkmcnt(0)
	s_barrier
	s_setprio 1
	v_mfma_f32_16x16x32_bf16 v[64:67], v[132:135], v[178:181], 0
	v_mfma_f32_16x16x32_bf16 v[60:63], v[140:143], v[178:181], 0
	v_mfma_f32_16x16x32_bf16 v[48:51], v[132:135], v[186:189], 0
	v_mfma_f32_16x16x32_bf16 v[44:47], v[140:143], v[186:189], 0
	v_mfma_f32_16x16x32_bf16 v[32:35], v[132:135], v[198:201], 0
	v_mfma_f32_16x16x32_bf16 v[28:31], v[140:143], v[198:201], 0
	v_mfma_f32_16x16x32_bf16 v[16:19], v[132:135], v[206:209], 0
	v_mfma_f32_16x16x32_bf16 v[12:15], v[140:143], v[206:209], 0
	v_mfma_f32_16x16x32_bf16 v[64:67], v[136:139], v[182:185], v[64:67]
	v_mfma_f32_16x16x32_bf16 v[60:63], v[144:147], v[182:185], v[60:63]
	v_mfma_f32_16x16x32_bf16 v[48:51], v[136:139], v[190:193], v[48:51]
	v_mfma_f32_16x16x32_bf16 v[44:47], v[144:147], v[190:193], v[44:47]
	v_mfma_f32_16x16x32_bf16 v[32:35], v[136:139], v[202:205], v[32:35]
	v_mfma_f32_16x16x32_bf16 v[28:31], v[144:147], v[202:205], v[28:31]
	v_mfma_f32_16x16x32_bf16 v[16:19], v[136:139], v[210:213], v[16:19]
	v_mfma_f32_16x16x32_bf16 v[12:15], v[144:147], v[210:213], v[12:15]
	s_setprio 0
	s_setprio 1
	v_mfma_f32_16x16x32_bf16 v[56:59], v[148:151], v[178:181], 0
	v_mfma_f32_16x16x32_bf16 v[52:55], v[156:159], v[178:181], 0
	v_mfma_f32_16x16x32_bf16 v[40:43], v[148:151], v[186:189], 0
	v_mfma_f32_16x16x32_bf16 v[36:39], v[156:159], v[186:189], 0
	v_mfma_f32_16x16x32_bf16 v[24:27], v[148:151], v[198:201], 0
	v_mfma_f32_16x16x32_bf16 v[20:23], v[156:159], v[198:201], 0
	v_mfma_f32_16x16x32_bf16 v[8:11], v[148:151], v[206:209], 0
	v_mfma_f32_16x16x32_bf16 v[4:7], v[156:159], v[206:209], 0
	v_mfma_f32_16x16x32_bf16 v[56:59], v[152:155], v[182:185], v[56:59]
	v_mfma_f32_16x16x32_bf16 v[52:55], v[160:163], v[182:185], v[52:55]
	v_mfma_f32_16x16x32_bf16 v[40:43], v[152:155], v[190:193], v[40:43]
	v_mfma_f32_16x16x32_bf16 v[36:39], v[160:163], v[190:193], v[36:39]
	v_mfma_f32_16x16x32_bf16 v[24:27], v[152:155], v[202:205], v[24:27]
	v_mfma_f32_16x16x32_bf16 v[20:23], v[160:163], v[202:205], v[20:23]
	v_mfma_f32_16x16x32_bf16 v[8:11], v[152:155], v[210:213], v[8:11]
	v_mfma_f32_16x16x32_bf16 v[4:7], v[160:163], v[210:213], v[4:7]
	s_setprio 0
	s_barrier
	s_branch .Lpe_join_431

; #define PG8_STAGE(bufoff, gbase, voff) do { _Pragma("unroll") for (int _i = 0; _i < 2; ++_i) \
;         __builtin_amdgcn_global_load_lds((const unsigned*)((const char*)(gbase) + (voff)[_i]), (PG8_LAS unsigned*)(lds + (bufoff) + ldsw + _i * 8192), 16, 0, 0); } while (0)
; #define PG8_LDA(dst, b, h) do { _Pragma("unroll") for (int m = 0; m < 4; ++m) _Pragma("unroll") for (int k = 0; k < 2; ++k) dst[m][k] = *(const PG8_LAS bf16x8*)(lds + PG8_SA(b, h) + aoff + m * 2048 + k * 1024); } while (0)
; #define PG8_LDB(dst, b, h) do { _Pragma("unroll") for (int n = 0; n < 2; ++n) _Pragma("unroll") for (int k = 0; k < 2; ++k) dst[n][k] = *(const PG8_LAS bf16x8*)(lds + PG8_SB(b, h) + boff + n * 2048 + k * 1024); } while (0)
; #define PG8_MMA(ai, bj, At, Bt) do { __builtin_amdgcn_s_setprio(1); _Pragma("unroll") for (int m = 0; m < 4; ++m) _Pragma("unroll") for (int n = 0; n < 2; ++n) _Pragma("unroll") for (int k = 0; k < 2; ++k) \
;         acc[ai][bj][m][n] = __builtin_amdgcn_mfma_f32_16x16x32_bf16(Bt[n][k], At[m][k], acc[ai][bj][m][n], 0, 0, 0); __builtin_amdgcn_s_setprio(0); } while (0)
; #define PG8_WAIT_V(n) asm volatile("s_waitcnt vmcnt(" #n ")" ::: "memory")
; #define PG8_WAIT_L(n) asm volatile("s_waitcnt lgkmcnt(" #n ")" ::: "memory")
; #define PG8_BAR __builtin_amdgcn_s_barrier()
; #define PG8_SCHED __builtin_amdgcn_sched_barrier(0)
; template <class Epi, class Sched, bool ALIGN_EPI = false, bool SP2 = false, bool ACHUNK = false>
; __device__ __forceinline__ void gemm_phase(PG8_LAS unsigned char* lds, const Gemm g, const Sched& S, const Epi& E) {
;     ...
;             PG8_LDB(B0, 0, 0); PG8_LDB(B1, 0, 1); PG8_SCHED; PG8_LDA(At, 0, 0); PG8_STAGE(PG8_SA(1, 1), a1 + hstepA, voffA);
;             PG8_WAIT_V(8); PG8_WAIT_L(0); PG8_BAR; PG8_MMA(0, 0, At, B0); PG8_MMA(0, 1, At, B1); PG8_BAR; PG8_SCHED;
;             PG8_LDA(At, 0, 1); PG8_STAGE(PG8_SB(0, 0), b2, voffB); PG8_STAGE(PG8_SB(0, 1), b2 + hstepB, voffB); PG8_STAGE(PG8_SA(0, 0), a2, voffA);
;             PG8_WAIT_V(8); PG8_WAIT_L(0); PG8_BAR; PG8_MMA(1, 0, At, B0); PG8_MMA(1, 1, At, B1); PG8_BAR; PG8_SCHED;
.Lnl_pl:
	s_add_i32 s9, 0, 0x14000
	ds_read_b128 v[132:135], v214
	ds_read_b128 v[136:139], v214 offset:1024
	ds_read_b128 v[140:143], v214 offset:2048
	ds_read_b128 v[144:147], v214 offset:3072
	ds_read_b128 v[148:151], v214 offset:16384
	ds_read_b128 v[152:155], v214 offset:17408
	ds_read_b128 v[156:159], v214 offset:18432
	ds_read_b128 v[160:163], v214 offset:19456
	s_add_i32 m0, s27, 0xc000
	ds_read_b128 v[178:181], v223
	ds_read_b128 v[182:185], v223 offset:1024
	ds_read_b128 v[186:189], v223 offset:2048
	ds_read_b128 v[190:193], v223 offset:3072
	ds_read_b128 v[198:201], v223 offset:4096
	ds_read_b128 v[202:205], v223 offset:5120
	ds_read_b128 v[206:209], v223 offset:6144
	ds_read_b128 v[210:213], v223 offset:7168
	global_load_lds_dwordx4 v174, s[0:1]
	s_add_i32 m0, s27, 0xe000
	s_nop 0
	global_load_lds_dwordx4 v176, s[0:1]
	s_waitcnt vmcnt(8)
	s_waitcnt lgkmcnt(0)
	s_barrier
	s_setprio 1
	v_mfma_f32_16x16x32_bf16 v[128:131], v[132:135], v[178:181], v[128:131]
	v_mfma_f32_16x16x32_bf16 v[124:127], v[140:143], v[178:181], v[124:127]
	v_mfma_f32_16x16x32_bf16 v[112:115], v[132:135], v[186:189], v[112:115]
	v_mfma_f32_16x16x32_bf16 v[108:111], v[140:143], v[186:189], v[108:111]
	v_mfma_f32_16x16x32_bf16 v[96:99], v[132:135], v[198:201], v[96:99]
	v_mfma_f32_16x16x32_bf16 v[92:95], v[140:143], v[198:201], v[92:95]
	v_mfma_f32_16x16x32_bf16 v[80:83], v[132:135], v[206:209], v[80:83]
	v_mfma_f32_16x16x32_bf16 v[76:79], v[140:143], v[206:209], v[76:79]
	v_mfma_f32_16x16x32_bf16 v[128:131], v[136:139], v[182:185], v[128:131]
	v_mfma_f32_16x16x32_bf16 v[124:127], v[144:147], v[182:185], v[124:127]
	v_mfma_f32_16x16x32_bf16 v[112:115], v[136:139], v[190:193], v[112:115]
	v_mfma_f32_16x16x32_bf16 v[108:111], v[144:147], v[190:193], v[108:111]
	v_mfma_f32_16x16x32_bf16 v[96:99], v[136:139], v[202:205], v[96:99]
	v_mfma_f32_16x16x32_bf16 v[92:95], v[144:147], v[202:205], v[92:95]
	v_mfma_f32_16x16x32_bf16 v[80:83], v[136:139], v[210:213], v[80:83]
	v_mfma_f32_16x16x32_bf16 v[76:79], v[144:147], v[210:213], v[76:79]
	s_setprio 0
	s_setprio 1
	v_mfma_f32_16x16x32_bf16 v[120:123], v[148:151], v[178:181], v[120:123]
	v_mfma_f32_16x16x32_bf16 v[116:119], v[156:159], v[178:181], v[116:119]
	v_mfma_f32_16x16x32_bf16 v[104:107], v[148:151], v[186:189], v[104:107]
	v_mfma_f32_16x16x32_bf16 v[100:103], v[156:159], v[186:189], v[100:103]
	v_mfma_f32_16x16x32_bf16 v[88:91], v[148:151], v[198:201], v[88:91]
	v_mfma_f32_16x16x32_bf16 v[84:87], v[156:159], v[198:201], v[84:87]
	v_mfma_f32_16x16x32_bf16 v[72:75], v[148:151], v[206:209], v[72:75]
	v_mfma_f32_16x16x32_bf16 v[68:71], v[156:159], v[206:209], v[68:71]
	v_mfma_f32_16x16x32_bf16 v[120:123], v[152:155], v[182:185], v[120:123]
	v_mfma_f32_16x16x32_bf16 v[116:119], v[160:163], v[182:185], v[116:119]
	v_mfma_f32_16x16x32_bf16 v[104:107], v[152:155], v[190:193], v[104:107]
	v_mfma_f32_16x16x32_bf16 v[100:103], v[160:163], v[190:193], v[100:103]
	v_mfma_f32_16x16x32_bf16 v[88:91], v[152:155], v[202:205], v[88:91]
	v_mfma_f32_16x16x32_bf16 v[84:87], v[160:163], v[202:205], v[84:87]
	v_mfma_f32_16x16x32_bf16 v[72:75], v[152:155], v[210:213], v[72:75]
	v_mfma_f32_16x16x32_bf16 v[68:71], v[160:163], v[210:213], v[68:71]
	s_setprio 0
	s_barrier
	s_add_i32 s15, s15, s26
	s_mov_b32 m0, s15
	ds_read_b128 v[178:181], v223 offset:16384
	ds_read_b128 v[182:185], v223 offset:17408
	ds_read_b128 v[186:189], v223 offset:18432
	ds_read_b128 v[190:193], v223 offset:19456
	ds_read_b128 v[198:201], v223 offset:20480
	ds_read_b128 v[202:205], v223 offset:21504
	ds_read_b128 v[206:209], v223 offset:22528
	ds_read_b128 v[210:213], v223 offset:23552
	global_load_lds_dwordx4 v2, s[16:17]
	s_add_i32 m0, s15, 0x2000
	s_add_i32 s9, s9, s26
	global_load_lds_dwordx4 v168, s[16:17]
	s_add_u32 s16, s16, s18
	s_addc_u32 s17, s17, s19
	s_mov_b64 vcc, s[16:17]
	s_sub_u32 s98, s16, s18
	s_subb_u32 s99, s17, s19
	s_mov_b32 m0, s9
	s_nop 0
	global_load_lds_dwordx4 v2, s[16:17]
	s_add_i32 m0, s9, 0x2000
	s_nop 0
	global_load_lds_dwordx4 v168, s[16:17]
	s_mov_b32 m0, s27
	s_nop 0
	global_load_lds_dwordx4 v164, s[4:5]
	s_mov_b32 m0, s36
	s_nop 0
	global_load_lds_dwordx4 v166, s[4:5]
	s_waitcnt vmcnt(8)
	s_waitcnt lgkmcnt(0)
	s_barrier
	s_setprio 1
	v_mfma_f32_16x16x32_bf16 v[64:67], v[132:135], v[178:181], v[64:67]
	v_mfma_f32_16x16x32_bf16 v[60:63], v[140:143], v[178:181], v[60:63]
	v_mfma_f32_16x16x32_bf16 v[48:51], v[132:135], v[186:189], v[48:51]
	v_mfma_f32_16x16x32_bf16 v[44:47], v[140:143], v[186:189], v[44:47]
	v_mfma_f32_16x16x32_bf16 v[32:35], v[132:135], v[198:201], v[32:35]
	v_mfma_f32_16x16x32_bf16 v[28:31], v[140:143], v[198:201], v[28:31]
	v_mfma_f32_16x16x32_bf16 v[16:19], v[132:135], v[206:209], v[16:19]
	v_mfma_f32_16x16x32_bf16 v[12:15], v[140:143], v[206:209], v[12:15]
	v_mfma_f32_16x16x32_bf16 v[64:67], v[136:139], v[182:185], v[64:67]
	v_mfma_f32_16x16x32_bf16 v[60:63], v[144:147], v[182:185], v[60:63]
	v_mfma_f32_16x16x32_bf16 v[48:51], v[136:139], v[190:193], v[48:51]
	v_mfma_f32_16x16x32_bf16 v[44:47], v[144:147], v[190:193], v[44:47]
	v_mfma_f32_16x16x32_bf16 v[32:35], v[136:139], v[202:205], v[32:35]
	v_mfma_f32_16x16x32_bf16 v[28:31], v[144:147], v[202:205], v[28:31]
	v_mfma_f32_16x16x32_bf16 v[16:19], v[136:139], v[210:213], v[16:19]
	v_mfma_f32_16x16x32_bf16 v[12:15], v[144:147], v[210:213], v[12:15]
	s_setprio 0
	s_setprio 1
	v_mfma_f32_16x16x32_bf16 v[56:59], v[148:151], v[178:181], v[56:59]
	v_mfma_f32_16x16x32_bf16 v[52:55], v[156:159], v[178:181], v[52:55]
	v_mfma_f32_16x16x32_bf16 v[40:43], v[148:151], v[186:189], v[40:43]
	v_mfma_f32_16x16x32_bf16 v[36:39], v[156:159], v[186:189], v[36:39]
	v_mfma_f32_16x16x32_bf16 v[24:27], v[148:151], v[198:201], v[24:27]
	v_mfma_f32_16x16x32_bf16 v[20:23], v[156:159], v[198:201], v[20:23]
	v_mfma_f32_16x16x32_bf16 v[8:11], v[148:151], v[206:209], v[8:11]
	v_mfma_f32_16x16x32_bf16 v[4:7], v[156:159], v[206:209], v[4:7]
	v_mfma_f32_16x16x32_bf16 v[56:59], v[152:155], v[182:185], v[56:59]
	v_mfma_f32_16x16x32_bf16 v[52:55], v[160:163], v[182:185], v[52:55]
	v_mfma_f32_16x16x32_bf16 v[40:43], v[152:155], v[190:193], v[40:43]
	v_mfma_f32_16x16x32_bf16 v[36:39], v[160:163], v[190:193], v[36:39]
	v_mfma_f32_16x16x32_bf16 v[24:27], v[152:155], v[202:205], v[24:27]
	v_mfma_f32_16x16x32_bf16 v[20:23], v[160:163], v[202:205], v[20:23]
	v_mfma_f32_16x16x32_bf16 v[8:11], v[152:155], v[210:213], v[8:11]
	v_mfma_f32_16x16x32_bf16 v[4:7], v[160:163], v[210:213], v[4:7]
	s_setprio 0
	s_barrier
; #define PG8_STAGE(bufoff, gbase, voff) do { _Pragma("unroll") for (int _i = 0; _i < 2; ++_i) \
;         __builtin_amdgcn_global_load_lds((const unsigned*)((const char*)(gbase) + (voff)[_i]), (PG8_LAS unsigned*)(lds + (bufoff) + ldsw + _i * 8192), 16, 0, 0); } while (0)
; #define PG8_LDA(dst, b, h) do { _Pragma("unroll") for (int m = 0; m < 4; ++m) _Pragma("unroll") for (int k = 0; k < 2; ++k) dst[m][k] = *(const PG8_LAS bf16x8*)(lds + PG8_SA(b, h) + aoff + m * 2048 + k * 1024); } while (0)
; #define PG8_LDB(dst, b, h) do { _Pragma("unroll") for (int n = 0; n < 2; ++n) _Pragma("unroll") for (int k = 0; k < 2; ++k) dst[n][k] = *(const PG8_LAS bf16x8*)(lds + PG8_SB(b, h) + boff + n * 2048 + k * 1024); } while (0)
; #define PG8_MMA(ai, bj, At, Bt) do { __builtin_amdgcn_s_setprio(1); _Pragma("unroll") for (int m = 0; m < 4; ++m) _Pragma("unroll") for (int n = 0; n < 2; ++n) _Pragma("unroll") for (int k = 0; k < 2; ++k) \
;         acc[ai][bj][m][n] = __builtin_amdgcn_mfma_f32_16x16x32_bf16(Bt[n][k], At[m][k], acc[ai][bj][m][n], 0, 0, 0); __builtin_amdgcn_s_setprio(0); } while (0)
; #define PG8_WAIT_V(n) asm volatile("s_waitcnt vmcnt(" #n ")" ::: "memory")
; #define PG8_WAIT_L(n) asm volatile("s_waitcnt lgkmcnt(" #n ")" ::: "memory")
; #define PG8_BAR __builtin_amdgcn_s_barrier()
; #define PG8_SCHED __builtin_amdgcn_sched_barrier(0)
; template <class Epi, class Sched, bool ALIGN_EPI = false, bool SP2 = false, bool ACHUNK = false>
; __device__ __forceinline__ void gemm_phase(PG8_LAS unsigned char* lds, const Gemm g, const Sched& S, const Epi& E) {
;     ...
;         for (int t = 0; t < nt; t += 2) {
;     ...
;             PG8_LDB(B0, 1, 0); PG8_LDB(B1, 1, 1); PG8_SCHED; PG8_LDA(At, 1, 0); PG8_STAGE(PG8_SA(0, 1), a2 + hstepA, voffA);
;             PG8_WAIT_V(8); PG8_WAIT_L(0); PG8_BAR; PG8_MMA(0, 0, At, B0); PG8_MMA(0, 1, At, B1); PG8_BAR; PG8_SCHED;
;             PG8_LDA(At, 1, 1); PG8_STAGE(PG8_SB(1, 0), b3, voffB); PG8_STAGE(PG8_SB(1, 1), b3 + hstepB, voffB); PG8_STAGE(PG8_SA(1, 0), a3, voffA);
;             PG8_WAIT_V(8); PG8_WAIT_L(0); PG8_BAR; PG8_MMA(1, 0, At, B0); PG8_MMA(1, 1, At, B1); PG8_BAR; PG8_SCHED;
.Lpe_join_431:
	s_add_i32 s9, 0, 0x18000
	s_add_i32 s15, 0, 0x1c000
	ds_read_b128 v[132:135], v214 offset:32768
	ds_read_b128 v[136:139], v214 offset:33792
	ds_read_b128 v[140:143], v214 offset:34816
	ds_read_b128 v[144:147], v214 offset:35840
	ds_read_b128 v[148:151], v214 offset:49152
	ds_read_b128 v[152:155], v214 offset:50176
	ds_read_b128 v[156:159], v214 offset:51200
	ds_read_b128 v[160:163], v214 offset:52224
	s_add_u32 s4, s4, s18
	s_addc_u32 s5, s5, s19
	s_mov_b32 m0, s37
	ds_read_b128 v[178:181], v223 offset:32768
	ds_read_b128 v[182:185], v223 offset:33792
	ds_read_b128 v[186:189], v223 offset:34816
	ds_read_b128 v[190:193], v223 offset:35840
	ds_read_b128 v[198:201], v223 offset:36864
	ds_read_b128 v[202:205], v223 offset:37888
	ds_read_b128 v[206:209], v223 offset:38912
	ds_read_b128 v[210:213], v223 offset:39936
	global_load_lds_dwordx4 v164, s[4:5]
	s_mov_b32 m0, s76
	s_nop 0
	global_load_lds_dwordx4 v166, s[4:5]
	s_waitcnt vmcnt(8)
	s_waitcnt lgkmcnt(0)
	s_barrier
	s_setprio 1
	v_mfma_f32_16x16x32_bf16 v[128:131], v[132:135], v[178:181], v[128:131]
	v_mfma_f32_16x16x32_bf16 v[124:127], v[140:143], v[178:181], v[124:127]
	v_mfma_f32_16x16x32_bf16 v[112:115], v[132:135], v[186:189], v[112:115]
	v_mfma_f32_16x16x32_bf16 v[108:111], v[140:143], v[186:189], v[108:111]
	v_mfma_f32_16x16x32_bf16 v[96:99], v[132:135], v[198:201], v[96:99]
	v_mfma_f32_16x16x32_bf16 v[92:95], v[140:143], v[198:201], v[92:95]
	v_mfma_f32_16x16x32_bf16 v[80:83], v[132:135], v[206:209], v[80:83]
	v_mfma_f32_16x16x32_bf16 v[76:79], v[140:143], v[206:209], v[76:79]
	v_mfma_f32_16x16x32_bf16 v[128:131], v[136:139], v[182:185], v[128:131]
	v_mfma_f32_16x16x32_bf16 v[124:127], v[144:147], v[182:185], v[124:127]
	v_mfma_f32_16x16x32_bf16 v[112:115], v[136:139], v[190:193], v[112:115]
	v_mfma_f32_16x16x32_bf16 v[108:111], v[144:147], v[190:193], v[108:111]
	v_mfma_f32_16x16x32_bf16 v[96:99], v[136:139], v[202:205], v[96:99]
	v_mfma_f32_16x16x32_bf16 v[92:95], v[144:147], v[202:205], v[92:95]
	v_mfma_f32_16x16x32_bf16 v[80:83], v[136:139], v[210:213], v[80:83]
	v_mfma_f32_16x16x32_bf16 v[76:79], v[144:147], v[210:213], v[76:79]
	s_setprio 0
	s_setprio 1
	v_mfma_f32_16x16x32_bf16 v[120:123], v[148:151], v[178:181], v[120:123]
	v_mfma_f32_16x16x32_bf16 v[116:119], v[156:159], v[178:181], v[116:119]
	v_mfma_f32_16x16x32_bf16 v[104:107], v[148:151], v[186:189], v[104:107]
	v_mfma_f32_16x16x32_bf16 v[100:103], v[156:159], v[186:189], v[100:103]
	v_mfma_f32_16x16x32_bf16 v[88:91], v[148:151], v[198:201], v[88:91]
	v_mfma_f32_16x16x32_bf16 v[84:87], v[156:159], v[198:201], v[84:87]
	v_mfma_f32_16x16x32_bf16 v[72:75], v[148:151], v[206:209], v[72:75]
	v_mfma_f32_16x16x32_bf16 v[68:71], v[156:159], v[206:209], v[68:71]
	v_mfma_f32_16x16x32_bf16 v[120:123], v[152:155], v[182:185], v[120:123]
	v_mfma_f32_16x16x32_bf16 v[116:119], v[160:163], v[182:185], v[116:119]
	v_mfma_f32_16x16x32_bf16 v[104:107], v[152:155], v[190:193], v[104:107]
	v_mfma_f32_16x16x32_bf16 v[100:103], v[160:163], v[190:193], v[100:103]
	v_mfma_f32_16x16x32_bf16 v[88:91], v[152:155], v[202:205], v[88:91]
	v_mfma_f32_16x16x32_bf16 v[84:87], v[160:163], v[202:205], v[84:87]
	v_mfma_f32_16x16x32_bf16 v[72:75], v[152:155], v[210:213], v[72:75]
	v_mfma_f32_16x16x32_bf16 v[68:71], v[160:163], v[210:213], v[68:71]
	s_setprio 0
	s_barrier
	s_add_u32 vcc_lo, vcc_lo, s10
	s_addc_u32 vcc_hi, vcc_hi, s11
	s_add_u32 s98, s98, s10
	s_addc_u32 s99, s99, s11
	s_sub_u32 s4, s4, s18
	s_subb_u32 s5, s5, s19
	s_add_u32 s4, s4, s10
	s_addc_u32 s5, s5, s11
	s_add_i32 m0, s9, s26
	ds_read_b128 v[178:181], v223 offset:49152
	ds_read_b128 v[182:185], v223 offset:50176
	ds_read_b128 v[186:189], v223 offset:51200
	ds_read_b128 v[190:193], v223 offset:52224
	ds_read_b128 v[198:201], v223 offset:53248
	ds_read_b128 v[202:205], v223 offset:54272
	ds_read_b128 v[206:209], v223 offset:55296
	ds_read_b128 v[210:213], v223 offset:56320
	global_load_lds_dwordx4 v2, s[98:99]
	s_add_i32 m0, m0, 0x2000
	s_nop 0
	global_load_lds_dwordx4 v168, s[98:99]
	s_add_i32 m0, s15, s26
	s_nop 0
	global_load_lds_dwordx4 v2, vcc
	s_add_i32 m0, m0, 0x2000
	s_nop 0
	global_load_lds_dwordx4 v168, vcc
	s_mov_b32 m0, s77
	s_nop 0
	global_load_lds_dwordx4 v164, s[4:5]
	s_mov_b32 m0, s78
	s_nop 0
	global_load_lds_dwordx4 v166, s[4:5]
	s_waitcnt vmcnt(8)
	s_waitcnt lgkmcnt(0)
	s_barrier
	s_setprio 1
	v_mfma_f32_16x16x32_bf16 v[64:67], v[132:135], v[178:181], v[64:67]
	v_mfma_f32_16x16x32_bf16 v[60:63], v[140:143], v[178:181], v[60:63]
	v_mfma_f32_16x16x32_bf16 v[48:51], v[132:135], v[186:189], v[48:51]
	v_mfma_f32_16x16x32_bf16 v[44:47], v[140:143], v[186:189], v[44:47]
	v_mfma_f32_16x16x32_bf16 v[32:35], v[132:135], v[198:201], v[32:35]
	v_mfma_f32_16x16x32_bf16 v[28:31], v[140:143], v[198:201], v[28:31]
	v_mfma_f32_16x16x32_bf16 v[16:19], v[132:135], v[206:209], v[16:19]
	v_mfma_f32_16x16x32_bf16 v[12:15], v[140:143], v[206:209], v[12:15]
	v_mfma_f32_16x16x32_bf16 v[64:67], v[136:139], v[182:185], v[64:67]
	v_mfma_f32_16x16x32_bf16 v[60:63], v[144:147], v[182:185], v[60:63]
	v_mfma_f32_16x16x32_bf16 v[48:51], v[136:139], v[190:193], v[48:51]
	v_mfma_f32_16x16x32_bf16 v[44:47], v[144:147], v[190:193], v[44:47]
	v_mfma_f32_16x16x32_bf16 v[32:35], v[136:139], v[202:205], v[32:35]
	v_mfma_f32_16x16x32_bf16 v[28:31], v[144:147], v[202:205], v[28:31]
	v_mfma_f32_16x16x32_bf16 v[16:19], v[136:139], v[210:213], v[16:19]
	v_mfma_f32_16x16x32_bf16 v[12:15], v[144:147], v[210:213], v[12:15]
	s_setprio 0
	s_setprio 1
	v_mfma_f32_16x16x32_bf16 v[56:59], v[148:151], v[178:181], v[56:59]
	v_mfma_f32_16x16x32_bf16 v[52:55], v[156:159], v[178:181], v[52:55]
	v_mfma_f32_16x16x32_bf16 v[40:43], v[148:151], v[186:189], v[40:43]
	v_mfma_f32_16x16x32_bf16 v[36:39], v[156:159], v[186:189], v[36:39]
	v_mfma_f32_16x16x32_bf16 v[24:27], v[148:151], v[198:201], v[24:27]
	v_mfma_f32_16x16x32_bf16 v[20:23], v[156:159], v[198:201], v[20:23]
	v_mfma_f32_16x16x32_bf16 v[8:11], v[148:151], v[206:209], v[8:11]
	v_mfma_f32_16x16x32_bf16 v[4:7], v[156:159], v[206:209], v[4:7]
	v_mfma_f32_16x16x32_bf16 v[56:59], v[152:155], v[182:185], v[56:59]
	v_mfma_f32_16x16x32_bf16 v[52:55], v[160:163], v[182:185], v[52:55]
	v_mfma_f32_16x16x32_bf16 v[40:43], v[152:155], v[190:193], v[40:43]
	v_mfma_f32_16x16x32_bf16 v[36:39], v[160:163], v[190:193], v[36:39]
	v_mfma_f32_16x16x32_bf16 v[24:27], v[152:155], v[202:205], v[24:27]
	v_mfma_f32_16x16x32_bf16 v[20:23], v[160:163], v[202:205], v[20:23]
	v_mfma_f32_16x16x32_bf16 v[8:11], v[152:155], v[210:213], v[8:11]
	v_mfma_f32_16x16x32_bf16 v[4:7], v[160:163], v[210:213], v[4:7]
	s_setprio 0
	s_barrier
	s_add_u32 s0, s0, 0x100
	s_addc_u32 s1, s1, 0
	s_add_u32 s6, s6, 0x100
	s_addc_u32 s7, s7, 0
	s_cmp_ge_i32 s8, s80
	s_mov_b32 s4, s8
	s_cbranch_scc0 .LBB0_431
